# gate scratch buffer re-laid out so the gate-GEMM epilogue stores and the PLE epilogue loads are contiguous across the 16 row lanes
# baseline (speedup 1.0000x reference)
.LBB0_680:
	ds_read_b128 v[154:157], v149
	ds_read_b128 v[158:161], v149 offset:1024
	ds_read_b128 v[162:165], v149 offset:2048
	ds_read_b128 v[166:169], v149 offset:3072
	s_add_u32 s26, s24, 0xfffc0080
	s_addc_u32 s27, s25, -1
	s_cmp_eq_u32 s59, 12
	s_cselect_b32 s29, s17, s27
	s_cselect_b32 s28, s55, s26
	s_cselect_b32 s27, s15, s58
	s_cselect_b32 s26, s56, s57
	v_lshl_add_u64 v[146:147], s[24:25], 0, v[138:139]
	s_add_i32 m0, s38, 0xc000
	ds_read_b128 v[170:173], v150
	ds_read_b128 v[174:177], v150 offset:1024
	ds_read_b128 v[178:181], v150 offset:2048
	ds_read_b128 v[182:185], v150 offset:3072
	ds_read_b128 v[186:189], v150 offset:4096
	ds_read_b128 v[190:193], v150 offset:5120
	ds_read_b128 v[194:197], v150 offset:6144
	ds_read_b128 v[198:201], v150 offset:7168
	global_load_lds_dwordx4 v[146:147], off
	v_lshl_add_u64 v[146:147], s[24:25], 0, v[140:141]
	s_add_i32 m0, s38, 0xe000
	s_nop 0
	global_load_lds_dwordx4 v[146:147], off
	s_waitcnt lgkmcnt(8)
	s_barrier
	s_waitcnt lgkmcnt(0)
	s_setprio 1
	s_waitcnt lgkmcnt(0)
	v_mfma_f32_16x16x32_bf16 v[124:127], v[154:157], v[170:173], v[124:127]
	v_mfma_f32_16x16x32_bf16 v[120:123], v[162:165], v[170:173], v[120:123]
	v_mfma_f32_16x16x32_bf16 v[108:111], v[154:157], v[178:181], v[108:111]
	v_mfma_f32_16x16x32_bf16 v[104:107], v[162:165], v[178:181], v[104:107]
	v_mfma_f32_16x16x32_bf16 v[92:95], v[154:157], v[186:189], v[92:95]
	v_mfma_f32_16x16x32_bf16 v[88:91], v[162:165], v[186:189], v[88:91]
	v_mfma_f32_16x16x32_bf16 v[76:79], v[154:157], v[194:197], v[76:79]
	v_mfma_f32_16x16x32_bf16 v[72:75], v[162:165], v[194:197], v[72:75]
	v_mfma_f32_16x16x32_bf16 v[124:127], v[158:161], v[174:177], v[124:127]
	v_mfma_f32_16x16x32_bf16 v[120:123], v[166:169], v[174:177], v[120:123]
	v_mfma_f32_16x16x32_bf16 v[108:111], v[158:161], v[182:185], v[108:111]
	v_mfma_f32_16x16x32_bf16 v[104:107], v[166:169], v[182:185], v[104:107]
	v_mfma_f32_16x16x32_bf16 v[92:95], v[158:161], v[190:193], v[92:95]
	v_mfma_f32_16x16x32_bf16 v[88:91], v[166:169], v[190:193], v[88:91]
	v_mfma_f32_16x16x32_bf16 v[76:79], v[158:161], v[198:201], v[76:79]
	v_mfma_f32_16x16x32_bf16 v[72:75], v[166:169], v[198:201], v[72:75]
	s_setprio 0
	s_barrier
	s_mov_b32 m0, s23
	v_lshl_add_u64 v[146:147], s[26:27], 0, v[130:131]
	ds_read_b128 v[202:205], v151
	ds_read_b128 v[206:209], v151 offset:1024
	ds_read_b128 v[210:213], v151 offset:2048
	ds_read_b128 v[214:217], v151 offset:3072
	global_load_lds_dwordx4 v[146:147], off
	v_lshl_add_u64 v[218:219], s[26:27], 0, v[134:135]
	s_mov_b32 m0, s37
	s_nop 0
	global_load_lds_dwordx4 v[218:219], off
	s_barrier
	s_waitcnt lgkmcnt(0)
	s_setprio 1
	s_waitcnt lgkmcnt(0)
	v_mfma_f32_16x16x32_bf16 v[116:119], v[202:205], v[170:173], v[116:119]
	v_mfma_f32_16x16x32_bf16 v[112:115], v[210:213], v[170:173], v[112:115]
	v_mfma_f32_16x16x32_bf16 v[100:103], v[202:205], v[178:181], v[100:103]
	v_mfma_f32_16x16x32_bf16 v[96:99], v[210:213], v[178:181], v[96:99]
	v_mfma_f32_16x16x32_bf16 v[84:87], v[202:205], v[186:189], v[84:87]
	v_mfma_f32_16x16x32_bf16 v[80:83], v[210:213], v[186:189], v[80:83]
	v_mfma_f32_16x16x32_bf16 v[68:71], v[202:205], v[194:197], v[68:71]
	v_mfma_f32_16x16x32_bf16 v[64:67], v[210:213], v[194:197], v[64:67]
	v_mfma_f32_16x16x32_bf16 v[116:119], v[206:209], v[174:177], v[116:119]
	v_mfma_f32_16x16x32_bf16 v[112:115], v[214:217], v[174:177], v[112:115]
	v_mfma_f32_16x16x32_bf16 v[100:103], v[206:209], v[182:185], v[100:103]
	v_mfma_f32_16x16x32_bf16 v[96:99], v[214:217], v[182:185], v[96:99]
	v_mfma_f32_16x16x32_bf16 v[84:87], v[206:209], v[190:193], v[84:87]
	v_mfma_f32_16x16x32_bf16 v[80:83], v[214:217], v[190:193], v[80:83]
	v_mfma_f32_16x16x32_bf16 v[68:71], v[206:209], v[198:201], v[68:71]
	v_mfma_f32_16x16x32_bf16 v[64:67], v[214:217], v[198:201], v[64:67]
	s_setprio 0
	s_mov_b32 m0, s38
	v_lshl_add_u64 v[220:221], s[28:29], 0, v[128:129]
	s_barrier
	ds_read_b128 v[170:173], v150 offset:16384
	ds_read_b128 v[174:177], v150 offset:17408
	ds_read_b128 v[178:181], v150 offset:18432
	ds_read_b128 v[182:185], v150 offset:19456
	ds_read_b128 v[186:189], v150 offset:20480
	ds_read_b128 v[190:193], v150 offset:21504
	ds_read_b128 v[194:197], v150 offset:22528
	ds_read_b128 v[198:201], v150 offset:23552
	global_load_lds_dwordx4 v[220:221], off
	v_lshl_add_u64 v[222:223], s[28:29], 0, v[132:133]
	s_mov_b32 m0, s39
	s_nop 0
	global_load_lds_dwordx4 v[222:223], off
	s_barrier
	s_waitcnt lgkmcnt(0)
	s_setprio 1
	s_waitcnt lgkmcnt(0)
	v_mfma_f32_16x16x32_bf16 v[60:63], v[154:157], v[170:173], v[60:63]
	v_mfma_f32_16x16x32_bf16 v[56:59], v[162:165], v[170:173], v[56:59]
	v_mfma_f32_16x16x32_bf16 v[44:47], v[154:157], v[178:181], v[44:47]
	v_mfma_f32_16x16x32_bf16 v[40:43], v[162:165], v[178:181], v[40:43]
	v_mfma_f32_16x16x32_bf16 v[28:31], v[154:157], v[186:189], v[28:31]
	v_mfma_f32_16x16x32_bf16 v[24:27], v[162:165], v[186:189], v[24:27]
	v_mfma_f32_16x16x32_bf16 v[12:15], v[154:157], v[194:197], v[12:15]
	v_mfma_f32_16x16x32_bf16 v[8:11], v[162:165], v[194:197], v[8:11]
	v_mfma_f32_16x16x32_bf16 v[60:63], v[158:161], v[174:177], v[60:63]
	v_mfma_f32_16x16x32_bf16 v[56:59], v[166:169], v[174:177], v[56:59]
	v_mfma_f32_16x16x32_bf16 v[44:47], v[158:161], v[182:185], v[44:47]
	v_mfma_f32_16x16x32_bf16 v[40:43], v[166:169], v[182:185], v[40:43]
	v_mfma_f32_16x16x32_bf16 v[28:31], v[158:161], v[190:193], v[28:31]
	v_mfma_f32_16x16x32_bf16 v[24:27], v[166:169], v[190:193], v[24:27]
	v_mfma_f32_16x16x32_bf16 v[12:15], v[158:161], v[198:201], v[12:15]
	v_mfma_f32_16x16x32_bf16 v[8:11], v[166:169], v[198:201], v[8:11]
	s_setprio 0
	s_barrier
	s_add_u32 s60, s26, 0x40000
	s_addc_u32 s61, s27, 0
	s_mov_b32 m0, s40
	v_lshl_add_u64 v[154:155], s[60:61], 0, v[130:131]
	global_load_lds_dwordx4 v[154:155], off
	v_lshl_add_u64 v[154:155], s[60:61], 0, v[134:135]
	s_mov_b32 m0, s41
	s_nop 0
	global_load_lds_dwordx4 v[154:155], off
	s_waitcnt vmcnt(6)
	s_barrier
	s_setprio 1
	v_mfma_f32_16x16x32_bf16 v[52:55], v[202:205], v[170:173], v[52:55]
	v_mfma_f32_16x16x32_bf16 v[48:51], v[210:213], v[170:173], v[48:51]
	v_mfma_f32_16x16x32_bf16 v[36:39], v[202:205], v[178:181], v[36:39]
	v_mfma_f32_16x16x32_bf16 v[32:35], v[210:213], v[178:181], v[32:35]
	v_mfma_f32_16x16x32_bf16 v[20:23], v[202:205], v[186:189], v[20:23]
	v_mfma_f32_16x16x32_bf16 v[16:19], v[210:213], v[186:189], v[16:19]
	v_mfma_f32_16x16x32_bf16 v[4:7], v[202:205], v[194:197], v[4:7]
	v_mfma_f32_16x16x32_bf16 v[0:3], v[210:213], v[194:197], v[0:3]
	v_mfma_f32_16x16x32_bf16 v[52:55], v[206:209], v[174:177], v[52:55]
	v_mfma_f32_16x16x32_bf16 v[48:51], v[214:217], v[174:177], v[48:51]
	v_mfma_f32_16x16x32_bf16 v[36:39], v[206:209], v[182:185], v[36:39]
	v_mfma_f32_16x16x32_bf16 v[32:35], v[214:217], v[182:185], v[32:35]
	v_mfma_f32_16x16x32_bf16 v[20:23], v[206:209], v[190:193], v[20:23]
	v_mfma_f32_16x16x32_bf16 v[16:19], v[214:217], v[190:193], v[16:19]
	v_mfma_f32_16x16x32_bf16 v[4:7], v[206:209], v[198:201], v[4:7]
	v_mfma_f32_16x16x32_bf16 v[0:3], v[214:217], v[198:201], v[0:3]
	s_setprio 0
	s_barrier
	ds_read_b128 v[154:157], v152
	ds_read_b128 v[158:161], v152 offset:1024
	ds_read_b128 v[162:165], v152 offset:2048
	ds_read_b128 v[166:169], v152 offset:3072
	s_add_u32 s28, s28, 0x40000
	s_addc_u32 s29, s29, 0
	s_mov_b32 m0, s42
	v_lshl_add_u64 v[202:203], s[28:29], 0, v[128:129]
	ds_read_b128 v[170:173], v150 offset:32768
	ds_read_b128 v[174:177], v150 offset:33792
	ds_read_b128 v[178:181], v150 offset:34816
	ds_read_b128 v[182:185], v150 offset:35840
	ds_read_b128 v[186:189], v150 offset:36864
	ds_read_b128 v[190:193], v150 offset:37888
	ds_read_b128 v[194:197], v150 offset:38912
	ds_read_b128 v[198:201], v150 offset:39936
	global_load_lds_dwordx4 v[202:203], off
	v_lshl_add_u64 v[202:203], s[28:29], 0, v[132:133]
	s_mov_b32 m0, s43
	s_nop 0
	global_load_lds_dwordx4 v[202:203], off
	s_waitcnt lgkmcnt(8)
	s_barrier
	s_waitcnt lgkmcnt(0)
	s_setprio 1
	s_waitcnt lgkmcnt(0)
	v_mfma_f32_16x16x32_bf16 v[124:127], v[154:157], v[170:173], v[124:127]
	v_mfma_f32_16x16x32_bf16 v[120:123], v[162:165], v[170:173], v[120:123]
	v_mfma_f32_16x16x32_bf16 v[108:111], v[154:157], v[178:181], v[108:111]
	v_mfma_f32_16x16x32_bf16 v[104:107], v[162:165], v[178:181], v[104:107]
	v_mfma_f32_16x16x32_bf16 v[92:95], v[154:157], v[186:189], v[92:95]
	v_mfma_f32_16x16x32_bf16 v[88:91], v[162:165], v[186:189], v[88:91]
	v_mfma_f32_16x16x32_bf16 v[76:79], v[154:157], v[194:197], v[76:79]
	v_mfma_f32_16x16x32_bf16 v[72:75], v[162:165], v[194:197], v[72:75]
	v_mfma_f32_16x16x32_bf16 v[124:127], v[158:161], v[174:177], v[124:127]
	v_mfma_f32_16x16x32_bf16 v[120:123], v[166:169], v[174:177], v[120:123]
	v_mfma_f32_16x16x32_bf16 v[108:111], v[158:161], v[182:185], v[108:111]
	v_mfma_f32_16x16x32_bf16 v[104:107], v[166:169], v[182:185], v[104:107]
	v_mfma_f32_16x16x32_bf16 v[92:95], v[158:161], v[190:193], v[92:95]
	v_mfma_f32_16x16x32_bf16 v[88:91], v[166:169], v[190:193], v[88:91]
	v_mfma_f32_16x16x32_bf16 v[76:79], v[158:161], v[198:201], v[76:79]
	v_mfma_f32_16x16x32_bf16 v[72:75], v[166:169], v[198:201], v[72:75]
	s_setprio 0
	s_barrier
	s_mov_b32 m0, s46
	v_lshl_add_u64 v[146:147], v[146:147], 0, s[10:11]
	ds_read_b128 v[202:205], v153
	ds_read_b128 v[206:209], v153 offset:1024
	ds_read_b128 v[210:213], v153 offset:2048
	ds_read_b128 v[214:217], v153 offset:3072
	global_load_lds_dwordx4 v[146:147], off
	v_lshl_add_u64 v[146:147], v[218:219], 0, s[10:11]
	s_mov_b32 m0, s47
	s_nop 0
	global_load_lds_dwordx4 v[146:147], off
	s_barrier
	s_waitcnt lgkmcnt(0)
	s_setprio 1
	s_waitcnt lgkmcnt(0)
	v_mfma_f32_16x16x32_bf16 v[116:119], v[202:205], v[170:173], v[116:119]
	v_mfma_f32_16x16x32_bf16 v[112:115], v[210:213], v[170:173], v[112:115]
	v_mfma_f32_16x16x32_bf16 v[100:103], v[202:205], v[178:181], v[100:103]
	v_mfma_f32_16x16x32_bf16 v[96:99], v[210:213], v[178:181], v[96:99]
	v_mfma_f32_16x16x32_bf16 v[84:87], v[202:205], v[186:189], v[84:87]
	v_mfma_f32_16x16x32_bf16 v[80:83], v[210:213], v[186:189], v[80:83]
	v_mfma_f32_16x16x32_bf16 v[68:71], v[202:205], v[194:197], v[68:71]
	v_mfma_f32_16x16x32_bf16 v[64:67], v[210:213], v[194:197], v[64:67]
	v_mfma_f32_16x16x32_bf16 v[116:119], v[206:209], v[174:177], v[116:119]
	v_mfma_f32_16x16x32_bf16 v[112:115], v[214:217], v[174:177], v[112:115]
	v_mfma_f32_16x16x32_bf16 v[100:103], v[206:209], v[182:185], v[100:103]
	v_mfma_f32_16x16x32_bf16 v[96:99], v[214:217], v[182:185], v[96:99]
	v_mfma_f32_16x16x32_bf16 v[84:87], v[206:209], v[190:193], v[84:87]
	v_mfma_f32_16x16x32_bf16 v[80:83], v[214:217], v[190:193], v[80:83]
	v_mfma_f32_16x16x32_bf16 v[68:71], v[206:209], v[198:201], v[68:71]
	v_mfma_f32_16x16x32_bf16 v[64:67], v[214:217], v[198:201], v[64:67]
	s_setprio 0
	s_mov_b32 m0, s48
	v_lshl_add_u64 v[146:147], v[220:221], 0, s[10:11]
	s_barrier
	ds_read_b128 v[170:173], v150 offset:49152
	ds_read_b128 v[174:177], v150 offset:50176
	ds_read_b128 v[178:181], v150 offset:51200
	ds_read_b128 v[182:185], v150 offset:52224
	ds_read_b128 v[186:189], v150 offset:53248
	ds_read_b128 v[190:193], v150 offset:54272
	ds_read_b128 v[194:197], v150 offset:55296
	ds_read_b128 v[198:201], v150 offset:56320
	global_load_lds_dwordx4 v[146:147], off
	v_lshl_add_u64 v[146:147], v[222:223], 0, s[10:11]
	s_mov_b32 m0, s49
	s_nop 0
	global_load_lds_dwordx4 v[146:147], off
	s_barrier
	s_waitcnt lgkmcnt(0)
	s_setprio 1
	s_waitcnt lgkmcnt(0)
	v_mfma_f32_16x16x32_bf16 v[60:63], v[154:157], v[170:173], v[60:63]
	v_mfma_f32_16x16x32_bf16 v[56:59], v[162:165], v[170:173], v[56:59]
	v_mfma_f32_16x16x32_bf16 v[44:47], v[154:157], v[178:181], v[44:47]
	v_mfma_f32_16x16x32_bf16 v[40:43], v[162:165], v[178:181], v[40:43]
	v_mfma_f32_16x16x32_bf16 v[28:31], v[154:157], v[186:189], v[28:31]
	v_mfma_f32_16x16x32_bf16 v[24:27], v[162:165], v[186:189], v[24:27]
	v_mfma_f32_16x16x32_bf16 v[12:15], v[154:157], v[194:197], v[12:15]
	v_mfma_f32_16x16x32_bf16 v[8:11], v[162:165], v[194:197], v[8:11]
	v_mfma_f32_16x16x32_bf16 v[60:63], v[158:161], v[174:177], v[60:63]
	v_mfma_f32_16x16x32_bf16 v[56:59], v[166:169], v[174:177], v[56:59]
	v_mfma_f32_16x16x32_bf16 v[44:47], v[158:161], v[182:185], v[44:47]
	v_mfma_f32_16x16x32_bf16 v[40:43], v[166:169], v[182:185], v[40:43]
	v_mfma_f32_16x16x32_bf16 v[28:31], v[158:161], v[190:193], v[28:31]
	v_mfma_f32_16x16x32_bf16 v[24:27], v[166:169], v[190:193], v[24:27]
	v_mfma_f32_16x16x32_bf16 v[12:15], v[158:161], v[198:201], v[12:15]
	v_mfma_f32_16x16x32_bf16 v[8:11], v[166:169], v[198:201], v[8:11]
	s_setprio 0
	s_barrier
	s_add_u32 s26, s26, 0x40080
	s_addc_u32 s27, s27, 0
	s_mov_b32 m0, s50
	v_lshl_add_u64 v[146:147], s[26:27], 0, v[130:131]
	global_load_lds_dwordx4 v[146:147], off
	v_lshl_add_u64 v[146:147], s[26:27], 0, v[134:135]
	s_mov_b32 m0, s51
	s_nop 0
	global_load_lds_dwordx4 v[146:147], off
	s_waitcnt vmcnt(6)
	s_barrier
	s_setprio 1
	v_mfma_f32_16x16x32_bf16 v[52:55], v[202:205], v[170:173], v[52:55]
	v_mfma_f32_16x16x32_bf16 v[48:51], v[210:213], v[170:173], v[48:51]
	v_mfma_f32_16x16x32_bf16 v[36:39], v[202:205], v[178:181], v[36:39]
	v_mfma_f32_16x16x32_bf16 v[32:35], v[210:213], v[178:181], v[32:35]
	v_mfma_f32_16x16x32_bf16 v[20:23], v[202:205], v[186:189], v[20:23]
	v_mfma_f32_16x16x32_bf16 v[16:19], v[210:213], v[186:189], v[16:19]
	v_mfma_f32_16x16x32_bf16 v[4:7], v[202:205], v[194:197], v[4:7]
	v_mfma_f32_16x16x32_bf16 v[0:3], v[210:213], v[194:197], v[0:3]
	v_mfma_f32_16x16x32_bf16 v[52:55], v[206:209], v[174:177], v[52:55]
	v_mfma_f32_16x16x32_bf16 v[48:51], v[214:217], v[174:177], v[48:51]
	v_mfma_f32_16x16x32_bf16 v[36:39], v[206:209], v[182:185], v[36:39]
	v_mfma_f32_16x16x32_bf16 v[32:35], v[214:217], v[182:185], v[32:35]
	v_mfma_f32_16x16x32_bf16 v[20:23], v[206:209], v[190:193], v[20:23]
	v_mfma_f32_16x16x32_bf16 v[16:19], v[214:217], v[190:193], v[16:19]
	v_mfma_f32_16x16x32_bf16 v[4:7], v[206:209], v[198:201], v[4:7]
	v_mfma_f32_16x16x32_bf16 v[0:3], v[214:217], v[198:201], v[0:3]
	s_setprio 0
	s_add_i32 s59, s59, 2
	s_add_u32 s24, s24, 0x100
	s_addc_u32 s25, s25, 0
	s_add_u32 s57, s57, 0x100
	s_addc_u32 s58, s58, 0
	s_cmp_gt_u32 s59, 13
	s_barrier
	s_cbranch_scc0 .LBB0_680
	v_mul_f32_e32 v124, 0xbfb8aa3b, v124
	v_mul_f32_e32 v125, 0xbfb8aa3b, v125
	v_mul_f32_e32 v120, 0xbfb8aa3b, v120
	v_mul_f32_e32 v121, 0xbfb8aa3b, v121
	v_exp_f32_e32 v124, v124
	v_exp_f32_e32 v125, v125
	v_exp_f32_e32 v120, v120
	v_exp_f32_e32 v121, v121
	v_mov_b32_e32 v136, 0
	v_mul_f32_e32 v126, 0xbfb8aa3b, v126
	v_mul_f32_e32 v127, 0xbfb8aa3b, v127
	v_mul_f32_e32 v122, 0xbfb8aa3b, v122
	v_exp_f32_e32 v126, v126
	v_exp_f32_e32 v127, v127
	v_exp_f32_e32 v122, v122
	v_mul_f32_e32 v123, 0xbfb8aa3b, v123
	v_mbcnt_lo_u32_b32 v136, -1, v136
	s_lshl_b32 s15, s22, 8
	v_exp_f32_e32 v123, v123
	v_mbcnt_hi_u32_b32 v136, -1, v136
	s_add_i32 s15, s15, s44
	v_add_f32_e32 v124, 1.0, v124
	v_add_f32_e32 v125, 1.0, v125
	v_add_f32_e32 v120, 1.0, v120
	v_add_f32_e32 v121, 1.0, v121
	v_and_or_b32 v146, v136, 15, s15
	s_lshl_b32 s15, s54, 8
	v_ashrrev_i32_e32 v136, 1, v136
	v_rcp_f32_e32 v124, v124
	v_rcp_f32_e32 v125, v125
	v_rcp_f32_e32 v120, v120
	v_rcp_f32_e32 v121, v121
	v_and_b32_e32 v136, -8, v136
	s_or_b32 s15, s15, s45
	v_add_f32_e32 v126, 1.0, v126
	v_add_f32_e32 v127, 1.0, v127
	v_add_f32_e32 v122, 1.0, v122
	v_mul_f32_e32 v116, 0xbfb8aa3b, v116
	v_mul_f32_e32 v117, 0xbfb8aa3b, v117
	v_mul_f32_e32 v118, 0xbfb8aa3b, v118
	v_mul_f32_e32 v119, 0xbfb8aa3b, v119
	v_mul_f32_e32 v112, 0xbfb8aa3b, v112
	v_mul_f32_e32 v113, 0xbfb8aa3b, v113
	v_add_u32_e32 v154, s15, v136
	v_rcp_f32_e32 v126, v126
	v_rcp_f32_e32 v127, v127
	v_rcp_f32_e32 v136, v122
	v_add_f32_e32 v122, 1.0, v123
	v_exp_f32_e32 v116, v116
	v_exp_f32_e32 v117, v117
	v_exp_f32_e32 v118, v118
	v_exp_f32_e32 v119, v119
	v_exp_f32_e32 v112, v112
	v_exp_f32_e32 v113, v113
	v_rcp_f32_e32 v155, v122
	v_mul_f32_e32 v114, 0xbfb8aa3b, v114
	v_mul_f32_e32 v115, 0xbfb8aa3b, v115
	v_cvt_pk_bf16_f32 v122, v124, v125
	v_cvt_pk_bf16_f32 v124, v120, v121
	v_lshrrev_b32_e32 v120, 8, v154
	v_exp_f32_e32 v114, v114
	v_exp_f32_e32 v115, v115
	v_ashrrev_i32_e32 v147, 31, v146
	v_mul_hi_i32_i24_e32 v121, 0x4080, v120
	v_mul_i32_i24_e32 v120, 0x4080, v120
	v_cvt_pk_bf16_f32 v123, v126, v127
	v_lshl_add_u64 v[126:127], v[120:121], 0, v[146:147]
	v_add_f32_e32 v116, 1.0, v116
	v_add_f32_e32 v117, 1.0, v117
	v_add_f32_e32 v118, 1.0, v118
	v_add_f32_e32 v119, 1.0, v119
	v_add_f32_e32 v112, 1.0, v112
	v_add_f32_e32 v113, 1.0, v113
	v_cvt_pk_bf16_f32 v125, v136, v155
	v_and_b32_e32 v136, 0xf8, v154
	v_mbcnt_lo_u32_b32 v230, -1, 0
	v_mbcnt_hi_u32_b32 v230, -1, v230
	v_and_b32_e32 v231, 15, v230
	v_bfe_u32 v232, v154, 4, 4
	v_sub_u32_e32 v232, v232, v231
	v_lshlrev_b32_e32 v232, 9, v232
	v_lshl_add_u32 v232, v231, 4, v232
	v_bfe_u32 v233, v230, 4, 1
	v_lshl_add_u32 v232, v233, 8, v232
	v_and_b32_e32 v233, 0xf8, v154
	v_lshlrev_b32_e32 v233, 1, v233
	v_sub_u32_e32 v226, v232, v233
	v_ashrrev_i32_e32 v227, 31, v226
	v_add_u32_e32 v228, 0xf00, v226
	v_ashrrev_i32_e32 v229, 31, v228
	v_lshlrev_b64 v[126:127], 9, v[126:127]
	v_rcp_f32_e32 v116, v116
	v_rcp_f32_e32 v117, v117
	v_rcp_f32_e32 v118, v118
	v_rcp_f32_e32 v119, v119
	v_rcp_f32_e32 v112, v112
	v_rcp_f32_e32 v113, v113
	v_lshl_add_u64 v[126:127], s[12:13], 0, v[126:127]
	v_lshlrev_b32_e32 v136, 1, v136
	v_add_f32_e32 v114, 1.0, v114
	v_add_f32_e32 v115, 1.0, v115
	v_lshl_add_u64 v[126:127], v[126:127], 0, v[136:137]
	v_rcp_f32_e32 v114, v114
	v_rcp_f32_e32 v115, v115
	v_lshl_add_u64 v[126:127], v[126:127], 0, v[226:227]
	global_store_dwordx4 v[126:127], v[122:125], off
	v_cvt_pk_bf16_f32 v116, v116, v117
	v_cvt_pk_bf16_f32 v117, v118, v119
	v_add_u32_e32 v122, 0x80, v154
	v_cvt_pk_bf16_f32 v118, v112, v113
	v_lshrrev_b32_e32 v112, 8, v122
	v_mul_f32_e32 v104, 0xbfb8aa3b, v104
	v_mul_hi_i32_i24_e32 v113, 0x4080, v112
	v_mul_i32_i24_e32 v112, 0x4080, v112
	v_exp_f32_e32 v104, v104
	v_mul_f32_e32 v105, 0xbfb8aa3b, v105
	v_cvt_pk_bf16_f32 v119, v114, v115
	v_lshl_add_u64 v[114:115], v[112:113], 0, v[146:147]
	v_exp_f32_e32 v105, v105
	v_and_b32_e32 v124, 0xf8, v122
	v_lshlrev_b64 v[114:115], 9, v[114:115]
	v_lshl_add_u64 v[122:123], s[12:13], 0, v[114:115]
	v_lshlrev_b32_e32 v114, 1, v124
	v_mov_b32_e32 v115, v137
	v_mul_f32_e32 v108, 0xbfb8aa3b, v108
	v_mul_f32_e32 v109, 0xbfb8aa3b, v109
	v_lshl_add_u64 v[122:123], v[122:123], 0, v[114:115]
	v_exp_f32_e32 v108, v108
	v_exp_f32_e32 v109, v109
	v_add_f32_e32 v104, 1.0, v104
	v_lshl_add_u64 v[122:123], v[122:123], 0, v[228:229]
	global_store_dwordx4 v[122:123], v[116:119], off
	v_mul_f32_e32 v110, 0xbfb8aa3b, v110
	v_mul_f32_e32 v111, 0xbfb8aa3b, v111
	v_rcp_f32_e32 v118, v104
	v_add_f32_e32 v104, 1.0, v105
	v_mul_f32_e32 v105, 0xbfb8aa3b, v106
	v_exp_f32_e32 v105, v105
	v_mul_f32_e32 v106, 0xbfb8aa3b, v107
	v_exp_f32_e32 v110, v110
	v_exp_f32_e32 v111, v111
	v_exp_f32_e32 v106, v106
	v_add_f32_e32 v108, 1.0, v108
	v_add_f32_e32 v109, 1.0, v109
	v_rcp_f32_e32 v108, v108
	v_rcp_f32_e32 v109, v109
	v_rcp_f32_e32 v107, v104
	v_add_f32_e32 v104, 1.0, v105
	v_or_b32_e32 v116, 16, v146
	v_add_f32_e32 v110, 1.0, v110
	v_add_f32_e32 v111, 1.0, v111
	v_rcp_f32_e32 v119, v104
	v_add_f32_e32 v104, 1.0, v106
	v_mul_f32_e32 v96, 0xbfb8aa3b, v96
	v_ashrrev_i32_e32 v117, 31, v116
	v_rcp_f32_e32 v110, v110
	v_rcp_f32_e32 v111, v111
	v_rcp_f32_e32 v122, v104
	v_exp_f32_e32 v96, v96
	v_mul_f32_e32 v97, 0xbfb8aa3b, v97
	v_cvt_pk_bf16_f32 v104, v108, v109
	v_lshl_add_u64 v[108:109], v[120:121], 0, v[116:117]
	v_exp_f32_e32 v97, v97
	v_lshlrev_b64 v[108:109], 9, v[108:109]
	v_lshl_add_u64 v[108:109], s[12:13], 0, v[108:109]
	v_mul_f32_e32 v100, 0xbfb8aa3b, v100
	v_mul_f32_e32 v101, 0xbfb8aa3b, v101
	v_cvt_pk_bf16_f32 v105, v110, v111
	v_cvt_pk_bf16_f32 v106, v118, v107
	v_cvt_pk_bf16_f32 v107, v119, v122
	v_lshl_add_u64 v[108:109], v[108:109], 0, v[136:137]
	v_exp_f32_e32 v100, v100
	v_exp_f32_e32 v101, v101
	v_add_f32_e32 v96, 1.0, v96
	v_lshl_add_u64 v[108:109], v[108:109], 0, v[226:227]
	global_store_dwordx4 v[108:109], v[104:107], off
	v_mul_f32_e32 v102, 0xbfb8aa3b, v102
	v_mul_f32_e32 v103, 0xbfb8aa3b, v103
	v_rcp_f32_e32 v104, v96
	v_add_f32_e32 v96, 1.0, v97
	v_mul_f32_e32 v97, 0xbfb8aa3b, v98
	v_exp_f32_e32 v97, v97
	v_mul_f32_e32 v98, 0xbfb8aa3b, v99
	v_exp_f32_e32 v102, v102
	v_exp_f32_e32 v103, v103
	v_exp_f32_e32 v98, v98
	v_add_f32_e32 v100, 1.0, v100
	v_add_f32_e32 v101, 1.0, v101
	v_rcp_f32_e32 v100, v100
	v_rcp_f32_e32 v101, v101
	v_rcp_f32_e32 v99, v96
	v_add_f32_e32 v96, 1.0, v97
	v_add_f32_e32 v102, 1.0, v102
	v_add_f32_e32 v103, 1.0, v103
	v_rcp_f32_e32 v105, v96
	v_add_f32_e32 v96, 1.0, v98
	v_mul_f32_e32 v88, 0xbfb8aa3b, v88
	v_rcp_f32_e32 v102, v102
	v_rcp_f32_e32 v103, v103
	v_rcp_f32_e32 v106, v96
	v_exp_f32_e32 v88, v88
	v_mul_f32_e32 v89, 0xbfb8aa3b, v89
	v_cvt_pk_bf16_f32 v96, v100, v101
	v_lshl_add_u64 v[100:101], v[112:113], 0, v[116:117]
	v_exp_f32_e32 v89, v89
	v_lshlrev_b64 v[100:101], 9, v[100:101]
	v_lshl_add_u64 v[100:101], s[12:13], 0, v[100:101]
	v_mul_f32_e32 v92, 0xbfb8aa3b, v92
	v_mul_f32_e32 v93, 0xbfb8aa3b, v93
	v_cvt_pk_bf16_f32 v97, v102, v103
	v_cvt_pk_bf16_f32 v98, v104, v99
	v_cvt_pk_bf16_f32 v99, v105, v106
	v_lshl_add_u64 v[100:101], v[100:101], 0, v[114:115]
	v_exp_f32_e32 v92, v92
	v_exp_f32_e32 v93, v93
	v_add_f32_e32 v88, 1.0, v88
	v_lshl_add_u64 v[100:101], v[100:101], 0, v[228:229]
	global_store_dwordx4 v[100:101], v[96:99], off
	v_mul_f32_e32 v94, 0xbfb8aa3b, v94
	v_mul_f32_e32 v95, 0xbfb8aa3b, v95
	v_rcp_f32_e32 v98, v88
	v_add_f32_e32 v88, 1.0, v89
	v_mul_f32_e32 v89, 0xbfb8aa3b, v90
	v_exp_f32_e32 v89, v89
	v_mul_f32_e32 v90, 0xbfb8aa3b, v91
	v_exp_f32_e32 v94, v94
	v_exp_f32_e32 v95, v95
	v_exp_f32_e32 v90, v90
	v_add_f32_e32 v92, 1.0, v92
	v_add_f32_e32 v93, 1.0, v93
	v_rcp_f32_e32 v92, v92
	v_rcp_f32_e32 v93, v93
	v_rcp_f32_e32 v91, v88
	v_add_f32_e32 v88, 1.0, v89
	v_or_b32_e32 v96, 32, v146
	v_add_f32_e32 v94, 1.0, v94
	v_add_f32_e32 v95, 1.0, v95
	v_rcp_f32_e32 v99, v88
	v_add_f32_e32 v88, 1.0, v90
	v_mul_f32_e32 v80, 0xbfb8aa3b, v80
	v_ashrrev_i32_e32 v97, 31, v96
	v_rcp_f32_e32 v94, v94
	v_rcp_f32_e32 v95, v95
	v_rcp_f32_e32 v100, v88
	v_exp_f32_e32 v80, v80
	v_mul_f32_e32 v81, 0xbfb8aa3b, v81
	v_cvt_pk_bf16_f32 v88, v92, v93
	v_lshl_add_u64 v[92:93], v[120:121], 0, v[96:97]
	v_exp_f32_e32 v81, v81
	v_lshlrev_b64 v[92:93], 9, v[92:93]
	v_lshl_add_u64 v[92:93], s[12:13], 0, v[92:93]
	v_mul_f32_e32 v84, 0xbfb8aa3b, v84
	v_mul_f32_e32 v85, 0xbfb8aa3b, v85
	v_cvt_pk_bf16_f32 v89, v94, v95
	v_cvt_pk_bf16_f32 v90, v98, v91
	v_cvt_pk_bf16_f32 v91, v99, v100
	v_lshl_add_u64 v[92:93], v[92:93], 0, v[136:137]
	v_exp_f32_e32 v84, v84
	v_exp_f32_e32 v85, v85
	v_add_f32_e32 v80, 1.0, v80
	v_lshl_add_u64 v[92:93], v[92:93], 0, v[226:227]
	global_store_dwordx4 v[92:93], v[88:91], off
	v_mul_f32_e32 v86, 0xbfb8aa3b, v86
	v_mul_f32_e32 v87, 0xbfb8aa3b, v87
	v_rcp_f32_e32 v88, v80
	v_add_f32_e32 v80, 1.0, v81
	v_mul_f32_e32 v81, 0xbfb8aa3b, v82
	v_exp_f32_e32 v81, v81
	v_mul_f32_e32 v82, 0xbfb8aa3b, v83
	v_exp_f32_e32 v86, v86
	v_exp_f32_e32 v87, v87
	v_exp_f32_e32 v82, v82
	v_add_f32_e32 v84, 1.0, v84
	v_add_f32_e32 v85, 1.0, v85
	v_rcp_f32_e32 v84, v84
	v_rcp_f32_e32 v85, v85
	v_rcp_f32_e32 v83, v80
	v_add_f32_e32 v80, 1.0, v81
	v_add_f32_e32 v86, 1.0, v86
	v_add_f32_e32 v87, 1.0, v87
	v_rcp_f32_e32 v89, v80
	v_add_f32_e32 v80, 1.0, v82
	v_mul_f32_e32 v72, 0xbfb8aa3b, v72
	v_rcp_f32_e32 v86, v86
	v_rcp_f32_e32 v87, v87
	v_rcp_f32_e32 v90, v80
	v_exp_f32_e32 v72, v72
	v_mul_f32_e32 v73, 0xbfb8aa3b, v73
	v_cvt_pk_bf16_f32 v80, v84, v85
	v_lshl_add_u64 v[84:85], v[112:113], 0, v[96:97]
	v_exp_f32_e32 v73, v73
	v_lshlrev_b64 v[84:85], 9, v[84:85]
	v_lshl_add_u64 v[84:85], s[12:13], 0, v[84:85]
	v_mul_f32_e32 v76, 0xbfb8aa3b, v76
	v_mul_f32_e32 v77, 0xbfb8aa3b, v77
	v_cvt_pk_bf16_f32 v81, v86, v87
	v_cvt_pk_bf16_f32 v82, v88, v83
	v_cvt_pk_bf16_f32 v83, v89, v90
	v_lshl_add_u64 v[84:85], v[84:85], 0, v[114:115]
	v_exp_f32_e32 v76, v76
	v_exp_f32_e32 v77, v77
	v_add_f32_e32 v72, 1.0, v72
	v_lshl_add_u64 v[84:85], v[84:85], 0, v[228:229]
	global_store_dwordx4 v[84:85], v[80:83], off
	v_mul_f32_e32 v78, 0xbfb8aa3b, v78
	v_mul_f32_e32 v79, 0xbfb8aa3b, v79
	v_rcp_f32_e32 v82, v72
	v_add_f32_e32 v72, 1.0, v73
	v_mul_f32_e32 v73, 0xbfb8aa3b, v74
	v_exp_f32_e32 v73, v73
	v_mul_f32_e32 v74, 0xbfb8aa3b, v75
	v_exp_f32_e32 v78, v78
	v_exp_f32_e32 v79, v79
	v_exp_f32_e32 v74, v74
	v_add_f32_e32 v76, 1.0, v76
	v_add_f32_e32 v77, 1.0, v77
	v_rcp_f32_e32 v76, v76
	v_rcp_f32_e32 v77, v77
	v_rcp_f32_e32 v75, v72
	v_add_f32_e32 v72, 1.0, v73
	v_or_b32_e32 v80, 48, v146
	v_add_f32_e32 v78, 1.0, v78
	v_add_f32_e32 v79, 1.0, v79
	v_rcp_f32_e32 v83, v72
	v_add_f32_e32 v72, 1.0, v74
	v_mul_f32_e32 v64, 0xbfb8aa3b, v64
	v_ashrrev_i32_e32 v81, 31, v80
	v_rcp_f32_e32 v78, v78
	v_rcp_f32_e32 v79, v79
	v_rcp_f32_e32 v84, v72
	v_exp_f32_e32 v64, v64
	v_mul_f32_e32 v65, 0xbfb8aa3b, v65
	v_cvt_pk_bf16_f32 v72, v76, v77
	v_lshl_add_u64 v[76:77], v[120:121], 0, v[80:81]
	v_exp_f32_e32 v65, v65
	v_lshlrev_b64 v[76:77], 9, v[76:77]
	v_lshl_add_u64 v[76:77], s[12:13], 0, v[76:77]
	v_mul_f32_e32 v68, 0xbfb8aa3b, v68
	v_mul_f32_e32 v69, 0xbfb8aa3b, v69
	v_cvt_pk_bf16_f32 v73, v78, v79
	v_cvt_pk_bf16_f32 v74, v82, v75
	v_cvt_pk_bf16_f32 v75, v83, v84
	v_lshl_add_u64 v[76:77], v[76:77], 0, v[136:137]
	v_exp_f32_e32 v68, v68
	v_exp_f32_e32 v69, v69
	v_add_f32_e32 v64, 1.0, v64
	v_lshl_add_u64 v[76:77], v[76:77], 0, v[226:227]
	global_store_dwordx4 v[76:77], v[72:75], off
	v_mul_f32_e32 v70, 0xbfb8aa3b, v70
	v_mul_f32_e32 v71, 0xbfb8aa3b, v71
	v_rcp_f32_e32 v72, v64
	v_add_f32_e32 v64, 1.0, v65
	v_mul_f32_e32 v65, 0xbfb8aa3b, v66
	v_exp_f32_e32 v65, v65
	v_mul_f32_e32 v66, 0xbfb8aa3b, v67
	v_exp_f32_e32 v70, v70
	v_exp_f32_e32 v71, v71
	v_exp_f32_e32 v66, v66
	v_add_f32_e32 v68, 1.0, v68
	v_add_f32_e32 v69, 1.0, v69
	v_rcp_f32_e32 v68, v68
	v_rcp_f32_e32 v69, v69
	v_rcp_f32_e32 v67, v64
	v_add_f32_e32 v64, 1.0, v65
	v_add_f32_e32 v70, 1.0, v70
	v_add_f32_e32 v71, 1.0, v71
	v_rcp_f32_e32 v73, v64
	v_add_f32_e32 v64, 1.0, v66
	v_mul_f32_e32 v56, 0xbfb8aa3b, v56
	v_rcp_f32_e32 v70, v70
	v_rcp_f32_e32 v71, v71
	v_rcp_f32_e32 v74, v64
	v_exp_f32_e32 v56, v56
	v_mul_f32_e32 v57, 0xbfb8aa3b, v57
	v_cvt_pk_bf16_f32 v64, v68, v69
	v_lshl_add_u64 v[68:69], v[112:113], 0, v[80:81]
	v_exp_f32_e32 v57, v57
	v_lshlrev_b64 v[68:69], 9, v[68:69]
	v_lshl_add_u64 v[68:69], s[12:13], 0, v[68:69]
	v_mul_f32_e32 v60, 0xbfb8aa3b, v60
	v_mul_f32_e32 v61, 0xbfb8aa3b, v61
	v_cvt_pk_bf16_f32 v65, v70, v71
	v_cvt_pk_bf16_f32 v66, v72, v67
	v_cvt_pk_bf16_f32 v67, v73, v74
	v_lshl_add_u64 v[68:69], v[68:69], 0, v[114:115]
	v_exp_f32_e32 v60, v60
	v_exp_f32_e32 v61, v61
	v_add_f32_e32 v56, 1.0, v56
	v_lshl_add_u64 v[68:69], v[68:69], 0, v[228:229]
	global_store_dwordx4 v[68:69], v[64:67], off
	v_mul_f32_e32 v62, 0xbfb8aa3b, v62
	v_mul_f32_e32 v63, 0xbfb8aa3b, v63
	v_rcp_f32_e32 v66, v56
	v_add_f32_e32 v56, 1.0, v57
	v_mul_f32_e32 v57, 0xbfb8aa3b, v58
	v_exp_f32_e32 v57, v57
	v_mul_f32_e32 v58, 0xbfb8aa3b, v59
	v_exp_f32_e32 v62, v62
	v_exp_f32_e32 v63, v63
	v_exp_f32_e32 v58, v58
	v_add_f32_e32 v60, 1.0, v60
	v_add_f32_e32 v61, 1.0, v61
	v_rcp_f32_e32 v60, v60
	v_rcp_f32_e32 v61, v61
	v_rcp_f32_e32 v59, v56
	v_add_f32_e32 v56, 1.0, v57
	v_add_u32_e32 v64, 0x80, v146
	v_add_f32_e32 v62, 1.0, v62
	v_add_f32_e32 v63, 1.0, v63
	v_rcp_f32_e32 v67, v56
	v_add_f32_e32 v56, 1.0, v58
	v_mul_f32_e32 v48, 0xbfb8aa3b, v48
	v_ashrrev_i32_e32 v65, 31, v64
	v_rcp_f32_e32 v62, v62
	v_rcp_f32_e32 v63, v63
	v_rcp_f32_e32 v68, v56
	v_exp_f32_e32 v48, v48
	v_mul_f32_e32 v49, 0xbfb8aa3b, v49
	v_cvt_pk_bf16_f32 v56, v60, v61
	v_lshl_add_u64 v[60:61], v[120:121], 0, v[64:65]
	v_exp_f32_e32 v49, v49
	v_lshlrev_b64 v[60:61], 9, v[60:61]
	v_lshl_add_u64 v[60:61], s[12:13], 0, v[60:61]
	v_mul_f32_e32 v52, 0xbfb8aa3b, v52
	v_mul_f32_e32 v53, 0xbfb8aa3b, v53
	v_cvt_pk_bf16_f32 v57, v62, v63
	v_cvt_pk_bf16_f32 v58, v66, v59
	v_cvt_pk_bf16_f32 v59, v67, v68
	v_lshl_add_u64 v[60:61], v[60:61], 0, v[136:137]
	v_exp_f32_e32 v52, v52
	v_exp_f32_e32 v53, v53
	v_add_f32_e32 v48, 1.0, v48
	v_lshl_add_u64 v[60:61], v[60:61], 0, v[226:227]
	global_store_dwordx4 v[60:61], v[56:59], off
	v_mul_f32_e32 v54, 0xbfb8aa3b, v54
	v_mul_f32_e32 v55, 0xbfb8aa3b, v55
	v_rcp_f32_e32 v56, v48
	v_add_f32_e32 v48, 1.0, v49
	v_mul_f32_e32 v49, 0xbfb8aa3b, v50
	v_exp_f32_e32 v49, v49
	v_mul_f32_e32 v50, 0xbfb8aa3b, v51
	v_exp_f32_e32 v54, v54
	v_exp_f32_e32 v55, v55
	v_exp_f32_e32 v50, v50
	v_add_f32_e32 v52, 1.0, v52
	v_add_f32_e32 v53, 1.0, v53
	v_rcp_f32_e32 v52, v52
	v_rcp_f32_e32 v53, v53
	v_rcp_f32_e32 v51, v48
	v_add_f32_e32 v48, 1.0, v49
	v_add_f32_e32 v54, 1.0, v54
	v_add_f32_e32 v55, 1.0, v55
	v_rcp_f32_e32 v57, v48
	v_add_f32_e32 v48, 1.0, v50
	v_mul_f32_e32 v40, 0xbfb8aa3b, v40
	v_rcp_f32_e32 v54, v54
	v_rcp_f32_e32 v55, v55
	v_rcp_f32_e32 v58, v48
	v_exp_f32_e32 v40, v40
	v_mul_f32_e32 v41, 0xbfb8aa3b, v41
	v_cvt_pk_bf16_f32 v48, v52, v53
	v_lshl_add_u64 v[52:53], v[112:113], 0, v[64:65]
	v_exp_f32_e32 v41, v41
	v_lshlrev_b64 v[52:53], 9, v[52:53]
	v_lshl_add_u64 v[52:53], s[12:13], 0, v[52:53]
	v_mul_f32_e32 v44, 0xbfb8aa3b, v44
	v_mul_f32_e32 v45, 0xbfb8aa3b, v45
	v_cvt_pk_bf16_f32 v49, v54, v55
	v_cvt_pk_bf16_f32 v50, v56, v51
	v_cvt_pk_bf16_f32 v51, v57, v58
	v_lshl_add_u64 v[52:53], v[52:53], 0, v[114:115]
	v_exp_f32_e32 v44, v44
	v_exp_f32_e32 v45, v45
	v_add_f32_e32 v40, 1.0, v40
	v_lshl_add_u64 v[52:53], v[52:53], 0, v[228:229]
	global_store_dwordx4 v[52:53], v[48:51], off
	v_mul_f32_e32 v46, 0xbfb8aa3b, v46
	v_mul_f32_e32 v47, 0xbfb8aa3b, v47
	v_rcp_f32_e32 v50, v40
	v_add_f32_e32 v40, 1.0, v41
	v_mul_f32_e32 v41, 0xbfb8aa3b, v42
	v_exp_f32_e32 v41, v41
	v_mul_f32_e32 v42, 0xbfb8aa3b, v43
	v_exp_f32_e32 v46, v46
	v_exp_f32_e32 v47, v47
	v_exp_f32_e32 v42, v42
	v_add_f32_e32 v44, 1.0, v44
	v_add_f32_e32 v45, 1.0, v45
	v_rcp_f32_e32 v44, v44
	v_rcp_f32_e32 v45, v45
	v_rcp_f32_e32 v43, v40
	v_add_f32_e32 v40, 1.0, v41
	v_add_u32_e32 v48, 0x90, v146
	v_add_f32_e32 v46, 1.0, v46
	v_add_f32_e32 v47, 1.0, v47
	v_rcp_f32_e32 v51, v40
	v_add_f32_e32 v40, 1.0, v42
	v_mul_f32_e32 v32, 0xbfb8aa3b, v32
	v_ashrrev_i32_e32 v49, 31, v48
	v_rcp_f32_e32 v46, v46
	v_rcp_f32_e32 v47, v47
	v_rcp_f32_e32 v52, v40
	v_exp_f32_e32 v32, v32
	v_mul_f32_e32 v33, 0xbfb8aa3b, v33
	v_cvt_pk_bf16_f32 v40, v44, v45
	v_lshl_add_u64 v[44:45], v[120:121], 0, v[48:49]
	v_exp_f32_e32 v33, v33
	v_lshlrev_b64 v[44:45], 9, v[44:45]
	v_lshl_add_u64 v[44:45], s[12:13], 0, v[44:45]
	v_mul_f32_e32 v36, 0xbfb8aa3b, v36
	v_mul_f32_e32 v37, 0xbfb8aa3b, v37
	v_cvt_pk_bf16_f32 v41, v46, v47
	v_cvt_pk_bf16_f32 v42, v50, v43
	v_cvt_pk_bf16_f32 v43, v51, v52
	v_lshl_add_u64 v[44:45], v[44:45], 0, v[136:137]
	v_exp_f32_e32 v36, v36
	v_exp_f32_e32 v37, v37
	v_add_f32_e32 v32, 1.0, v32
	v_lshl_add_u64 v[44:45], v[44:45], 0, v[226:227]
	global_store_dwordx4 v[44:45], v[40:43], off
	v_mul_f32_e32 v38, 0xbfb8aa3b, v38
	v_mul_f32_e32 v39, 0xbfb8aa3b, v39
	v_rcp_f32_e32 v40, v32
	v_add_f32_e32 v32, 1.0, v33
	v_mul_f32_e32 v33, 0xbfb8aa3b, v34
	v_exp_f32_e32 v33, v33
	v_mul_f32_e32 v34, 0xbfb8aa3b, v35
	v_exp_f32_e32 v38, v38
	v_exp_f32_e32 v39, v39
	v_exp_f32_e32 v34, v34
	v_add_f32_e32 v36, 1.0, v36
	v_add_f32_e32 v37, 1.0, v37
	v_rcp_f32_e32 v36, v36
	v_rcp_f32_e32 v37, v37
	v_rcp_f32_e32 v35, v32
	v_add_f32_e32 v32, 1.0, v33
	v_add_f32_e32 v38, 1.0, v38
	v_add_f32_e32 v39, 1.0, v39
	v_rcp_f32_e32 v41, v32
	v_add_f32_e32 v32, 1.0, v34
	v_mul_f32_e32 v24, 0xbfb8aa3b, v24
	v_rcp_f32_e32 v38, v38
	v_rcp_f32_e32 v39, v39
	v_rcp_f32_e32 v42, v32
	v_exp_f32_e32 v24, v24
	v_mul_f32_e32 v25, 0xbfb8aa3b, v25
	v_cvt_pk_bf16_f32 v32, v36, v37
	v_lshl_add_u64 v[36:37], v[112:113], 0, v[48:49]
	v_exp_f32_e32 v25, v25
	v_lshlrev_b64 v[36:37], 9, v[36:37]
	v_lshl_add_u64 v[36:37], s[12:13], 0, v[36:37]
	v_mul_f32_e32 v28, 0xbfb8aa3b, v28
	v_mul_f32_e32 v29, 0xbfb8aa3b, v29
	v_cvt_pk_bf16_f32 v33, v38, v39
	v_cvt_pk_bf16_f32 v34, v40, v35
	v_cvt_pk_bf16_f32 v35, v41, v42
	v_lshl_add_u64 v[36:37], v[36:37], 0, v[114:115]
	v_exp_f32_e32 v28, v28
	v_exp_f32_e32 v29, v29
	v_add_f32_e32 v24, 1.0, v24
	v_lshl_add_u64 v[36:37], v[36:37], 0, v[228:229]
	global_store_dwordx4 v[36:37], v[32:35], off
	v_mul_f32_e32 v30, 0xbfb8aa3b, v30
	v_mul_f32_e32 v31, 0xbfb8aa3b, v31
	v_rcp_f32_e32 v34, v24
	v_add_f32_e32 v24, 1.0, v25
	v_mul_f32_e32 v25, 0xbfb8aa3b, v26
	v_exp_f32_e32 v25, v25
	v_mul_f32_e32 v26, 0xbfb8aa3b, v27
	v_exp_f32_e32 v30, v30
	v_exp_f32_e32 v31, v31
	v_exp_f32_e32 v26, v26
	v_add_f32_e32 v28, 1.0, v28
	v_add_f32_e32 v29, 1.0, v29
	v_rcp_f32_e32 v28, v28
	v_rcp_f32_e32 v29, v29
	v_rcp_f32_e32 v27, v24
	v_add_f32_e32 v24, 1.0, v25
	v_add_u32_e32 v32, 0xa0, v146
	v_add_f32_e32 v30, 1.0, v30
	v_add_f32_e32 v31, 1.0, v31
	v_rcp_f32_e32 v35, v24
	v_add_f32_e32 v24, 1.0, v26
	v_mul_f32_e32 v16, 0xbfb8aa3b, v16
	v_ashrrev_i32_e32 v33, 31, v32
	v_rcp_f32_e32 v30, v30
	v_rcp_f32_e32 v31, v31
	v_rcp_f32_e32 v36, v24
	v_exp_f32_e32 v16, v16
	v_mul_f32_e32 v17, 0xbfb8aa3b, v17
	v_cvt_pk_bf16_f32 v24, v28, v29
	v_lshl_add_u64 v[28:29], v[120:121], 0, v[32:33]
	v_exp_f32_e32 v17, v17
	v_lshlrev_b64 v[28:29], 9, v[28:29]
	v_lshl_add_u64 v[28:29], s[12:13], 0, v[28:29]
	v_mul_f32_e32 v20, 0xbfb8aa3b, v20
	v_mul_f32_e32 v21, 0xbfb8aa3b, v21
	v_cvt_pk_bf16_f32 v25, v30, v31
	v_cvt_pk_bf16_f32 v26, v34, v27
	v_cvt_pk_bf16_f32 v27, v35, v36
	v_lshl_add_u64 v[28:29], v[28:29], 0, v[136:137]
	v_exp_f32_e32 v20, v20
	v_exp_f32_e32 v21, v21
	v_add_f32_e32 v16, 1.0, v16
	v_lshl_add_u64 v[28:29], v[28:29], 0, v[226:227]
	global_store_dwordx4 v[28:29], v[24:27], off
	v_mul_f32_e32 v22, 0xbfb8aa3b, v22
	v_mul_f32_e32 v23, 0xbfb8aa3b, v23
	v_rcp_f32_e32 v24, v16
	v_add_f32_e32 v16, 1.0, v17
	v_mul_f32_e32 v17, 0xbfb8aa3b, v18
	v_exp_f32_e32 v17, v17
	v_mul_f32_e32 v18, 0xbfb8aa3b, v19
	v_exp_f32_e32 v22, v22
	v_exp_f32_e32 v23, v23
	v_exp_f32_e32 v18, v18
	v_add_f32_e32 v20, 1.0, v20
	v_add_f32_e32 v21, 1.0, v21
	v_rcp_f32_e32 v20, v20
	v_rcp_f32_e32 v21, v21
	v_rcp_f32_e32 v19, v16
	v_add_f32_e32 v16, 1.0, v17
	v_add_f32_e32 v22, 1.0, v22
	v_add_f32_e32 v23, 1.0, v23
	v_rcp_f32_e32 v25, v16
	v_add_f32_e32 v16, 1.0, v18
	v_mul_f32_e32 v8, 0xbfb8aa3b, v8
	v_rcp_f32_e32 v22, v22
	v_rcp_f32_e32 v23, v23
	v_rcp_f32_e32 v26, v16
	v_exp_f32_e32 v8, v8
	v_mul_f32_e32 v9, 0xbfb8aa3b, v9
	v_cvt_pk_bf16_f32 v16, v20, v21
	v_lshl_add_u64 v[20:21], v[112:113], 0, v[32:33]
	v_exp_f32_e32 v9, v9
	v_lshlrev_b64 v[20:21], 9, v[20:21]
	v_lshl_add_u64 v[20:21], s[12:13], 0, v[20:21]
	v_mul_f32_e32 v12, 0xbfb8aa3b, v12
	v_mul_f32_e32 v13, 0xbfb8aa3b, v13
	v_cvt_pk_bf16_f32 v17, v22, v23
	v_cvt_pk_bf16_f32 v18, v24, v19
	v_cvt_pk_bf16_f32 v19, v25, v26
	v_lshl_add_u64 v[20:21], v[20:21], 0, v[114:115]
	v_exp_f32_e32 v12, v12
	v_exp_f32_e32 v13, v13
	v_add_f32_e32 v8, 1.0, v8
	v_lshl_add_u64 v[20:21], v[20:21], 0, v[228:229]
	global_store_dwordx4 v[20:21], v[16:19], off
	v_mul_f32_e32 v14, 0xbfb8aa3b, v14
	v_mul_f32_e32 v15, 0xbfb8aa3b, v15
	v_rcp_f32_e32 v18, v8
	v_add_f32_e32 v8, 1.0, v9
	v_mul_f32_e32 v9, 0xbfb8aa3b, v10
	v_exp_f32_e32 v9, v9
	v_mul_f32_e32 v10, 0xbfb8aa3b, v11
	v_exp_f32_e32 v14, v14
	v_exp_f32_e32 v15, v15
	v_exp_f32_e32 v10, v10
	v_add_f32_e32 v12, 1.0, v12
	v_add_f32_e32 v13, 1.0, v13
	v_rcp_f32_e32 v12, v12
	v_rcp_f32_e32 v13, v13
	v_rcp_f32_e32 v11, v8
	v_add_f32_e32 v8, 1.0, v9
	v_add_u32_e32 v16, 0xb0, v146
	v_add_f32_e32 v14, 1.0, v14
	v_add_f32_e32 v15, 1.0, v15
	v_rcp_f32_e32 v19, v8
	v_add_f32_e32 v8, 1.0, v10
	v_mul_f32_e32 v0, 0xbfb8aa3b, v0
	v_ashrrev_i32_e32 v17, 31, v16
	v_rcp_f32_e32 v14, v14
	v_rcp_f32_e32 v15, v15
	v_rcp_f32_e32 v20, v8
	v_exp_f32_e32 v0, v0
	v_mul_f32_e32 v1, 0xbfb8aa3b, v1
	v_cvt_pk_bf16_f32 v8, v12, v13
	v_lshl_add_u64 v[12:13], v[120:121], 0, v[16:17]
	v_exp_f32_e32 v1, v1
	v_lshlrev_b64 v[12:13], 9, v[12:13]
	v_lshl_add_u64 v[12:13], s[12:13], 0, v[12:13]
	v_mul_f32_e32 v4, 0xbfb8aa3b, v4
	v_mul_f32_e32 v5, 0xbfb8aa3b, v5
	v_cvt_pk_bf16_f32 v9, v14, v15
	v_cvt_pk_bf16_f32 v10, v18, v11
	v_cvt_pk_bf16_f32 v11, v19, v20
	v_lshl_add_u64 v[12:13], v[12:13], 0, v[136:137]
	v_exp_f32_e32 v4, v4
	v_exp_f32_e32 v5, v5
	v_add_f32_e32 v0, 1.0, v0
	v_lshl_add_u64 v[12:13], v[12:13], 0, v[226:227]
	global_store_dwordx4 v[12:13], v[8:11], off
	v_mul_f32_e32 v6, 0xbfb8aa3b, v6
	v_mul_f32_e32 v7, 0xbfb8aa3b, v7
	v_rcp_f32_e32 v8, v0
	v_add_f32_e32 v0, 1.0, v1
	v_mul_f32_e32 v1, 0xbfb8aa3b, v2
	v_exp_f32_e32 v1, v1
	v_mul_f32_e32 v2, 0xbfb8aa3b, v3
	v_exp_f32_e32 v6, v6
	v_exp_f32_e32 v7, v7
	v_exp_f32_e32 v2, v2
	v_add_f32_e32 v4, 1.0, v4
	v_add_f32_e32 v5, 1.0, v5
	v_rcp_f32_e32 v4, v4
	v_rcp_f32_e32 v5, v5
	v_rcp_f32_e32 v3, v0
	v_add_f32_e32 v0, 1.0, v1
	v_add_f32_e32 v6, 1.0, v6
	v_add_f32_e32 v7, 1.0, v7
	v_rcp_f32_e32 v9, v0
	v_add_f32_e32 v0, 1.0, v2
	v_rcp_f32_e32 v6, v6
	v_rcp_f32_e32 v7, v7
	v_rcp_f32_e32 v10, v0
	v_cvt_pk_bf16_f32 v0, v4, v5
	v_lshl_add_u64 v[4:5], v[112:113], 0, v[16:17]
	v_lshlrev_b64 v[4:5], 9, v[4:5]
	v_lshl_add_u64 v[4:5], s[12:13], 0, v[4:5]
	v_cvt_pk_bf16_f32 v1, v6, v7
	v_cvt_pk_bf16_f32 v2, v8, v3
	v_cvt_pk_bf16_f32 v3, v9, v10
	v_lshl_add_u64 v[4:5], v[4:5], 0, v[114:115]
	s_and_b64 vcc, exec, s[2:3]
	s_mov_b32 s54, s14
	s_mov_b32 s22, s16
	s_mov_b64 s[26:27], s[20:21]
	s_mov_b64 s[24:25], s[18:19]
	v_lshl_add_u64 v[4:5], v[4:5], 0, v[228:229]
	global_store_dwordx4 v[4:5], v[0:3], off
	s_cbranch_vccz .LBB0_673
	s_waitcnt vmcnt(0)
	s_cmpk_gt_u32 s31, 0xff
	s_cbranch_scc1 .LBB0_684
	s_barrier

.LBB0_702:
	s_ashr_i32 s27, s26, 31
	s_lshl_b64 s[28:29], s[26:27], 17
	v_mov_b64_e32 v[0:1], 0x100
	s_add_u32 s28, s16, s28
	v_cmp_lt_i64_e32 vcc, s[6:7], v[0:1]
	s_addc_u32 s29, s17, s29
	ds_read_b128 v[0:3], v216
	ds_read_b128 v[4:7], v216 offset:1024
	ds_read_b128 v[8:11], v216 offset:2048
	ds_read_b128 v[12:15], v216 offset:3072
	s_and_b64 s[30:31], vcc, exec
	s_cselect_b32 s45, s29, s39
	s_cselect_b32 s44, s28, s38
	s_ashr_i32 s25, s24, 31
	s_lshl_b64 s[30:31], s[24:25], 17
	s_add_u32 s30, s14, s30
	s_addc_u32 s31, s15, s31
	s_and_b64 s[42:43], vcc, exec
	s_cselect_b32 s43, s31, s41
	s_cselect_b32 s42, s30, s40
	s_add_u32 s64, s38, 0x10080
	s_addc_u32 s65, s39, 0
	s_add_i32 s27, s48, 0xc000
	v_lshl_add_u64 v[48:49], s[64:65], 0, v[176:177]
	s_mov_b32 m0, s27
	s_add_i32 s25, s48, 0xe000
	ds_read_b128 v[16:19], v217
	ds_read_b128 v[20:23], v217 offset:1024
	ds_read_b128 v[24:27], v217 offset:2048
	ds_read_b128 v[28:31], v217 offset:3072
	ds_read_b128 v[32:35], v217 offset:4096
	ds_read_b128 v[36:39], v217 offset:5120
	ds_read_b128 v[40:43], v217 offset:6144
	ds_read_b128 v[44:47], v217 offset:7168
	global_load_lds_dwordx4 v[48:49], off
	v_lshl_add_u64 v[48:49], s[64:65], 0, v[180:181]
	s_mov_b32 m0, s25
	s_nop 0
	global_load_lds_dwordx4 v[48:49], off
	s_waitcnt lgkmcnt(8)
	s_barrier
	s_waitcnt lgkmcnt(0)
	s_setprio 1
	s_waitcnt lgkmcnt(0)
	v_mfma_f32_16x16x32_bf16 v[48:51], v[0:3], v[16:19], 0
	v_mfma_f32_16x16x32_bf16 v[52:55], v[8:11], v[16:19], 0
	v_mfma_f32_16x16x32_bf16 v[56:59], v[0:3], v[24:27], 0
	v_mfma_f32_16x16x32_bf16 v[60:63], v[8:11], v[24:27], 0
	v_mfma_f32_16x16x32_bf16 v[64:67], v[0:3], v[32:35], 0
	v_mfma_f32_16x16x32_bf16 v[68:71], v[8:11], v[32:35], 0
	v_mfma_f32_16x16x32_bf16 v[72:75], v[0:3], v[40:43], 0
	v_mfma_f32_16x16x32_bf16 v[76:79], v[8:11], v[40:43], 0
	v_mfma_f32_16x16x32_bf16 v[48:51], v[4:7], v[20:23], v[48:51]
	v_mfma_f32_16x16x32_bf16 v[52:55], v[12:15], v[20:23], v[52:55]
	v_mfma_f32_16x16x32_bf16 v[56:59], v[4:7], v[28:31], v[56:59]
	v_mfma_f32_16x16x32_bf16 v[60:63], v[12:15], v[28:31], v[60:63]
	v_mfma_f32_16x16x32_bf16 v[64:67], v[4:7], v[36:39], v[64:67]
	v_mfma_f32_16x16x32_bf16 v[68:71], v[12:15], v[36:39], v[68:71]
	v_mfma_f32_16x16x32_bf16 v[72:75], v[4:7], v[44:47], v[72:75]
	v_mfma_f32_16x16x32_bf16 v[76:79], v[12:15], v[44:47], v[76:79]
	s_setprio 0
	s_barrier
	v_lshl_add_u64 v[206:207], s[40:41], 0, v[178:179]
	s_mov_b32 m0, s37
	v_lshl_add_u64 v[96:97], v[206:207], 0, s[20:21]
	v_lshl_add_u64 v[208:209], s[40:41], 0, v[182:183]
	ds_read_b128 v[80:83], v218
	ds_read_b128 v[84:87], v218 offset:1024
	ds_read_b128 v[88:91], v218 offset:2048
	ds_read_b128 v[92:95], v218 offset:3072
	global_load_lds_dwordx4 v[96:97], off
	v_lshl_add_u64 v[96:97], v[208:209], 0, s[20:21]
	s_mov_b32 m0, s47
	s_nop 0
	global_load_lds_dwordx4 v[96:97], off
	s_barrier
	s_waitcnt lgkmcnt(0)
	s_setprio 1
	s_waitcnt lgkmcnt(0)
	v_mfma_f32_16x16x32_bf16 v[96:99], v[80:83], v[16:19], 0
	v_mfma_f32_16x16x32_bf16 v[16:19], v[88:91], v[16:19], 0
	v_mfma_f32_16x16x32_bf16 v[96:99], v[84:87], v[20:23], v[96:99]
	v_mfma_f32_16x16x32_bf16 v[16:19], v[92:95], v[20:23], v[16:19]
	v_mfma_f32_16x16x32_bf16 v[20:23], v[80:83], v[24:27], 0
	v_mfma_f32_16x16x32_bf16 v[24:27], v[88:91], v[24:27], 0
	v_mfma_f32_16x16x32_bf16 v[20:23], v[84:87], v[28:31], v[20:23]
	v_mfma_f32_16x16x32_bf16 v[24:27], v[92:95], v[28:31], v[24:27]
	v_mfma_f32_16x16x32_bf16 v[28:31], v[80:83], v[32:35], 0
	v_mfma_f32_16x16x32_bf16 v[32:35], v[88:91], v[32:35], 0
	v_mfma_f32_16x16x32_bf16 v[28:31], v[84:87], v[36:39], v[28:31]
	v_mfma_f32_16x16x32_bf16 v[32:35], v[92:95], v[36:39], v[32:35]
	v_mfma_f32_16x16x32_bf16 v[36:39], v[80:83], v[40:43], 0
	v_mfma_f32_16x16x32_bf16 v[40:43], v[88:91], v[40:43], 0
	v_mfma_f32_16x16x32_bf16 v[36:39], v[84:87], v[44:47], v[36:39]
	v_mfma_f32_16x16x32_bf16 v[40:43], v[92:95], v[44:47], v[40:43]
	s_setprio 0
	v_lshl_add_u64 v[210:211], s[38:39], 0, v[176:177]
	s_mov_b32 m0, s48
	v_lshl_add_u64 v[128:129], v[210:211], 0, s[20:21]
	v_lshl_add_u64 v[212:213], s[38:39], 0, v[180:181]
	s_barrier
	ds_read_b128 v[44:47], v217 offset:16384
	ds_read_b128 v[100:103], v217 offset:17408
	ds_read_b128 v[104:107], v217 offset:18432
	ds_read_b128 v[108:111], v217 offset:19456
	ds_read_b128 v[112:115], v217 offset:20480
	ds_read_b128 v[116:119], v217 offset:21504
	ds_read_b128 v[120:123], v217 offset:22528
	ds_read_b128 v[124:127], v217 offset:23552
	global_load_lds_dwordx4 v[128:129], off
	v_lshl_add_u64 v[128:129], v[212:213], 0, s[20:21]
	s_mov_b32 m0, s49
	s_nop 0
	global_load_lds_dwordx4 v[128:129], off
	s_barrier
	s_waitcnt lgkmcnt(0)
	s_setprio 1
	s_waitcnt lgkmcnt(0)
	v_mfma_f32_16x16x32_bf16 v[128:131], v[0:3], v[44:47], 0
	v_mfma_f32_16x16x32_bf16 v[136:139], v[0:3], v[104:107], 0
	v_mfma_f32_16x16x32_bf16 v[144:147], v[0:3], v[112:115], 0
	v_mfma_f32_16x16x32_bf16 v[0:3], v[0:3], v[120:123], 0
	v_mfma_f32_16x16x32_bf16 v[128:131], v[4:7], v[100:103], v[128:131]
	v_mfma_f32_16x16x32_bf16 v[132:135], v[8:11], v[44:47], 0
	v_mfma_f32_16x16x32_bf16 v[136:139], v[4:7], v[108:111], v[136:139]
	v_mfma_f32_16x16x32_bf16 v[140:143], v[8:11], v[104:107], 0
	v_mfma_f32_16x16x32_bf16 v[144:147], v[4:7], v[116:119], v[144:147]
	v_mfma_f32_16x16x32_bf16 v[0:3], v[4:7], v[124:127], v[0:3]
	v_mfma_f32_16x16x32_bf16 v[4:7], v[8:11], v[120:123], 0
	v_mfma_f32_16x16x32_bf16 v[132:135], v[12:15], v[100:103], v[132:135]
	v_mfma_f32_16x16x32_bf16 v[140:143], v[12:15], v[108:111], v[140:143]
	v_mfma_f32_16x16x32_bf16 v[148:151], v[8:11], v[112:115], 0
	v_mfma_f32_16x16x32_bf16 v[4:7], v[12:15], v[124:127], v[4:7]
	v_mfma_f32_16x16x32_bf16 v[148:151], v[12:15], v[116:119], v[148:151]
	s_setprio 0
	s_barrier
	s_add_u32 s64, s40, 0x10100
	s_addc_u32 s65, s41, 0
	s_mov_b32 m0, s50
	v_lshl_add_u64 v[8:9], s[64:65], 0, v[178:179]
	global_load_lds_dwordx4 v[8:9], off
	v_lshl_add_u64 v[8:9], s[64:65], 0, v[182:183]
	s_mov_b32 m0, s51
	s_nop 0
	global_load_lds_dwordx4 v[8:9], off
	s_waitcnt vmcnt(6)
	s_barrier
	s_setprio 1
	v_mfma_f32_16x16x32_bf16 v[8:11], v[80:83], v[44:47], 0
	v_mfma_f32_16x16x32_bf16 v[12:15], v[88:91], v[44:47], 0
	v_mfma_f32_16x16x32_bf16 v[8:11], v[84:87], v[100:103], v[8:11]
	v_mfma_f32_16x16x32_bf16 v[12:15], v[92:95], v[100:103], v[12:15]
	v_mfma_f32_16x16x32_bf16 v[44:47], v[80:83], v[104:107], 0
	v_mfma_f32_16x16x32_bf16 v[100:103], v[88:91], v[104:107], 0
	v_mfma_f32_16x16x32_bf16 v[104:107], v[80:83], v[112:115], 0
	v_mfma_f32_16x16x32_bf16 v[80:83], v[80:83], v[120:123], 0
	v_mfma_f32_16x16x32_bf16 v[44:47], v[84:87], v[108:111], v[44:47]
	v_mfma_f32_16x16x32_bf16 v[100:103], v[92:95], v[108:111], v[100:103]
	v_mfma_f32_16x16x32_bf16 v[104:107], v[84:87], v[116:119], v[104:107]
	v_mfma_f32_16x16x32_bf16 v[108:111], v[88:91], v[112:115], 0
	v_mfma_f32_16x16x32_bf16 v[80:83], v[84:87], v[124:127], v[80:83]
	v_mfma_f32_16x16x32_bf16 v[84:87], v[88:91], v[120:123], 0
	v_mfma_f32_16x16x32_bf16 v[108:111], v[92:95], v[116:119], v[108:111]
	v_mfma_f32_16x16x32_bf16 v[84:87], v[92:95], v[124:127], v[84:87]
	s_setprio 0
	s_barrier
	ds_read_b128 v[88:91], v219
	ds_read_b128 v[92:95], v219 offset:1024
	ds_read_b128 v[112:115], v219 offset:2048
	ds_read_b128 v[116:119], v219 offset:3072
	s_add_u32 s64, s38, 0x10100
	s_addc_u32 s65, s39, 0
	s_mov_b32 m0, s52
	v_lshl_add_u64 v[190:191], s[64:65], 0, v[176:177]
	ds_read_b128 v[120:123], v217 offset:32768
	ds_read_b128 v[124:127], v217 offset:33792
	ds_read_b128 v[152:155], v217 offset:34816
	ds_read_b128 v[156:159], v217 offset:35840
	ds_read_b128 v[160:163], v217 offset:36864
	ds_read_b128 v[164:167], v217 offset:37888
	ds_read_b128 v[168:171], v217 offset:38912
	ds_read_b128 v[172:175], v217 offset:39936
	global_load_lds_dwordx4 v[190:191], off
	v_lshl_add_u64 v[190:191], s[64:65], 0, v[180:181]
	s_mov_b32 m0, s53
	s_nop 0
	global_load_lds_dwordx4 v[190:191], off
	s_waitcnt lgkmcnt(8)
	s_barrier
	s_waitcnt lgkmcnt(0)
	s_setprio 1
	s_waitcnt lgkmcnt(0)
	v_mfma_f32_16x16x32_bf16 v[48:51], v[88:91], v[120:123], v[48:51]
	v_mfma_f32_16x16x32_bf16 v[52:55], v[112:115], v[120:123], v[52:55]
	v_mfma_f32_16x16x32_bf16 v[56:59], v[88:91], v[152:155], v[56:59]
	v_mfma_f32_16x16x32_bf16 v[60:63], v[112:115], v[152:155], v[60:63]
	v_mfma_f32_16x16x32_bf16 v[64:67], v[88:91], v[160:163], v[64:67]
	v_mfma_f32_16x16x32_bf16 v[68:71], v[112:115], v[160:163], v[68:71]
	v_mfma_f32_16x16x32_bf16 v[72:75], v[88:91], v[168:171], v[72:75]
	v_mfma_f32_16x16x32_bf16 v[76:79], v[112:115], v[168:171], v[76:79]
	v_mfma_f32_16x16x32_bf16 v[48:51], v[92:95], v[124:127], v[48:51]
	v_mfma_f32_16x16x32_bf16 v[52:55], v[116:119], v[124:127], v[52:55]
	v_mfma_f32_16x16x32_bf16 v[56:59], v[92:95], v[156:159], v[56:59]
	v_mfma_f32_16x16x32_bf16 v[60:63], v[116:119], v[156:159], v[60:63]
	v_mfma_f32_16x16x32_bf16 v[64:67], v[92:95], v[164:167], v[64:67]
	v_mfma_f32_16x16x32_bf16 v[68:71], v[116:119], v[164:167], v[68:71]
	v_mfma_f32_16x16x32_bf16 v[72:75], v[92:95], v[172:175], v[72:75]
	v_mfma_f32_16x16x32_bf16 v[76:79], v[116:119], v[172:175], v[76:79]
	s_setprio 0
	s_barrier
	s_mov_b32 m0, s56
	v_lshl_add_u64 v[206:207], v[206:207], 0, s[22:23]
	ds_read_b128 v[190:193], v220
	ds_read_b128 v[194:197], v220 offset:1024
	ds_read_b128 v[198:201], v220 offset:2048
	ds_read_b128 v[202:205], v220 offset:3072
	global_load_lds_dwordx4 v[206:207], off
	v_lshl_add_u64 v[206:207], v[208:209], 0, s[22:23]
	s_mov_b32 m0, s57
	s_nop 0
	global_load_lds_dwordx4 v[206:207], off
	s_barrier
	s_waitcnt lgkmcnt(0)
	s_setprio 1
	s_waitcnt lgkmcnt(0)
	v_mfma_f32_16x16x32_bf16 v[96:99], v[190:193], v[120:123], v[96:99]
	v_mfma_f32_16x16x32_bf16 v[16:19], v[198:201], v[120:123], v[16:19]
	v_mfma_f32_16x16x32_bf16 v[20:23], v[190:193], v[152:155], v[20:23]
	v_mfma_f32_16x16x32_bf16 v[24:27], v[198:201], v[152:155], v[24:27]
	v_mfma_f32_16x16x32_bf16 v[28:31], v[190:193], v[160:163], v[28:31]
	v_mfma_f32_16x16x32_bf16 v[32:35], v[198:201], v[160:163], v[32:35]
	v_mfma_f32_16x16x32_bf16 v[36:39], v[190:193], v[168:171], v[36:39]
	v_mfma_f32_16x16x32_bf16 v[40:43], v[198:201], v[168:171], v[40:43]
	v_mfma_f32_16x16x32_bf16 v[96:99], v[194:197], v[124:127], v[96:99]
	v_mfma_f32_16x16x32_bf16 v[16:19], v[202:205], v[124:127], v[16:19]
	v_mfma_f32_16x16x32_bf16 v[20:23], v[194:197], v[156:159], v[20:23]
	v_mfma_f32_16x16x32_bf16 v[24:27], v[202:205], v[156:159], v[24:27]
	v_mfma_f32_16x16x32_bf16 v[28:31], v[194:197], v[164:167], v[28:31]
	v_mfma_f32_16x16x32_bf16 v[32:35], v[202:205], v[164:167], v[32:35]
	v_mfma_f32_16x16x32_bf16 v[36:39], v[194:197], v[172:175], v[36:39]
	v_mfma_f32_16x16x32_bf16 v[40:43], v[202:205], v[172:175], v[40:43]
	s_setprio 0
	s_mov_b32 m0, s58
	v_lshl_add_u64 v[206:207], v[210:211], 0, s[22:23]
	s_barrier
	ds_read_b128 v[120:123], v217 offset:49152
	ds_read_b128 v[124:127], v217 offset:50176
	ds_read_b128 v[152:155], v217 offset:51200
	ds_read_b128 v[156:159], v217 offset:52224
	ds_read_b128 v[160:163], v217 offset:53248
	ds_read_b128 v[164:167], v217 offset:54272
	ds_read_b128 v[168:171], v217 offset:55296
	ds_read_b128 v[172:175], v217 offset:56320
	global_load_lds_dwordx4 v[206:207], off
	v_lshl_add_u64 v[206:207], v[212:213], 0, s[22:23]
	s_mov_b32 m0, s59
	s_nop 0
	global_load_lds_dwordx4 v[206:207], off
	s_barrier
	s_waitcnt lgkmcnt(0)
	s_setprio 1
	s_waitcnt lgkmcnt(0)
	v_mfma_f32_16x16x32_bf16 v[128:131], v[88:91], v[120:123], v[128:131]
	v_mfma_f32_16x16x32_bf16 v[132:135], v[112:115], v[120:123], v[132:135]
	v_mfma_f32_16x16x32_bf16 v[136:139], v[88:91], v[152:155], v[136:139]
	v_mfma_f32_16x16x32_bf16 v[140:143], v[112:115], v[152:155], v[140:143]
	v_mfma_f32_16x16x32_bf16 v[144:147], v[88:91], v[160:163], v[144:147]
	v_mfma_f32_16x16x32_bf16 v[0:3], v[88:91], v[168:171], v[0:3]
	v_mfma_f32_16x16x32_bf16 v[4:7], v[112:115], v[168:171], v[4:7]
	v_mfma_f32_16x16x32_bf16 v[128:131], v[92:95], v[124:127], v[128:131]
	v_mfma_f32_16x16x32_bf16 v[132:135], v[116:119], v[124:127], v[132:135]
	v_mfma_f32_16x16x32_bf16 v[136:139], v[92:95], v[156:159], v[136:139]
	v_mfma_f32_16x16x32_bf16 v[140:143], v[116:119], v[156:159], v[140:143]
	v_mfma_f32_16x16x32_bf16 v[144:147], v[92:95], v[164:167], v[144:147]
	v_mfma_f32_16x16x32_bf16 v[148:151], v[112:115], v[160:163], v[148:151]
	v_mfma_f32_16x16x32_bf16 v[0:3], v[92:95], v[172:175], v[0:3]
	v_mfma_f32_16x16x32_bf16 v[4:7], v[116:119], v[172:175], v[4:7]
	v_mfma_f32_16x16x32_bf16 v[148:151], v[116:119], v[164:167], v[148:151]
	s_setprio 0
	s_barrier
	s_add_u32 s40, s40, 0x10180
	s_addc_u32 s41, s41, 0
	s_mov_b32 m0, s60
	v_lshl_add_u64 v[88:89], s[40:41], 0, v[178:179]
	global_load_lds_dwordx4 v[88:89], off
	v_lshl_add_u64 v[88:89], s[40:41], 0, v[182:183]
	s_mov_b32 m0, s61
	s_nop 0
	global_load_lds_dwordx4 v[88:89], off
	s_waitcnt vmcnt(6)
	s_barrier
	s_setprio 1
	v_mfma_f32_16x16x32_bf16 v[8:11], v[190:193], v[120:123], v[8:11]
	v_mfma_f32_16x16x32_bf16 v[12:15], v[198:201], v[120:123], v[12:15]
	v_mfma_f32_16x16x32_bf16 v[44:47], v[190:193], v[152:155], v[44:47]
	v_mfma_f32_16x16x32_bf16 v[88:91], v[198:201], v[152:155], v[100:103]
	v_mfma_f32_16x16x32_bf16 v[92:95], v[190:193], v[160:163], v[104:107]
	v_mfma_f32_16x16x32_bf16 v[100:103], v[198:201], v[160:163], v[108:111]
	v_mfma_f32_16x16x32_bf16 v[80:83], v[190:193], v[168:171], v[80:83]
	v_mfma_f32_16x16x32_bf16 v[84:87], v[198:201], v[168:171], v[84:87]
	v_mfma_f32_16x16x32_bf16 v[8:11], v[194:197], v[124:127], v[8:11]
	v_mfma_f32_16x16x32_bf16 v[12:15], v[202:205], v[124:127], v[12:15]
	v_mfma_f32_16x16x32_bf16 v[44:47], v[194:197], v[156:159], v[44:47]
	v_mfma_f32_16x16x32_bf16 v[88:91], v[202:205], v[156:159], v[88:91]
	v_mfma_f32_16x16x32_bf16 v[92:95], v[194:197], v[164:167], v[92:95]
	v_mfma_f32_16x16x32_bf16 v[100:103], v[202:205], v[164:167], v[100:103]
	v_mfma_f32_16x16x32_bf16 v[80:83], v[194:197], v[172:175], v[80:83]
	v_mfma_f32_16x16x32_bf16 v[84:87], v[202:205], v[172:175], v[84:87]
	s_setprio 0
	s_barrier
	ds_read_b128 v[104:107], v216
	ds_read_b128 v[108:111], v216 offset:1024
	ds_read_b128 v[112:115], v216 offset:2048
	ds_read_b128 v[116:119], v216 offset:3072
	s_add_u32 s38, s38, 0x10180
	s_addc_u32 s39, s39, 0
	s_mov_b32 m0, s27
	v_lshl_add_u64 v[190:191], s[38:39], 0, v[176:177]
	ds_read_b128 v[120:123], v217
	ds_read_b128 v[124:127], v217 offset:1024
	ds_read_b128 v[152:155], v217 offset:2048
	ds_read_b128 v[156:159], v217 offset:3072
	ds_read_b128 v[160:163], v217 offset:4096
	ds_read_b128 v[164:167], v217 offset:5120
	ds_read_b128 v[168:171], v217 offset:6144
	ds_read_b128 v[172:175], v217 offset:7168
	global_load_lds_dwordx4 v[190:191], off
	v_lshl_add_u64 v[190:191], s[38:39], 0, v[180:181]
	s_mov_b32 m0, s25
	s_nop 0
	global_load_lds_dwordx4 v[190:191], off
	s_waitcnt lgkmcnt(8)
	s_barrier
	s_waitcnt lgkmcnt(0)
	s_setprio 1
	s_waitcnt lgkmcnt(0)
	v_mfma_f32_16x16x32_bf16 v[48:51], v[104:107], v[120:123], v[48:51]
	v_mfma_f32_16x16x32_bf16 v[52:55], v[112:115], v[120:123], v[52:55]
	v_mfma_f32_16x16x32_bf16 v[56:59], v[104:107], v[152:155], v[56:59]
	v_mfma_f32_16x16x32_bf16 v[60:63], v[112:115], v[152:155], v[60:63]
	v_mfma_f32_16x16x32_bf16 v[64:67], v[104:107], v[160:163], v[64:67]
	v_mfma_f32_16x16x32_bf16 v[68:71], v[112:115], v[160:163], v[68:71]
	v_mfma_f32_16x16x32_bf16 v[72:75], v[104:107], v[168:171], v[72:75]
	v_mfma_f32_16x16x32_bf16 v[76:79], v[112:115], v[168:171], v[76:79]
	v_mfma_f32_16x16x32_bf16 v[48:51], v[108:111], v[124:127], v[48:51]
	v_mfma_f32_16x16x32_bf16 v[52:55], v[116:119], v[124:127], v[52:55]
	v_mfma_f32_16x16x32_bf16 v[56:59], v[108:111], v[156:159], v[56:59]
	v_mfma_f32_16x16x32_bf16 v[60:63], v[116:119], v[156:159], v[60:63]
	v_mfma_f32_16x16x32_bf16 v[64:67], v[108:111], v[164:167], v[64:67]
	v_mfma_f32_16x16x32_bf16 v[68:71], v[116:119], v[164:167], v[68:71]
	v_mfma_f32_16x16x32_bf16 v[72:75], v[108:111], v[172:175], v[72:75]
	v_mfma_f32_16x16x32_bf16 v[190:193], v[116:119], v[172:175], v[76:79]
	s_setprio 0
	s_barrier
	s_mov_b32 m0, s37
	v_lshl_add_u64 v[214:215], s[42:43], 0, v[178:179]
	ds_read_b128 v[76:79], v218
	ds_read_b128 v[194:197], v218 offset:1024
	ds_read_b128 v[198:201], v218 offset:2048
	ds_read_b128 v[202:205], v218 offset:3072
	global_load_lds_dwordx4 v[214:215], off
	v_lshl_add_u64 v[186:187], s[42:43], 0, v[182:183]
	s_mov_b32 m0, s47
	s_nop 0
	global_load_lds_dwordx4 v[186:187], off
	s_barrier
	s_waitcnt lgkmcnt(0)
	s_setprio 1
	s_waitcnt lgkmcnt(0)
	v_mfma_f32_16x16x32_bf16 v[96:99], v[76:79], v[120:123], v[96:99]
	v_mfma_f32_16x16x32_bf16 v[16:19], v[198:201], v[120:123], v[16:19]
	v_mfma_f32_16x16x32_bf16 v[20:23], v[76:79], v[152:155], v[20:23]
	v_mfma_f32_16x16x32_bf16 v[24:27], v[198:201], v[152:155], v[24:27]
	v_mfma_f32_16x16x32_bf16 v[28:31], v[76:79], v[160:163], v[28:31]
	v_mfma_f32_16x16x32_bf16 v[32:35], v[198:201], v[160:163], v[32:35]
	v_mfma_f32_16x16x32_bf16 v[36:39], v[76:79], v[168:171], v[36:39]
	v_mfma_f32_16x16x32_bf16 v[40:43], v[198:201], v[168:171], v[40:43]
	v_mfma_f32_16x16x32_bf16 v[96:99], v[194:197], v[124:127], v[96:99]
	v_mfma_f32_16x16x32_bf16 v[16:19], v[202:205], v[124:127], v[16:19]
	v_mfma_f32_16x16x32_bf16 v[20:23], v[194:197], v[156:159], v[20:23]
	v_mfma_f32_16x16x32_bf16 v[24:27], v[202:205], v[156:159], v[24:27]
	v_mfma_f32_16x16x32_bf16 v[28:31], v[194:197], v[164:167], v[28:31]
	v_mfma_f32_16x16x32_bf16 v[32:35], v[202:205], v[164:167], v[32:35]
	v_mfma_f32_16x16x32_bf16 v[36:39], v[194:197], v[172:175], v[36:39]
	v_mfma_f32_16x16x32_bf16 v[40:43], v[202:205], v[172:175], v[40:43]
	s_setprio 0
	s_mov_b32 m0, s48
	v_lshl_add_u64 v[188:189], s[44:45], 0, v[176:177]
	s_barrier
	ds_read_b128 v[120:123], v217 offset:16384
	ds_read_b128 v[124:127], v217 offset:17408
	ds_read_b128 v[152:155], v217 offset:18432
	ds_read_b128 v[156:159], v217 offset:19456
	ds_read_b128 v[160:163], v217 offset:20480
	ds_read_b128 v[164:167], v217 offset:21504
	ds_read_b128 v[168:171], v217 offset:22528
	ds_read_b128 v[172:175], v217 offset:23552
	global_load_lds_dwordx4 v[188:189], off
	v_lshl_add_u64 v[224:225], s[44:45], 0, v[180:181]
	s_mov_b32 m0, s49
	s_nop 0
	global_load_lds_dwordx4 v[224:225], off
	s_barrier
	s_waitcnt lgkmcnt(0)
	s_setprio 1
	s_waitcnt lgkmcnt(0)
	v_mfma_f32_16x16x32_bf16 v[144:147], v[104:107], v[160:163], v[144:147]
	v_mfma_f32_16x16x32_bf16 v[128:131], v[104:107], v[120:123], v[128:131]
	v_mfma_f32_16x16x32_bf16 v[132:135], v[112:115], v[120:123], v[132:135]
	v_mfma_f32_16x16x32_bf16 v[136:139], v[104:107], v[152:155], v[136:139]
	v_mfma_f32_16x16x32_bf16 v[140:143], v[112:115], v[152:155], v[140:143]
	v_mfma_f32_16x16x32_bf16 v[206:209], v[108:111], v[164:167], v[144:147]
	v_mfma_f32_16x16x32_bf16 v[144:147], v[112:115], v[160:163], v[148:151]
	v_mfma_f32_16x16x32_bf16 v[0:3], v[104:107], v[168:171], v[0:3]
	v_mfma_f32_16x16x32_bf16 v[4:7], v[112:115], v[168:171], v[4:7]
	v_mfma_f32_16x16x32_bf16 v[128:131], v[108:111], v[124:127], v[128:131]
	v_mfma_f32_16x16x32_bf16 v[132:135], v[116:119], v[124:127], v[132:135]
	v_mfma_f32_16x16x32_bf16 v[136:139], v[108:111], v[156:159], v[136:139]
	v_mfma_f32_16x16x32_bf16 v[140:143], v[116:119], v[156:159], v[140:143]
	v_mfma_f32_16x16x32_bf16 v[210:213], v[116:119], v[164:167], v[144:147]
	v_mfma_f32_16x16x32_bf16 v[0:3], v[108:111], v[172:175], v[0:3]
	v_mfma_f32_16x16x32_bf16 v[4:7], v[116:119], v[172:175], v[4:7]
	s_setprio 0
	s_barrier
	s_add_u32 s38, s42, 0x10000
	s_addc_u32 s39, s43, 0
	s_mov_b32 m0, s50
	v_lshl_add_u64 v[104:105], s[38:39], 0, v[178:179]
	global_load_lds_dwordx4 v[104:105], off
	v_lshl_add_u64 v[104:105], s[38:39], 0, v[182:183]
	s_mov_b32 m0, s51
	s_nop 0
	global_load_lds_dwordx4 v[104:105], off
	s_waitcnt vmcnt(6)
	s_barrier
	s_setprio 1
	v_mfma_f32_16x16x32_bf16 v[8:11], v[76:79], v[120:123], v[8:11]
	v_mfma_f32_16x16x32_bf16 v[104:107], v[194:197], v[124:127], v[8:11]
	v_mfma_f32_16x16x32_bf16 v[8:11], v[198:201], v[120:123], v[12:15]
	v_mfma_f32_16x16x32_bf16 v[108:111], v[202:205], v[124:127], v[8:11]
	v_mfma_f32_16x16x32_bf16 v[8:11], v[76:79], v[152:155], v[44:47]
	v_mfma_f32_16x16x32_bf16 v[226:229], v[194:197], v[156:159], v[8:11]
	v_mfma_f32_16x16x32_bf16 v[8:11], v[198:201], v[152:155], v[88:91]
	v_mfma_f32_16x16x32_bf16 v[156:159], v[202:205], v[156:159], v[8:11]
	v_mfma_f32_16x16x32_bf16 v[8:11], v[76:79], v[160:163], v[92:95]
	v_mfma_f32_16x16x32_bf16 v[230:233], v[194:197], v[164:167], v[8:11]
	v_mfma_f32_16x16x32_bf16 v[8:11], v[198:201], v[160:163], v[100:103]
	v_mfma_f32_16x16x32_bf16 v[100:103], v[202:205], v[164:167], v[8:11]
	v_mfma_f32_16x16x32_bf16 v[8:11], v[76:79], v[168:171], v[80:83]
	v_mfma_f32_16x16x32_bf16 v[160:163], v[194:197], v[172:175], v[8:11]
	v_mfma_f32_16x16x32_bf16 v[8:11], v[198:201], v[168:171], v[84:87]
	v_mfma_f32_16x16x32_bf16 v[168:171], v[202:205], v[172:175], v[8:11]
	s_setprio 0
	s_barrier
	s_nop 4
	ds_read_b128 v[8:11], v219
	ds_read_b128 v[12:15], v219 offset:1024
	ds_read_b128 v[172:175], v219 offset:2048
	ds_read_b128 v[194:197], v219 offset:3072
	s_add_u32 s38, s44, 0x10000
	s_addc_u32 s39, s45, 0
	s_mov_b32 m0, s52
	v_lshl_add_u64 v[76:77], s[38:39], 0, v[176:177]
	ds_read_b128 v[44:47], v217 offset:32768
	ds_read_b128 v[80:83], v217 offset:33792
	ds_read_b128 v[84:87], v217 offset:34816
	ds_read_b128 v[112:115], v217 offset:35840
	ds_read_b128 v[198:201], v217 offset:36864
	ds_read_b128 v[202:205], v217 offset:37888
	ds_read_b128 v[234:237], v217 offset:38912
	ds_read_b128 v[238:241], v217 offset:39936
	global_load_lds_dwordx4 v[76:77], off
	v_lshl_add_u64 v[76:77], s[38:39], 0, v[180:181]
	s_mov_b32 m0, s53
	s_nop 0
	global_load_lds_dwordx4 v[76:77], off
	s_waitcnt lgkmcnt(8)
	s_barrier
	s_waitcnt lgkmcnt(0)
	s_setprio 1
	s_waitcnt lgkmcnt(0)
	v_mfma_f32_16x16x32_bf16 v[48:51], v[8:11], v[44:47], v[48:51]
	v_mfma_f32_16x16x32_bf16 v[164:167], v[12:15], v[80:83], v[48:51]
	v_mfma_f32_16x16x32_bf16 v[48:51], v[172:175], v[44:47], v[52:55]
	v_mfma_f32_16x16x32_bf16 v[152:155], v[194:197], v[80:83], v[48:51]
	v_mfma_f32_16x16x32_bf16 v[48:51], v[8:11], v[84:87], v[56:59]
	v_mfma_f32_16x16x32_bf16 v[124:127], v[12:15], v[112:115], v[48:51]
	v_mfma_f32_16x16x32_bf16 v[48:51], v[172:175], v[84:87], v[60:63]
	v_mfma_f32_16x16x32_bf16 v[120:123], v[194:197], v[112:115], v[48:51]
	v_mfma_f32_16x16x32_bf16 v[48:51], v[8:11], v[198:201], v[64:67]
	v_mfma_f32_16x16x32_bf16 v[92:95], v[12:15], v[202:205], v[48:51]
	v_mfma_f32_16x16x32_bf16 v[48:51], v[172:175], v[198:201], v[68:71]
	v_mfma_f32_16x16x32_bf16 v[88:91], v[194:197], v[202:205], v[48:51]
	v_mfma_f32_16x16x32_bf16 v[48:51], v[8:11], v[234:237], v[72:75]
	v_mfma_f32_16x16x32_bf16 v[76:79], v[12:15], v[238:241], v[48:51]
	v_mfma_f32_16x16x32_bf16 v[48:51], v[172:175], v[234:237], v[190:193]
	v_mfma_f32_16x16x32_bf16 v[72:75], v[194:197], v[238:241], v[48:51]
	s_setprio 0
	s_barrier
	s_mov_b32 m0, s56
	s_nop 3
	v_lshl_add_u64 v[48:49], v[214:215], 0, s[18:19]
	ds_read_b128 v[190:193], v220
	ds_read_b128 v[242:245], v220 offset:1024
	ds_read_b128 v[246:249], v220 offset:2048
	ds_read_b128 v[250:253], v220 offset:3072
	global_load_lds_dwordx4 v[48:49], off
	v_lshl_add_u64 v[48:49], v[186:187], 0, s[18:19]
	s_mov_b32 m0, s57
	s_nop 0
	global_load_lds_dwordx4 v[48:49], off
	s_barrier
	s_waitcnt lgkmcnt(0)
	s_setprio 1
	s_waitcnt lgkmcnt(0)
	v_mfma_f32_16x16x32_bf16 v[16:19], v[246:249], v[44:47], v[16:19]
	v_mfma_f32_16x16x32_bf16 v[144:147], v[250:253], v[80:83], v[16:19]
	v_mfma_f32_16x16x32_bf16 v[16:19], v[190:193], v[84:87], v[20:23]
	v_mfma_f32_16x16x32_bf16 v[116:119], v[242:245], v[112:115], v[16:19]
	v_mfma_f32_16x16x32_bf16 v[16:19], v[246:249], v[84:87], v[24:27]
	v_mfma_f32_16x16x32_bf16 v[112:115], v[250:253], v[112:115], v[16:19]
	v_mfma_f32_16x16x32_bf16 v[16:19], v[190:193], v[198:201], v[28:31]
	v_mfma_f32_16x16x32_bf16 v[48:51], v[190:193], v[44:47], v[96:99]
	v_mfma_f32_16x16x32_bf16 v[84:87], v[242:245], v[202:205], v[16:19]
	v_mfma_f32_16x16x32_bf16 v[16:19], v[246:249], v[198:201], v[32:35]
	v_mfma_f32_16x16x32_bf16 v[148:151], v[242:245], v[80:83], v[48:51]
	v_mfma_f32_16x16x32_bf16 v[80:83], v[250:253], v[202:205], v[16:19]
	v_mfma_f32_16x16x32_bf16 v[16:19], v[190:193], v[234:237], v[36:39]
	v_mfma_f32_16x16x32_bf16 v[68:71], v[242:245], v[238:241], v[16:19]
	v_mfma_f32_16x16x32_bf16 v[16:19], v[246:249], v[234:237], v[40:43]
	v_mfma_f32_16x16x32_bf16 v[64:67], v[250:253], v[238:241], v[16:19]
	s_setprio 0
	s_mov_b32 m0, s58
	v_lshl_add_u64 v[24:25], v[188:189], 0, s[18:19]
	s_barrier
	s_nop 2
	ds_read_b128 v[16:19], v217 offset:49152
	ds_read_b128 v[20:23], v217 offset:50176
	ds_read_b128 v[32:35], v217 offset:51200
	ds_read_b128 v[96:99], v217 offset:52224
	ds_read_b128 v[198:201], v217 offset:53248
	ds_read_b128 v[202:205], v217 offset:54272
	ds_read_b128 v[234:237], v217 offset:55296
	ds_read_b128 v[238:241], v217 offset:56320
	global_load_lds_dwordx4 v[24:25], off
	v_lshl_add_u64 v[24:25], v[224:225], 0, s[18:19]
	s_mov_b32 m0, s59
	s_nop 0
	global_load_lds_dwordx4 v[24:25], off
	s_barrier
	s_waitcnt lgkmcnt(0)
	s_setprio 1
	s_waitcnt lgkmcnt(0)
	v_mfma_f32_16x16x32_bf16 v[24:27], v[8:11], v[16:19], v[128:131]
	v_mfma_f32_16x16x32_bf16 v[60:63], v[12:15], v[20:23], v[24:27]
	v_mfma_f32_16x16x32_bf16 v[24:27], v[172:175], v[16:19], v[132:135]
	v_mfma_f32_16x16x32_bf16 v[56:59], v[194:197], v[20:23], v[24:27]
	v_mfma_f32_16x16x32_bf16 v[24:27], v[8:11], v[32:35], v[136:139]
	v_mfma_f32_16x16x32_bf16 v[44:47], v[12:15], v[96:99], v[24:27]
	v_mfma_f32_16x16x32_bf16 v[24:27], v[172:175], v[32:35], v[140:143]
	v_mfma_f32_16x16x32_bf16 v[40:43], v[194:197], v[96:99], v[24:27]
	v_mfma_f32_16x16x32_bf16 v[24:27], v[8:11], v[198:201], v[206:209]
	v_mfma_f32_16x16x32_bf16 v[0:3], v[8:11], v[234:237], v[0:3]
	v_mfma_f32_16x16x32_bf16 v[28:31], v[12:15], v[202:205], v[24:27]
	v_mfma_f32_16x16x32_bf16 v[24:27], v[172:175], v[198:201], v[210:213]
	v_mfma_f32_16x16x32_bf16 v[12:15], v[12:15], v[238:241], v[0:3]
	v_mfma_f32_16x16x32_bf16 v[0:3], v[172:175], v[234:237], v[4:7]
	v_mfma_f32_16x16x32_bf16 v[24:27], v[194:197], v[202:205], v[24:27]
	v_mfma_f32_16x16x32_bf16 v[8:11], v[194:197], v[238:241], v[0:3]
	s_setprio 0
	s_barrier
	s_add_u32 s38, s42, 0x10080
	s_addc_u32 s39, s43, 0
	s_mov_b32 m0, s60
	s_nop 0
	v_lshl_add_u64 v[0:1], s[38:39], 0, v[178:179]
	global_load_lds_dwordx4 v[0:1], off
	v_lshl_add_u64 v[0:1], s[38:39], 0, v[182:183]
	s_mov_b32 m0, s61
	s_nop 0
	global_load_lds_dwordx4 v[0:1], off
	s_waitcnt vmcnt(6)
	s_barrier
	s_setprio 1
	v_mfma_f32_16x16x32_bf16 v[0:3], v[190:193], v[16:19], v[104:107]
	v_mfma_f32_16x16x32_bf16 v[52:55], v[242:245], v[20:23], v[0:3]
	v_mfma_f32_16x16x32_bf16 v[0:3], v[246:249], v[16:19], v[108:111]
	v_mfma_f32_16x16x32_bf16 v[48:51], v[250:253], v[20:23], v[0:3]
	v_mfma_f32_16x16x32_bf16 v[0:3], v[190:193], v[32:35], v[226:229]
	v_mfma_f32_16x16x32_bf16 v[36:39], v[242:245], v[96:99], v[0:3]
	v_mfma_f32_16x16x32_bf16 v[0:3], v[246:249], v[32:35], v[156:159]
	v_mfma_f32_16x16x32_bf16 v[32:35], v[250:253], v[96:99], v[0:3]
	v_mfma_f32_16x16x32_bf16 v[0:3], v[190:193], v[198:201], v[230:233]
	v_mfma_f32_16x16x32_bf16 v[20:23], v[242:245], v[202:205], v[0:3]
	v_mfma_f32_16x16x32_bf16 v[0:3], v[246:249], v[198:201], v[100:103]
	v_mfma_f32_16x16x32_bf16 v[16:19], v[250:253], v[202:205], v[0:3]
	v_mfma_f32_16x16x32_bf16 v[0:3], v[190:193], v[234:237], v[160:163]
	v_mfma_f32_16x16x32_bf16 v[4:7], v[242:245], v[238:241], v[0:3]
	v_mfma_f32_16x16x32_bf16 v[0:3], v[246:249], v[234:237], v[168:171]
	v_mfma_f32_16x16x32_bf16 v[0:3], v[250:253], v[238:241], v[0:3]
	s_setprio 0
	v_mov_b32_e32 v96, v185
	s_barrier
	s_lshl_b32 s25, s36, 8
	v_mbcnt_lo_u32_b32 v96, -1, v96
	v_mbcnt_hi_u32_b32 v188, -1, v96
	s_add_i32 s25, s25, s54
	v_and_or_b32 v196, v188, 15, s25
	s_lshl_b32 s25, s34, 8
	v_ashrrev_i32_e32 v96, 1, v188
	v_and_b32_e32 v96, -8, v96
	s_or_b32 s25, s25, s55
	v_add_u32_e32 v190, s25, v96
	v_ashrrev_i32_e32 v197, 31, v196
	v_ashrrev_i32_e32 v191, 31, v190
	v_lshlrev_b64 v[186:187], 11, v[196:197]
	v_lshl_add_u64 v[96:97], s[4:5], 0, v[186:187]
	v_lshlrev_b64 v[194:195], 1, v[190:191]
	v_lshl_add_u64 v[96:97], v[96:97], 0, v[194:195]
	v_add_u32_e32 v192, 0x80, v190
	v_lshrrev_b32_e32 v98, 8, v190
	global_load_dwordx4 v[228:231], v[96:97], off
	global_load_dwordx4 v[232:235], v[96:97], off offset:256
	v_lshrrev_b32_e32 v96, 8, v192
	v_mul_hi_i32_i24_e32 v199, 0x4080, v98
	v_mul_i32_i24_e32 v198, 0x4080, v98
	v_mul_hi_i32_i24_e32 v201, 0x4080, v96
	v_mul_i32_i24_e32 v200, 0x4080, v96
	v_lshl_add_u64 v[98:99], v[198:199], 0, v[196:197]
	v_and_b32_e32 v100, 0xf8, v190
	v_lshl_add_u64 v[96:97], v[200:201], 0, v[196:197]
	v_lshlrev_b64 v[98:99], 9, v[98:99]
	v_lshlrev_b32_e32 v184, 1, v100
	v_and_b32_e32 v100, 0xf8, v192
	v_lshlrev_b64 v[96:97], 9, v[96:97]
	v_or_b32_e32 v212, 16, v196
	v_lshl_add_u64 v[98:99], s[12:13], 0, v[98:99]
	v_lshl_add_u64 v[96:97], s[12:13], 0, v[96:97]
	v_lshlrev_b32_e32 v202, 1, v100
	v_mov_b32_e32 v203, v185
	v_mbcnt_lo_u32_b32 v100, -1, 0
	v_mbcnt_hi_u32_b32 v100, -1, v100
	v_bfe_u32 v184, v190, 4, 4
	v_and_b32_e32 v202, 15, v100
	v_sub_u32_e32 v184, v184, v202
	v_lshlrev_b32_e32 v184, 9, v184
	v_lshl_add_u32 v184, v202, 4, v184
	v_bfe_u32 v202, v100, 4, 1
	v_lshl_add_u32 v184, v202, 8, v184
	v_ashrrev_i32_e32 v185, 31, v184
	v_add_u32_e32 v202, 0x1000, v184
	v_ashrrev_i32_e32 v203, 31, v202
	v_ashrrev_i32_e32 v213, 31, v212
	v_lshl_add_u64 v[98:99], v[98:99], 0, v[184:185]
	v_lshl_add_u64 v[96:97], v[96:97], 0, v[202:203]
	v_lshlrev_b64 v[214:215], 11, v[212:213]
	global_load_dwordx4 v[236:239], v[98:99], off
	global_load_dwordx4 v[240:243], v[96:97], off
	v_lshl_add_u64 v[96:97], s[4:5], 0, v[214:215]
	v_lshl_add_u64 v[96:97], v[96:97], 0, v[194:195]
	v_lshl_add_u64 v[98:99], v[198:199], 0, v[212:213]
	global_load_dwordx4 v[168:171], v[96:97], off
	global_load_dwordx4 v[156:159], v[96:97], off offset:256
	v_lshl_add_u64 v[96:97], v[200:201], 0, v[212:213]
	v_lshlrev_b64 v[98:99], 9, v[98:99]
	v_lshlrev_b64 v[96:97], 9, v[96:97]
	v_or_b32_e32 v208, 32, v196
	v_lshl_add_u64 v[98:99], s[12:13], 0, v[98:99]
	v_lshl_add_u64 v[96:97], s[12:13], 0, v[96:97]
	v_ashrrev_i32_e32 v209, 31, v208
	v_lshl_add_u64 v[98:99], v[98:99], 0, v[184:185]
	v_lshl_add_u64 v[96:97], v[96:97], 0, v[202:203]
	v_lshlrev_b64 v[210:211], 11, v[208:209]
	global_load_dwordx4 v[172:175], v[98:99], off
	global_load_dwordx4 v[160:163], v[96:97], off
	v_lshl_add_u64 v[96:97], s[4:5], 0, v[210:211]
	v_lshl_add_u64 v[96:97], v[96:97], 0, v[194:195]
	v_lshl_add_u64 v[98:99], v[198:199], 0, v[208:209]
	v_lshlrev_b64 v[98:99], 9, v[98:99]
	global_load_dwordx4 v[136:139], v[96:97], off
	global_load_dwordx4 v[128:131], v[96:97], off offset:256
	v_lshl_add_u64 v[96:97], v[200:201], 0, v[208:209]
	v_lshl_add_u64 v[98:99], s[12:13], 0, v[98:99]
	v_lshlrev_b64 v[96:97], 9, v[96:97]
	v_or_b32_e32 v204, 48, v196
	v_lshl_add_u64 v[98:99], v[98:99], 0, v[184:185]
	v_lshl_add_u64 v[96:97], s[12:13], 0, v[96:97]
	v_ashrrev_i32_e32 v205, 31, v204
	v_lshl_add_u64 v[96:97], v[96:97], 0, v[202:203]
	global_load_dwordx4 v[140:143], v[98:99], off
	global_load_dwordx4 v[132:135], v[96:97], off
	v_lshl_add_u64 v[98:99], v[198:199], 0, v[204:205]
	v_lshl_add_u64 v[102:103], v[200:201], 0, v[204:205]
	v_lshlrev_b64 v[206:207], 11, v[204:205]
	v_lshlrev_b64 v[98:99], 9, v[98:99]
	v_lshlrev_b64 v[102:103], 9, v[102:103]
	v_lshl_add_u64 v[96:97], s[4:5], 0, v[206:207]
	v_lshl_add_u64 v[98:99], s[12:13], 0, v[98:99]
	v_lshl_add_u64 v[102:103], s[12:13], 0, v[102:103]
	v_lshl_add_u64 v[96:97], v[96:97], 0, v[194:195]
	v_lshl_add_u64 v[100:101], v[98:99], 0, v[184:185]
	v_lshl_add_u64 v[102:103], v[102:103], 0, v[202:203]
	global_load_dwordx4 v[104:107], v[96:97], off
	s_nop 0
	global_load_dwordx4 v[96:99], v[96:97], off offset:256
	s_nop 0
	global_load_dwordx4 v[108:111], v[100:101], off
	s_nop 0
	global_load_dwordx4 v[100:103], v[102:103], off
	v_xor_b32_e32 v189, 16, v221
	v_cmp_lt_i32_e32 vcc, v189, v223
	v_ashrrev_i32_e32 v193, 31, v192
	s_nop 0
	v_cndmask_b32_e32 v189, v221, v189, vcc
	v_cmp_lt_i32_e32 vcc, v222, v223
	v_lshlrev_b32_e32 v226, 2, v189
	s_nop 0
	v_cndmask_b32_e32 v189, v221, v222, vcc
	v_lshlrev_b32_e32 v225, 2, v189
	v_cmp_gt_u32_e32 vcc, 16, v188
	s_waitcnt vmcnt(0)
	v_lshlrev_b32_e32 v188, 16, v228
	v_and_b32_e32 v189, 0xffff0000, v228
	v_lshlrev_b32_e32 v244, 16, v236
	v_and_b32_e32 v245, 0xffff0000, v236
	v_pk_fma_f32 v[164:165], v[164:165], v[244:245], v[188:189]
	v_lshlrev_b32_e32 v228, 16, v229
	v_and_b32_e32 v229, 0xffff0000, v229
	v_lshlrev_b32_e32 v236, 16, v237
	v_and_b32_e32 v237, 0xffff0000, v237
	v_pk_mul_f32 v[188:189], v[164:165], v[164:165]
	v_pk_fma_f32 v[166:167], v[166:167], v[236:237], v[228:229]
	v_lshlrev_b32_e32 v236, 16, v230
	v_pk_mul_f32 v[228:229], v[166:167], v[166:167]
	v_and_b32_e32 v237, 0xffff0000, v230
	v_lshlrev_b32_e32 v244, 16, v238
	v_and_b32_e32 v245, 0xffff0000, v238
	v_add_f32_e32 v188, v188, v189
	v_pk_fma_f32 v[236:237], v[152:153], v[244:245], v[236:237]
	v_add_f32_e32 v188, v228, v188
	v_pk_mul_f32 v[244:245], v[236:237], v[236:237]
	v_lshlrev_b32_e32 v152, 16, v231
	v_and_b32_e32 v153, 0xffff0000, v231
	v_lshlrev_b32_e32 v230, 16, v239
	v_and_b32_e32 v231, 0xffff0000, v239
	v_add_f32_e32 v188, v229, v188
	v_pk_fma_f32 v[230:231], v[154:155], v[230:231], v[152:153]
	v_add_f32_e32 v188, v244, v188
	v_pk_mul_f32 v[238:239], v[230:231], v[230:231]
	v_cvt_pk_bf16_f32 v152, v164, v165
	v_cvt_pk_bf16_f32 v153, v166, v167
	v_lshl_add_u64 v[164:165], s[8:9], 0, v[186:187]
	v_lshlrev_b32_e32 v166, 16, v232
	v_and_b32_e32 v167, 0xffff0000, v232
	v_lshlrev_b32_e32 v186, 16, v240
	v_and_b32_e32 v187, 0xffff0000, v240
	v_add_f32_e32 v188, v245, v188
	v_pk_fma_f32 v[148:149], v[148:149], v[186:187], v[166:167]
	v_add_f32_e32 v188, v238, v188
	v_cvt_pk_bf16_f32 v155, v230, v231
	v_pk_mul_f32 v[166:167], v[148:149], v[148:149]
	v_lshlrev_b32_e32 v186, 16, v233
	v_and_b32_e32 v187, 0xffff0000, v233
	v_lshlrev_b32_e32 v230, 16, v241
	v_and_b32_e32 v231, 0xffff0000, v241
	v_add_f32_e32 v188, v239, v188
	v_pk_fma_f32 v[150:151], v[150:151], v[230:231], v[186:187]
	v_add_f32_e32 v166, v166, v188
	v_pk_mul_f32 v[186:187], v[150:151], v[150:151]
	v_lshlrev_b32_e32 v230, 16, v234
	v_and_b32_e32 v231, 0xffff0000, v234
	v_lshlrev_b32_e32 v232, 16, v242
	v_and_b32_e32 v233, 0xffff0000, v242
	v_add_f32_e32 v166, v167, v166
	v_pk_fma_f32 v[230:231], v[144:145], v[232:233], v[230:231]
	v_add_f32_e32 v166, v186, v166
	v_pk_mul_f32 v[144:145], v[230:231], v[230:231]
	v_lshlrev_b32_e32 v232, 16, v235
	v_and_b32_e32 v233, 0xffff0000, v235
	v_lshlrev_b32_e32 v234, 16, v243
	v_and_b32_e32 v235, 0xffff0000, v243
	v_add_f32_e32 v166, v187, v166
	v_pk_fma_f32 v[232:233], v[146:147], v[234:235], v[232:233]
	v_add_f32_e32 v144, v144, v166
	v_pk_mul_f32 v[146:147], v[232:233], v[232:233]
	v_add_f32_e32 v144, v145, v144
	v_add_f32_e32 v144, v146, v144
	v_add_f32_e32 v166, v147, v144
	ds_bpermute_b32 v167, v226, v166
	v_cvt_pk_bf16_f32 v154, v236, v237
	v_lshl_add_u64 v[144:145], v[164:165], 0, v[194:195]
	global_store_dwordx4 v[144:145], v[152:155], off
	v_cvt_pk_bf16_f32 v146, v148, v149
	s_waitcnt lgkmcnt(0)
	v_add_f32_e32 v144, v166, v167
	ds_bpermute_b32 v145, v225, v144
	v_cvt_pk_bf16_f32 v147, v150, v151
	v_cvt_pk_bf16_f32 v148, v230, v231
	v_cvt_pk_bf16_f32 v149, v232, v233
	v_lshl_add_u64 v[150:151], v[192:193], 1, v[164:165]
	global_store_dwordx4 v[150:151], v[146:149], off
	s_and_saveexec_b64 s[34:35], vcc
	s_cbranch_execz .LBB0_704
	v_lshl_add_u64 v[146:147], v[196:197], 2, s[10:11]
	s_waitcnt lgkmcnt(0)
	v_add_f32_e32 v144, v144, v145
	global_atomic_add_f32 v[146:147], v144, off

.LBB0_710:
	s_or_b64 exec, exec, s[34:35]
	v_add_u32_e32 v124, 0x80, v196
	v_ashrrev_i32_e32 v125, 31, v124
	v_lshlrev_b64 v[142:143], 11, v[124:125]
	s_waitcnt lgkmcnt(0)
	v_lshl_add_u64 v[64:65], s[4:5], 0, v[142:143]
	v_lshl_add_u64 v[64:65], v[64:65], 0, v[194:195]
	v_lshl_add_u64 v[66:67], v[198:199], 0, v[124:125]
	global_load_dwordx4 v[126:129], v[64:65], off
	global_load_dwordx4 v[130:133], v[64:65], off offset:256
	v_lshl_add_u64 v[64:65], v[200:201], 0, v[124:125]
	v_lshlrev_b64 v[66:67], 9, v[66:67]
	v_lshlrev_b64 v[64:65], 9, v[64:65]
	v_add_u32_e32 v120, 0x90, v196
	v_lshl_add_u64 v[66:67], s[12:13], 0, v[66:67]
	v_lshl_add_u64 v[64:65], s[12:13], 0, v[64:65]
	v_ashrrev_i32_e32 v203, 31, v202
	v_ashrrev_i32_e32 v121, 31, v120
	v_lshl_add_u64 v[66:67], v[66:67], 0, v[184:185]
	v_lshl_add_u64 v[64:65], v[64:65], 0, v[202:203]
	v_lshlrev_b64 v[122:123], 11, v[120:121]
	global_load_dwordx4 v[134:137], v[66:67], off
	global_load_dwordx4 v[138:141], v[64:65], off
	v_lshl_add_u64 v[64:65], s[4:5], 0, v[122:123]
	v_lshl_add_u64 v[64:65], v[64:65], 0, v[194:195]
	v_lshl_add_u64 v[66:67], v[198:199], 0, v[120:121]
	global_load_dwordx4 v[104:107], v[64:65], off
	global_load_dwordx4 v[96:99], v[64:65], off offset:256
	v_lshl_add_u64 v[64:65], v[200:201], 0, v[120:121]
	v_lshlrev_b64 v[66:67], 9, v[66:67]
	v_lshlrev_b64 v[64:65], 9, v[64:65]
	v_add_u32_e32 v116, 0xa0, v196
	v_lshl_add_u64 v[66:67], s[12:13], 0, v[66:67]
	v_lshl_add_u64 v[64:65], s[12:13], 0, v[64:65]
	v_ashrrev_i32_e32 v117, 31, v116
	v_lshl_add_u64 v[66:67], v[66:67], 0, v[184:185]
	v_lshl_add_u64 v[64:65], v[64:65], 0, v[202:203]
	v_lshlrev_b64 v[118:119], 11, v[116:117]
	global_load_dwordx4 v[108:111], v[66:67], off
	global_load_dwordx4 v[100:103], v[64:65], off
	v_lshl_add_u64 v[64:65], s[4:5], 0, v[118:119]
	v_lshl_add_u64 v[64:65], v[64:65], 0, v[194:195]
	v_lshl_add_u64 v[66:67], v[198:199], 0, v[116:117]
	v_lshlrev_b64 v[66:67], 9, v[66:67]
	global_load_dwordx4 v[88:91], v[64:65], off
	global_load_dwordx4 v[80:83], v[64:65], off offset:256
	v_lshl_add_u64 v[64:65], v[200:201], 0, v[116:117]
	v_lshl_add_u64 v[66:67], s[12:13], 0, v[66:67]
	v_lshlrev_b64 v[64:65], 9, v[64:65]
	v_add_u32_e32 v112, 0xb0, v196
	v_lshl_add_u64 v[66:67], v[66:67], 0, v[184:185]
	v_lshl_add_u64 v[64:65], s[12:13], 0, v[64:65]
	v_ashrrev_i32_e32 v113, 31, v112
	v_lshl_add_u64 v[64:65], v[64:65], 0, v[202:203]
	global_load_dwordx4 v[92:95], v[66:67], off
	global_load_dwordx4 v[84:87], v[64:65], off
	v_lshl_add_u64 v[66:67], v[198:199], 0, v[112:113]
	v_lshl_add_u64 v[70:71], v[200:201], 0, v[112:113]
	v_lshlrev_b64 v[114:115], 11, v[112:113]
	v_lshlrev_b64 v[66:67], 9, v[66:67]
	v_lshlrev_b64 v[70:71], 9, v[70:71]
	v_lshl_add_u64 v[64:65], s[4:5], 0, v[114:115]
	v_lshl_add_u64 v[66:67], s[12:13], 0, v[66:67]
	v_lshl_add_u64 v[70:71], s[12:13], 0, v[70:71]
	v_lshl_add_u64 v[64:65], v[64:65], 0, v[194:195]
	v_lshl_add_u64 v[68:69], v[66:67], 0, v[184:185]
	v_lshl_add_u64 v[70:71], v[70:71], 0, v[202:203]
	global_load_dwordx4 v[72:75], v[64:65], off
	s_nop 0
	global_load_dwordx4 v[64:67], v[64:65], off offset:256
	s_nop 0
	global_load_dwordx4 v[76:79], v[68:69], off
	s_nop 0
	global_load_dwordx4 v[68:71], v[70:71], off
	s_waitcnt vmcnt(15)
	v_lshlrev_b32_e32 v144, 16, v126
	v_and_b32_e32 v145, 0xffff0000, v126
	s_waitcnt vmcnt(13)
	v_lshlrev_b32_e32 v146, 16, v134
	v_and_b32_e32 v147, 0xffff0000, v134
	v_lshlrev_b32_e32 v126, 16, v127
	v_and_b32_e32 v127, 0xffff0000, v127
	v_lshlrev_b32_e32 v134, 16, v135
	v_and_b32_e32 v135, 0xffff0000, v135
	v_pk_fma_f32 v[60:61], v[60:61], v[146:147], v[144:145]
	v_pk_fma_f32 v[62:63], v[62:63], v[134:135], v[126:127]
	v_lshlrev_b32_e32 v134, 16, v128
	v_and_b32_e32 v135, 0xffff0000, v128
	v_lshlrev_b32_e32 v146, 16, v136
	v_and_b32_e32 v147, 0xffff0000, v136
	v_pk_fma_f32 v[134:135], v[56:57], v[146:147], v[134:135]
	v_lshlrev_b32_e32 v56, 16, v129
	v_and_b32_e32 v57, 0xffff0000, v129
	v_lshlrev_b32_e32 v128, 16, v137
	v_and_b32_e32 v129, 0xffff0000, v137
	v_pk_fma_f32 v[128:129], v[58:59], v[128:129], v[56:57]
	v_pk_mul_f32 v[126:127], v[62:63], v[62:63]
	v_pk_mul_f32 v[136:137], v[128:129], v[128:129]
	v_cvt_pk_bf16_f32 v57, v62, v63
	v_cvt_pk_bf16_f32 v59, v128, v129
	v_lshlrev_b32_e32 v62, 16, v130
	v_and_b32_e32 v63, 0xffff0000, v130
	s_waitcnt vmcnt(12)
	v_lshlrev_b32_e32 v128, 16, v138
	v_and_b32_e32 v129, 0xffff0000, v138
	v_pk_fma_f32 v[52:53], v[52:53], v[128:129], v[62:63]
	v_lshlrev_b32_e32 v128, 16, v131
	v_and_b32_e32 v129, 0xffff0000, v131
	v_lshlrev_b32_e32 v130, 16, v139
	v_and_b32_e32 v131, 0xffff0000, v139
	v_pk_mul_f32 v[146:147], v[134:135], v[134:135]
	v_cvt_pk_bf16_f32 v58, v134, v135
	v_pk_fma_f32 v[54:55], v[54:55], v[130:131], v[128:129]
	v_lshlrev_b32_e32 v130, 16, v132
	v_and_b32_e32 v131, 0xffff0000, v132
	v_lshlrev_b32_e32 v134, 16, v140
	v_and_b32_e32 v135, 0xffff0000, v140
	v_pk_mul_f32 v[144:145], v[60:61], v[60:61]
	v_pk_fma_f32 v[130:131], v[48:49], v[134:135], v[130:131]
	v_lshlrev_b32_e32 v132, 16, v133
	v_and_b32_e32 v133, 0xffff0000, v133
	v_lshlrev_b32_e32 v134, 16, v141
	v_and_b32_e32 v135, 0xffff0000, v141
	v_pk_fma_f32 v[132:133], v[50:51], v[134:135], v[132:133]
	v_add_f32_e32 v134, v144, v145
	v_add_f32_e32 v126, v126, v134
	v_add_f32_e32 v126, v127, v126
	v_add_f32_e32 v126, v146, v126
	v_add_f32_e32 v126, v147, v126
	v_add_f32_e32 v126, v136, v126
	v_pk_mul_f32 v[62:63], v[52:53], v[52:53]
	v_add_f32_e32 v126, v137, v126
	v_add_f32_e32 v62, v62, v126
	v_pk_mul_f32 v[128:129], v[54:55], v[54:55]
	v_add_f32_e32 v62, v63, v62
	v_add_f32_e32 v62, v128, v62
	v_pk_mul_f32 v[48:49], v[130:131], v[130:131]
	v_add_f32_e32 v62, v129, v62
	v_add_f32_e32 v48, v48, v62
	v_pk_mul_f32 v[50:51], v[132:133], v[132:133]
	v_add_f32_e32 v48, v49, v48
	v_add_f32_e32 v48, v50, v48
	v_add_f32_e32 v62, v51, v48
	ds_bpermute_b32 v63, v226, v62
	v_cvt_pk_bf16_f32 v56, v60, v61
	v_lshl_add_u64 v[60:61], s[8:9], 0, v[142:143]
	v_lshl_add_u64 v[48:49], v[60:61], 0, v[194:195]
	global_store_dwordx4 v[48:49], v[56:59], off
	s_waitcnt lgkmcnt(0)
	v_add_f32_e32 v48, v62, v63
	ds_bpermute_b32 v49, v225, v48
	v_cvt_pk_bf16_f32 v50, v52, v53
	v_cvt_pk_bf16_f32 v51, v54, v55
	v_cvt_pk_bf16_f32 v52, v130, v131
	v_cvt_pk_bf16_f32 v53, v132, v133
	v_lshl_add_u64 v[54:55], v[192:193], 1, v[60:61]
	global_store_dwordx4 v[54:55], v[50:53], off
	s_and_saveexec_b64 s[34:35], vcc
	s_cbranch_execz .LBB0_712
	v_lshl_add_u64 v[50:51], v[124:125], 2, s[10:11]
	s_waitcnt lgkmcnt(0)
	v_add_f32_e32 v48, v48, v49
	global_atomic_add_f32 v[50:51], v48, off

.LBB0_2272:
	ds_read_b128 v[154:157], v149
	ds_read_b128 v[158:161], v149 offset:1024
	ds_read_b128 v[162:165], v149 offset:2048
	ds_read_b128 v[166:169], v149 offset:3072
	s_add_u32 s26, s24, 0xfffc0080
	s_addc_u32 s27, s25, -1
	s_cmp_eq_u32 s59, 12
	s_cselect_b32 s29, s17, s27
	s_cselect_b32 s28, s55, s26
	s_cselect_b32 s27, s15, s58
	s_cselect_b32 s26, s56, s57
	v_lshl_add_u64 v[146:147], s[24:25], 0, v[138:139]
	s_add_i32 m0, s37, 0xc000
	ds_read_b128 v[170:173], v150
	ds_read_b128 v[174:177], v150 offset:1024
	ds_read_b128 v[178:181], v150 offset:2048
	ds_read_b128 v[182:185], v150 offset:3072
	ds_read_b128 v[186:189], v150 offset:4096
	ds_read_b128 v[190:193], v150 offset:5120
	ds_read_b128 v[194:197], v150 offset:6144
	ds_read_b128 v[198:201], v150 offset:7168
	global_load_lds_dwordx4 v[146:147], off
	v_lshl_add_u64 v[146:147], s[24:25], 0, v[140:141]
	s_add_i32 m0, s37, 0xe000
	s_nop 0
	global_load_lds_dwordx4 v[146:147], off
	s_waitcnt lgkmcnt(8)
	s_barrier
	s_waitcnt lgkmcnt(0)
	s_setprio 1
	s_waitcnt lgkmcnt(0)
	v_mfma_f32_16x16x32_bf16 v[124:127], v[154:157], v[170:173], v[124:127]
	v_mfma_f32_16x16x32_bf16 v[120:123], v[162:165], v[170:173], v[120:123]
	v_mfma_f32_16x16x32_bf16 v[108:111], v[154:157], v[178:181], v[108:111]
	v_mfma_f32_16x16x32_bf16 v[104:107], v[162:165], v[178:181], v[104:107]
	v_mfma_f32_16x16x32_bf16 v[92:95], v[154:157], v[186:189], v[92:95]
	v_mfma_f32_16x16x32_bf16 v[88:91], v[162:165], v[186:189], v[88:91]
	v_mfma_f32_16x16x32_bf16 v[76:79], v[154:157], v[194:197], v[76:79]
	v_mfma_f32_16x16x32_bf16 v[72:75], v[162:165], v[194:197], v[72:75]
	v_mfma_f32_16x16x32_bf16 v[124:127], v[158:161], v[174:177], v[124:127]
	v_mfma_f32_16x16x32_bf16 v[120:123], v[166:169], v[174:177], v[120:123]
	v_mfma_f32_16x16x32_bf16 v[108:111], v[158:161], v[182:185], v[108:111]
	v_mfma_f32_16x16x32_bf16 v[104:107], v[166:169], v[182:185], v[104:107]
	v_mfma_f32_16x16x32_bf16 v[92:95], v[158:161], v[190:193], v[92:95]
	v_mfma_f32_16x16x32_bf16 v[88:91], v[166:169], v[190:193], v[88:91]
	v_mfma_f32_16x16x32_bf16 v[76:79], v[158:161], v[198:201], v[76:79]
	v_mfma_f32_16x16x32_bf16 v[72:75], v[166:169], v[198:201], v[72:75]
	s_setprio 0
	s_barrier
	s_mov_b32 m0, s23
	v_lshl_add_u64 v[146:147], s[26:27], 0, v[130:131]
	ds_read_b128 v[202:205], v151
	ds_read_b128 v[206:209], v151 offset:1024
	ds_read_b128 v[210:213], v151 offset:2048
	ds_read_b128 v[214:217], v151 offset:3072
	global_load_lds_dwordx4 v[146:147], off
	v_lshl_add_u64 v[218:219], s[26:27], 0, v[134:135]
	s_mov_b32 m0, s36
	s_nop 0
	global_load_lds_dwordx4 v[218:219], off
	s_barrier
	s_waitcnt lgkmcnt(0)
	s_setprio 1
	s_waitcnt lgkmcnt(0)
	v_mfma_f32_16x16x32_bf16 v[116:119], v[202:205], v[170:173], v[116:119]
	v_mfma_f32_16x16x32_bf16 v[112:115], v[210:213], v[170:173], v[112:115]
	v_mfma_f32_16x16x32_bf16 v[100:103], v[202:205], v[178:181], v[100:103]
	v_mfma_f32_16x16x32_bf16 v[96:99], v[210:213], v[178:181], v[96:99]
	v_mfma_f32_16x16x32_bf16 v[84:87], v[202:205], v[186:189], v[84:87]
	v_mfma_f32_16x16x32_bf16 v[80:83], v[210:213], v[186:189], v[80:83]
	v_mfma_f32_16x16x32_bf16 v[68:71], v[202:205], v[194:197], v[68:71]
	v_mfma_f32_16x16x32_bf16 v[64:67], v[210:213], v[194:197], v[64:67]
	v_mfma_f32_16x16x32_bf16 v[116:119], v[206:209], v[174:177], v[116:119]
	v_mfma_f32_16x16x32_bf16 v[112:115], v[214:217], v[174:177], v[112:115]
	v_mfma_f32_16x16x32_bf16 v[100:103], v[206:209], v[182:185], v[100:103]
	v_mfma_f32_16x16x32_bf16 v[96:99], v[214:217], v[182:185], v[96:99]
	v_mfma_f32_16x16x32_bf16 v[84:87], v[206:209], v[190:193], v[84:87]
	v_mfma_f32_16x16x32_bf16 v[80:83], v[214:217], v[190:193], v[80:83]
	v_mfma_f32_16x16x32_bf16 v[68:71], v[206:209], v[198:201], v[68:71]
	v_mfma_f32_16x16x32_bf16 v[64:67], v[214:217], v[198:201], v[64:67]
	s_setprio 0
	s_mov_b32 m0, s37
	v_lshl_add_u64 v[220:221], s[28:29], 0, v[128:129]
	s_barrier
	ds_read_b128 v[170:173], v150 offset:16384
	ds_read_b128 v[174:177], v150 offset:17408
	ds_read_b128 v[178:181], v150 offset:18432
	ds_read_b128 v[182:185], v150 offset:19456
	ds_read_b128 v[186:189], v150 offset:20480
	ds_read_b128 v[190:193], v150 offset:21504
	ds_read_b128 v[194:197], v150 offset:22528
	ds_read_b128 v[198:201], v150 offset:23552
	global_load_lds_dwordx4 v[220:221], off
	v_lshl_add_u64 v[222:223], s[28:29], 0, v[132:133]
	s_mov_b32 m0, s39
	s_nop 0
	global_load_lds_dwordx4 v[222:223], off
	s_barrier
	s_waitcnt lgkmcnt(0)
	s_setprio 1
	s_waitcnt lgkmcnt(0)
	v_mfma_f32_16x16x32_bf16 v[60:63], v[154:157], v[170:173], v[60:63]
	v_mfma_f32_16x16x32_bf16 v[56:59], v[162:165], v[170:173], v[56:59]
	v_mfma_f32_16x16x32_bf16 v[44:47], v[154:157], v[178:181], v[44:47]
	v_mfma_f32_16x16x32_bf16 v[40:43], v[162:165], v[178:181], v[40:43]
	v_mfma_f32_16x16x32_bf16 v[28:31], v[154:157], v[186:189], v[28:31]
	v_mfma_f32_16x16x32_bf16 v[24:27], v[162:165], v[186:189], v[24:27]
	v_mfma_f32_16x16x32_bf16 v[12:15], v[154:157], v[194:197], v[12:15]
	v_mfma_f32_16x16x32_bf16 v[8:11], v[162:165], v[194:197], v[8:11]
	v_mfma_f32_16x16x32_bf16 v[60:63], v[158:161], v[174:177], v[60:63]
	v_mfma_f32_16x16x32_bf16 v[56:59], v[166:169], v[174:177], v[56:59]
	v_mfma_f32_16x16x32_bf16 v[44:47], v[158:161], v[182:185], v[44:47]
	v_mfma_f32_16x16x32_bf16 v[40:43], v[166:169], v[182:185], v[40:43]
	v_mfma_f32_16x16x32_bf16 v[28:31], v[158:161], v[190:193], v[28:31]
	v_mfma_f32_16x16x32_bf16 v[24:27], v[166:169], v[190:193], v[24:27]
	v_mfma_f32_16x16x32_bf16 v[12:15], v[158:161], v[198:201], v[12:15]
	v_mfma_f32_16x16x32_bf16 v[8:11], v[166:169], v[198:201], v[8:11]
	s_setprio 0
	s_barrier
	s_add_u32 s60, s26, 0x40000
	s_addc_u32 s61, s27, 0
	s_mov_b32 m0, s40
	v_lshl_add_u64 v[154:155], s[60:61], 0, v[130:131]
	global_load_lds_dwordx4 v[154:155], off
	v_lshl_add_u64 v[154:155], s[60:61], 0, v[134:135]
	s_mov_b32 m0, s41
	s_nop 0
	global_load_lds_dwordx4 v[154:155], off
	s_waitcnt vmcnt(6)
	s_barrier
	s_setprio 1
	v_mfma_f32_16x16x32_bf16 v[52:55], v[202:205], v[170:173], v[52:55]
	v_mfma_f32_16x16x32_bf16 v[48:51], v[210:213], v[170:173], v[48:51]
	v_mfma_f32_16x16x32_bf16 v[36:39], v[202:205], v[178:181], v[36:39]
	v_mfma_f32_16x16x32_bf16 v[32:35], v[210:213], v[178:181], v[32:35]
	v_mfma_f32_16x16x32_bf16 v[20:23], v[202:205], v[186:189], v[20:23]
	v_mfma_f32_16x16x32_bf16 v[16:19], v[210:213], v[186:189], v[16:19]
	v_mfma_f32_16x16x32_bf16 v[4:7], v[202:205], v[194:197], v[4:7]
	v_mfma_f32_16x16x32_bf16 v[0:3], v[210:213], v[194:197], v[0:3]
	v_mfma_f32_16x16x32_bf16 v[52:55], v[206:209], v[174:177], v[52:55]
	v_mfma_f32_16x16x32_bf16 v[48:51], v[214:217], v[174:177], v[48:51]
	v_mfma_f32_16x16x32_bf16 v[36:39], v[206:209], v[182:185], v[36:39]
	v_mfma_f32_16x16x32_bf16 v[32:35], v[214:217], v[182:185], v[32:35]
	v_mfma_f32_16x16x32_bf16 v[20:23], v[206:209], v[190:193], v[20:23]
	v_mfma_f32_16x16x32_bf16 v[16:19], v[214:217], v[190:193], v[16:19]
	v_mfma_f32_16x16x32_bf16 v[4:7], v[206:209], v[198:201], v[4:7]
	v_mfma_f32_16x16x32_bf16 v[0:3], v[214:217], v[198:201], v[0:3]
	s_setprio 0
	s_barrier
	ds_read_b128 v[154:157], v152
	ds_read_b128 v[158:161], v152 offset:1024
	ds_read_b128 v[162:165], v152 offset:2048
	ds_read_b128 v[166:169], v152 offset:3072
	s_add_u32 s28, s28, 0x40000
	s_addc_u32 s29, s29, 0
	s_mov_b32 m0, s42
	v_lshl_add_u64 v[202:203], s[28:29], 0, v[128:129]
	ds_read_b128 v[170:173], v150 offset:32768
	ds_read_b128 v[174:177], v150 offset:33792
	ds_read_b128 v[178:181], v150 offset:34816
	ds_read_b128 v[182:185], v150 offset:35840
	ds_read_b128 v[186:189], v150 offset:36864
	ds_read_b128 v[190:193], v150 offset:37888
	ds_read_b128 v[194:197], v150 offset:38912
	ds_read_b128 v[198:201], v150 offset:39936
	global_load_lds_dwordx4 v[202:203], off
	v_lshl_add_u64 v[202:203], s[28:29], 0, v[132:133]
	s_mov_b32 m0, s43
	s_nop 0
	global_load_lds_dwordx4 v[202:203], off
	s_waitcnt lgkmcnt(8)
	s_barrier
	s_waitcnt lgkmcnt(0)
	s_setprio 1
	s_waitcnt lgkmcnt(0)
	v_mfma_f32_16x16x32_bf16 v[124:127], v[154:157], v[170:173], v[124:127]
	v_mfma_f32_16x16x32_bf16 v[120:123], v[162:165], v[170:173], v[120:123]
	v_mfma_f32_16x16x32_bf16 v[108:111], v[154:157], v[178:181], v[108:111]
	v_mfma_f32_16x16x32_bf16 v[104:107], v[162:165], v[178:181], v[104:107]
	v_mfma_f32_16x16x32_bf16 v[92:95], v[154:157], v[186:189], v[92:95]
	v_mfma_f32_16x16x32_bf16 v[88:91], v[162:165], v[186:189], v[88:91]
	v_mfma_f32_16x16x32_bf16 v[76:79], v[154:157], v[194:197], v[76:79]
	v_mfma_f32_16x16x32_bf16 v[72:75], v[162:165], v[194:197], v[72:75]
	v_mfma_f32_16x16x32_bf16 v[124:127], v[158:161], v[174:177], v[124:127]
	v_mfma_f32_16x16x32_bf16 v[120:123], v[166:169], v[174:177], v[120:123]
	v_mfma_f32_16x16x32_bf16 v[108:111], v[158:161], v[182:185], v[108:111]
	v_mfma_f32_16x16x32_bf16 v[104:107], v[166:169], v[182:185], v[104:107]
	v_mfma_f32_16x16x32_bf16 v[92:95], v[158:161], v[190:193], v[92:95]
	v_mfma_f32_16x16x32_bf16 v[88:91], v[166:169], v[190:193], v[88:91]
	v_mfma_f32_16x16x32_bf16 v[76:79], v[158:161], v[198:201], v[76:79]
	v_mfma_f32_16x16x32_bf16 v[72:75], v[166:169], v[198:201], v[72:75]
	s_setprio 0
	s_barrier
	s_mov_b32 m0, s46
	v_lshl_add_u64 v[146:147], v[146:147], 0, s[12:13]
	ds_read_b128 v[202:205], v153
	ds_read_b128 v[206:209], v153 offset:1024
	ds_read_b128 v[210:213], v153 offset:2048
	ds_read_b128 v[214:217], v153 offset:3072
	global_load_lds_dwordx4 v[146:147], off
	v_lshl_add_u64 v[146:147], v[218:219], 0, s[12:13]
	s_mov_b32 m0, s47
	s_nop 0
	global_load_lds_dwordx4 v[146:147], off
	s_barrier
	s_waitcnt lgkmcnt(0)
	s_setprio 1
	s_waitcnt lgkmcnt(0)
	v_mfma_f32_16x16x32_bf16 v[116:119], v[202:205], v[170:173], v[116:119]
	v_mfma_f32_16x16x32_bf16 v[112:115], v[210:213], v[170:173], v[112:115]
	v_mfma_f32_16x16x32_bf16 v[100:103], v[202:205], v[178:181], v[100:103]
	v_mfma_f32_16x16x32_bf16 v[96:99], v[210:213], v[178:181], v[96:99]
	v_mfma_f32_16x16x32_bf16 v[84:87], v[202:205], v[186:189], v[84:87]
	v_mfma_f32_16x16x32_bf16 v[80:83], v[210:213], v[186:189], v[80:83]
	v_mfma_f32_16x16x32_bf16 v[68:71], v[202:205], v[194:197], v[68:71]
	v_mfma_f32_16x16x32_bf16 v[64:67], v[210:213], v[194:197], v[64:67]
	v_mfma_f32_16x16x32_bf16 v[116:119], v[206:209], v[174:177], v[116:119]
	v_mfma_f32_16x16x32_bf16 v[112:115], v[214:217], v[174:177], v[112:115]
	v_mfma_f32_16x16x32_bf16 v[100:103], v[206:209], v[182:185], v[100:103]
	v_mfma_f32_16x16x32_bf16 v[96:99], v[214:217], v[182:185], v[96:99]
	v_mfma_f32_16x16x32_bf16 v[84:87], v[206:209], v[190:193], v[84:87]
	v_mfma_f32_16x16x32_bf16 v[80:83], v[214:217], v[190:193], v[80:83]
	v_mfma_f32_16x16x32_bf16 v[68:71], v[206:209], v[198:201], v[68:71]
	v_mfma_f32_16x16x32_bf16 v[64:67], v[214:217], v[198:201], v[64:67]
	s_setprio 0
	s_mov_b32 m0, s48
	v_lshl_add_u64 v[146:147], v[220:221], 0, s[12:13]
	s_barrier
	ds_read_b128 v[170:173], v150 offset:49152
	ds_read_b128 v[174:177], v150 offset:50176
	ds_read_b128 v[178:181], v150 offset:51200
	ds_read_b128 v[182:185], v150 offset:52224
	ds_read_b128 v[186:189], v150 offset:53248
	ds_read_b128 v[190:193], v150 offset:54272
	ds_read_b128 v[194:197], v150 offset:55296
	ds_read_b128 v[198:201], v150 offset:56320
	global_load_lds_dwordx4 v[146:147], off
	v_lshl_add_u64 v[146:147], v[222:223], 0, s[12:13]
	s_mov_b32 m0, s49
	s_nop 0
	global_load_lds_dwordx4 v[146:147], off
	s_barrier
	s_waitcnt lgkmcnt(0)
	s_setprio 1
	s_waitcnt lgkmcnt(0)
	v_mfma_f32_16x16x32_bf16 v[60:63], v[154:157], v[170:173], v[60:63]
	v_mfma_f32_16x16x32_bf16 v[56:59], v[162:165], v[170:173], v[56:59]
	v_mfma_f32_16x16x32_bf16 v[44:47], v[154:157], v[178:181], v[44:47]
	v_mfma_f32_16x16x32_bf16 v[40:43], v[162:165], v[178:181], v[40:43]
	v_mfma_f32_16x16x32_bf16 v[28:31], v[154:157], v[186:189], v[28:31]
	v_mfma_f32_16x16x32_bf16 v[24:27], v[162:165], v[186:189], v[24:27]
	v_mfma_f32_16x16x32_bf16 v[12:15], v[154:157], v[194:197], v[12:15]
	v_mfma_f32_16x16x32_bf16 v[8:11], v[162:165], v[194:197], v[8:11]
	v_mfma_f32_16x16x32_bf16 v[60:63], v[158:161], v[174:177], v[60:63]
	v_mfma_f32_16x16x32_bf16 v[56:59], v[166:169], v[174:177], v[56:59]
	v_mfma_f32_16x16x32_bf16 v[44:47], v[158:161], v[182:185], v[44:47]
	v_mfma_f32_16x16x32_bf16 v[40:43], v[166:169], v[182:185], v[40:43]
	v_mfma_f32_16x16x32_bf16 v[28:31], v[158:161], v[190:193], v[28:31]
	v_mfma_f32_16x16x32_bf16 v[24:27], v[166:169], v[190:193], v[24:27]
	v_mfma_f32_16x16x32_bf16 v[12:15], v[158:161], v[198:201], v[12:15]
	v_mfma_f32_16x16x32_bf16 v[8:11], v[166:169], v[198:201], v[8:11]
	s_setprio 0
	s_barrier
	s_add_u32 s26, s26, 0x40080
	s_addc_u32 s27, s27, 0
	s_mov_b32 m0, s50
	v_lshl_add_u64 v[146:147], s[26:27], 0, v[130:131]
	global_load_lds_dwordx4 v[146:147], off
	v_lshl_add_u64 v[146:147], s[26:27], 0, v[134:135]
	s_mov_b32 m0, s51
	s_nop 0
	global_load_lds_dwordx4 v[146:147], off
	s_waitcnt vmcnt(6)
	s_barrier
	s_setprio 1
	v_mfma_f32_16x16x32_bf16 v[52:55], v[202:205], v[170:173], v[52:55]
	v_mfma_f32_16x16x32_bf16 v[48:51], v[210:213], v[170:173], v[48:51]
	v_mfma_f32_16x16x32_bf16 v[36:39], v[202:205], v[178:181], v[36:39]
	v_mfma_f32_16x16x32_bf16 v[32:35], v[210:213], v[178:181], v[32:35]
	v_mfma_f32_16x16x32_bf16 v[20:23], v[202:205], v[186:189], v[20:23]
	v_mfma_f32_16x16x32_bf16 v[16:19], v[210:213], v[186:189], v[16:19]
	v_mfma_f32_16x16x32_bf16 v[4:7], v[202:205], v[194:197], v[4:7]
	v_mfma_f32_16x16x32_bf16 v[0:3], v[210:213], v[194:197], v[0:3]
	v_mfma_f32_16x16x32_bf16 v[52:55], v[206:209], v[174:177], v[52:55]
	v_mfma_f32_16x16x32_bf16 v[48:51], v[214:217], v[174:177], v[48:51]
	v_mfma_f32_16x16x32_bf16 v[36:39], v[206:209], v[182:185], v[36:39]
	v_mfma_f32_16x16x32_bf16 v[32:35], v[214:217], v[182:185], v[32:35]
	v_mfma_f32_16x16x32_bf16 v[20:23], v[206:209], v[190:193], v[20:23]
	v_mfma_f32_16x16x32_bf16 v[16:19], v[214:217], v[190:193], v[16:19]
	v_mfma_f32_16x16x32_bf16 v[4:7], v[206:209], v[198:201], v[4:7]
	v_mfma_f32_16x16x32_bf16 v[0:3], v[214:217], v[198:201], v[0:3]
	s_setprio 0
	s_add_i32 s59, s59, 2
	s_add_u32 s24, s24, 0x100
	s_addc_u32 s25, s25, 0
	s_add_u32 s57, s57, 0x100
	s_addc_u32 s58, s58, 0
	s_cmp_gt_u32 s59, 13
	s_barrier
	s_cbranch_scc0 .LBB0_2272
	v_mul_f32_e32 v124, 0xbfb8aa3b, v124
	v_mul_f32_e32 v125, 0xbfb8aa3b, v125
	v_mul_f32_e32 v120, 0xbfb8aa3b, v120
	v_mul_f32_e32 v121, 0xbfb8aa3b, v121
	v_exp_f32_e32 v124, v124
	v_exp_f32_e32 v125, v125
	v_exp_f32_e32 v120, v120
	v_exp_f32_e32 v121, v121
	v_mov_b32_e32 v136, 0
	v_mul_f32_e32 v126, 0xbfb8aa3b, v126
	v_mul_f32_e32 v127, 0xbfb8aa3b, v127
	v_mul_f32_e32 v122, 0xbfb8aa3b, v122
	v_exp_f32_e32 v126, v126
	v_exp_f32_e32 v127, v127
	v_exp_f32_e32 v122, v122
	v_mul_f32_e32 v123, 0xbfb8aa3b, v123
	v_mbcnt_lo_u32_b32 v136, -1, v136
	s_lshl_b32 s15, s22, 8
	v_exp_f32_e32 v123, v123
	v_mbcnt_hi_u32_b32 v136, -1, v136
	s_add_i32 s15, s15, s44
	v_add_f32_e32 v124, 1.0, v124
	v_add_f32_e32 v125, 1.0, v125
	v_add_f32_e32 v120, 1.0, v120
	v_add_f32_e32 v121, 1.0, v121
	v_and_or_b32 v146, v136, 15, s15
	s_lshl_b32 s15, s54, 8
	v_ashrrev_i32_e32 v136, 1, v136
	v_rcp_f32_e32 v124, v124
	v_rcp_f32_e32 v125, v125
	v_rcp_f32_e32 v120, v120
	v_rcp_f32_e32 v121, v121
	v_and_b32_e32 v136, -8, v136
	s_or_b32 s15, s15, s45
	v_add_f32_e32 v126, 1.0, v126
	v_add_f32_e32 v127, 1.0, v127
	v_add_f32_e32 v122, 1.0, v122
	v_mul_f32_e32 v116, 0xbfb8aa3b, v116
	v_mul_f32_e32 v117, 0xbfb8aa3b, v117
	v_mul_f32_e32 v118, 0xbfb8aa3b, v118
	v_mul_f32_e32 v119, 0xbfb8aa3b, v119
	v_mul_f32_e32 v112, 0xbfb8aa3b, v112
	v_mul_f32_e32 v113, 0xbfb8aa3b, v113
	v_add_u32_e32 v154, s15, v136
	v_rcp_f32_e32 v126, v126
	v_rcp_f32_e32 v127, v127
	v_rcp_f32_e32 v136, v122
	v_add_f32_e32 v122, 1.0, v123
	v_exp_f32_e32 v116, v116
	v_exp_f32_e32 v117, v117
	v_exp_f32_e32 v118, v118
	v_exp_f32_e32 v119, v119
	v_exp_f32_e32 v112, v112
	v_exp_f32_e32 v113, v113
	v_rcp_f32_e32 v155, v122
	v_mul_f32_e32 v114, 0xbfb8aa3b, v114
	v_mul_f32_e32 v115, 0xbfb8aa3b, v115
	v_cvt_pk_bf16_f32 v122, v124, v125
	v_cvt_pk_bf16_f32 v124, v120, v121
	v_lshrrev_b32_e32 v120, 8, v154
	v_exp_f32_e32 v114, v114
	v_exp_f32_e32 v115, v115
	v_ashrrev_i32_e32 v147, 31, v146
	v_mul_hi_i32_i24_e32 v121, 0x4080, v120
	v_mul_i32_i24_e32 v120, 0x4080, v120
	v_cvt_pk_bf16_f32 v123, v126, v127
	v_lshl_add_u64 v[126:127], v[120:121], 0, v[146:147]
	v_add_f32_e32 v116, 1.0, v116
	v_add_f32_e32 v117, 1.0, v117
	v_add_f32_e32 v118, 1.0, v118
	v_add_f32_e32 v119, 1.0, v119
	v_add_f32_e32 v112, 1.0, v112
	v_add_f32_e32 v113, 1.0, v113
	v_cvt_pk_bf16_f32 v125, v136, v155
	v_and_b32_e32 v136, 0xf8, v154
	v_mbcnt_lo_u32_b32 v230, -1, 0
	v_mbcnt_hi_u32_b32 v230, -1, v230
	v_and_b32_e32 v231, 15, v230
	v_bfe_u32 v232, v154, 4, 4
	v_sub_u32_e32 v232, v232, v231
	v_lshlrev_b32_e32 v232, 9, v232
	v_lshl_add_u32 v232, v231, 4, v232
	v_bfe_u32 v233, v230, 4, 1
	v_lshl_add_u32 v232, v233, 8, v232
	v_and_b32_e32 v233, 0xf8, v154
	v_lshlrev_b32_e32 v233, 1, v233
	v_sub_u32_e32 v226, v232, v233
	v_ashrrev_i32_e32 v227, 31, v226
	v_add_u32_e32 v228, 0xf00, v226
	v_ashrrev_i32_e32 v229, 31, v228
	v_lshlrev_b64 v[126:127], 9, v[126:127]
	v_rcp_f32_e32 v116, v116
	v_rcp_f32_e32 v117, v117
	v_rcp_f32_e32 v118, v118
	v_rcp_f32_e32 v119, v119
	v_rcp_f32_e32 v112, v112
	v_rcp_f32_e32 v113, v113
	v_lshl_add_u64 v[126:127], s[0:1], 0, v[126:127]
	v_lshlrev_b32_e32 v136, 1, v136
	v_add_f32_e32 v114, 1.0, v114
	v_add_f32_e32 v115, 1.0, v115
	v_lshl_add_u64 v[126:127], v[126:127], 0, v[136:137]
	v_rcp_f32_e32 v114, v114
	v_rcp_f32_e32 v115, v115
	v_lshl_add_u64 v[126:127], v[126:127], 0, v[226:227]
	global_store_dwordx4 v[126:127], v[122:125], off
	v_cvt_pk_bf16_f32 v116, v116, v117
	v_cvt_pk_bf16_f32 v117, v118, v119
	v_add_u32_e32 v122, 0x80, v154
	v_cvt_pk_bf16_f32 v118, v112, v113
	v_lshrrev_b32_e32 v112, 8, v122
	v_mul_f32_e32 v104, 0xbfb8aa3b, v104
	v_mul_hi_i32_i24_e32 v113, 0x4080, v112
	v_mul_i32_i24_e32 v112, 0x4080, v112
	v_exp_f32_e32 v104, v104
	v_mul_f32_e32 v105, 0xbfb8aa3b, v105
	v_cvt_pk_bf16_f32 v119, v114, v115
	v_lshl_add_u64 v[114:115], v[112:113], 0, v[146:147]
	v_exp_f32_e32 v105, v105
	v_and_b32_e32 v124, 0xf8, v122
	v_lshlrev_b64 v[114:115], 9, v[114:115]
	v_lshl_add_u64 v[122:123], s[0:1], 0, v[114:115]
	v_lshlrev_b32_e32 v114, 1, v124
	v_mov_b32_e32 v115, v137
	v_mul_f32_e32 v108, 0xbfb8aa3b, v108
	v_mul_f32_e32 v109, 0xbfb8aa3b, v109
	v_lshl_add_u64 v[122:123], v[122:123], 0, v[114:115]
	v_exp_f32_e32 v108, v108
	v_exp_f32_e32 v109, v109
	v_add_f32_e32 v104, 1.0, v104
	v_lshl_add_u64 v[122:123], v[122:123], 0, v[228:229]
	global_store_dwordx4 v[122:123], v[116:119], off
	v_mul_f32_e32 v110, 0xbfb8aa3b, v110
	v_mul_f32_e32 v111, 0xbfb8aa3b, v111
	v_rcp_f32_e32 v118, v104
	v_add_f32_e32 v104, 1.0, v105
	v_mul_f32_e32 v105, 0xbfb8aa3b, v106
	v_exp_f32_e32 v105, v105
	v_mul_f32_e32 v106, 0xbfb8aa3b, v107
	v_exp_f32_e32 v110, v110
	v_exp_f32_e32 v111, v111
	v_exp_f32_e32 v106, v106
	v_add_f32_e32 v108, 1.0, v108
	v_add_f32_e32 v109, 1.0, v109
	v_rcp_f32_e32 v108, v108
	v_rcp_f32_e32 v109, v109
	v_rcp_f32_e32 v107, v104
	v_add_f32_e32 v104, 1.0, v105
	v_or_b32_e32 v116, 16, v146
	v_add_f32_e32 v110, 1.0, v110
	v_add_f32_e32 v111, 1.0, v111
	v_rcp_f32_e32 v119, v104
	v_add_f32_e32 v104, 1.0, v106
	v_mul_f32_e32 v96, 0xbfb8aa3b, v96
	v_ashrrev_i32_e32 v117, 31, v116
	v_rcp_f32_e32 v110, v110
	v_rcp_f32_e32 v111, v111
	v_rcp_f32_e32 v122, v104
	v_exp_f32_e32 v96, v96
	v_mul_f32_e32 v97, 0xbfb8aa3b, v97
	v_cvt_pk_bf16_f32 v104, v108, v109
	v_lshl_add_u64 v[108:109], v[120:121], 0, v[116:117]
	v_exp_f32_e32 v97, v97
	v_lshlrev_b64 v[108:109], 9, v[108:109]
	v_lshl_add_u64 v[108:109], s[0:1], 0, v[108:109]
	v_mul_f32_e32 v100, 0xbfb8aa3b, v100
	v_mul_f32_e32 v101, 0xbfb8aa3b, v101
	v_cvt_pk_bf16_f32 v105, v110, v111
	v_cvt_pk_bf16_f32 v106, v118, v107
	v_cvt_pk_bf16_f32 v107, v119, v122
	v_lshl_add_u64 v[108:109], v[108:109], 0, v[136:137]
	v_exp_f32_e32 v100, v100
	v_exp_f32_e32 v101, v101
	v_add_f32_e32 v96, 1.0, v96
	v_lshl_add_u64 v[108:109], v[108:109], 0, v[226:227]
	global_store_dwordx4 v[108:109], v[104:107], off
	v_mul_f32_e32 v102, 0xbfb8aa3b, v102
	v_mul_f32_e32 v103, 0xbfb8aa3b, v103
	v_rcp_f32_e32 v104, v96
	v_add_f32_e32 v96, 1.0, v97
	v_mul_f32_e32 v97, 0xbfb8aa3b, v98
	v_exp_f32_e32 v97, v97
	v_mul_f32_e32 v98, 0xbfb8aa3b, v99
	v_exp_f32_e32 v102, v102
	v_exp_f32_e32 v103, v103
	v_exp_f32_e32 v98, v98
	v_add_f32_e32 v100, 1.0, v100
	v_add_f32_e32 v101, 1.0, v101
	v_rcp_f32_e32 v100, v100
	v_rcp_f32_e32 v101, v101
	v_rcp_f32_e32 v99, v96
	v_add_f32_e32 v96, 1.0, v97
	v_add_f32_e32 v102, 1.0, v102
	v_add_f32_e32 v103, 1.0, v103
	v_rcp_f32_e32 v105, v96
	v_add_f32_e32 v96, 1.0, v98
	v_mul_f32_e32 v88, 0xbfb8aa3b, v88
	v_rcp_f32_e32 v102, v102
	v_rcp_f32_e32 v103, v103
	v_rcp_f32_e32 v106, v96
	v_exp_f32_e32 v88, v88
	v_mul_f32_e32 v89, 0xbfb8aa3b, v89
	v_cvt_pk_bf16_f32 v96, v100, v101
	v_lshl_add_u64 v[100:101], v[112:113], 0, v[116:117]
	v_exp_f32_e32 v89, v89
	v_lshlrev_b64 v[100:101], 9, v[100:101]
	v_lshl_add_u64 v[100:101], s[0:1], 0, v[100:101]
	v_mul_f32_e32 v92, 0xbfb8aa3b, v92
	v_mul_f32_e32 v93, 0xbfb8aa3b, v93
	v_cvt_pk_bf16_f32 v97, v102, v103
	v_cvt_pk_bf16_f32 v98, v104, v99
	v_cvt_pk_bf16_f32 v99, v105, v106
	v_lshl_add_u64 v[100:101], v[100:101], 0, v[114:115]
	v_exp_f32_e32 v92, v92
	v_exp_f32_e32 v93, v93
	v_add_f32_e32 v88, 1.0, v88
	v_lshl_add_u64 v[100:101], v[100:101], 0, v[228:229]
	global_store_dwordx4 v[100:101], v[96:99], off
	v_mul_f32_e32 v94, 0xbfb8aa3b, v94
	v_mul_f32_e32 v95, 0xbfb8aa3b, v95
	v_rcp_f32_e32 v98, v88
	v_add_f32_e32 v88, 1.0, v89
	v_mul_f32_e32 v89, 0xbfb8aa3b, v90
	v_exp_f32_e32 v89, v89
	v_mul_f32_e32 v90, 0xbfb8aa3b, v91
	v_exp_f32_e32 v94, v94
	v_exp_f32_e32 v95, v95
	v_exp_f32_e32 v90, v90
	v_add_f32_e32 v92, 1.0, v92
	v_add_f32_e32 v93, 1.0, v93
	v_rcp_f32_e32 v92, v92
	v_rcp_f32_e32 v93, v93
	v_rcp_f32_e32 v91, v88
	v_add_f32_e32 v88, 1.0, v89
	v_or_b32_e32 v96, 32, v146
	v_add_f32_e32 v94, 1.0, v94
	v_add_f32_e32 v95, 1.0, v95
	v_rcp_f32_e32 v99, v88
	v_add_f32_e32 v88, 1.0, v90
	v_mul_f32_e32 v80, 0xbfb8aa3b, v80
	v_ashrrev_i32_e32 v97, 31, v96
	v_rcp_f32_e32 v94, v94
	v_rcp_f32_e32 v95, v95
	v_rcp_f32_e32 v100, v88
	v_exp_f32_e32 v80, v80
	v_mul_f32_e32 v81, 0xbfb8aa3b, v81
	v_cvt_pk_bf16_f32 v88, v92, v93
	v_lshl_add_u64 v[92:93], v[120:121], 0, v[96:97]
	v_exp_f32_e32 v81, v81
	v_lshlrev_b64 v[92:93], 9, v[92:93]
	v_lshl_add_u64 v[92:93], s[0:1], 0, v[92:93]
	v_mul_f32_e32 v84, 0xbfb8aa3b, v84
	v_mul_f32_e32 v85, 0xbfb8aa3b, v85
	v_cvt_pk_bf16_f32 v89, v94, v95
	v_cvt_pk_bf16_f32 v90, v98, v91
	v_cvt_pk_bf16_f32 v91, v99, v100
	v_lshl_add_u64 v[92:93], v[92:93], 0, v[136:137]
	v_exp_f32_e32 v84, v84
	v_exp_f32_e32 v85, v85
	v_add_f32_e32 v80, 1.0, v80
	v_lshl_add_u64 v[92:93], v[92:93], 0, v[226:227]
	global_store_dwordx4 v[92:93], v[88:91], off
	v_mul_f32_e32 v86, 0xbfb8aa3b, v86
	v_mul_f32_e32 v87, 0xbfb8aa3b, v87
	v_rcp_f32_e32 v88, v80
	v_add_f32_e32 v80, 1.0, v81
	v_mul_f32_e32 v81, 0xbfb8aa3b, v82
	v_exp_f32_e32 v81, v81
	v_mul_f32_e32 v82, 0xbfb8aa3b, v83
	v_exp_f32_e32 v86, v86
	v_exp_f32_e32 v87, v87
	v_exp_f32_e32 v82, v82
	v_add_f32_e32 v84, 1.0, v84
	v_add_f32_e32 v85, 1.0, v85
	v_rcp_f32_e32 v84, v84
	v_rcp_f32_e32 v85, v85
	v_rcp_f32_e32 v83, v80
	v_add_f32_e32 v80, 1.0, v81
	v_add_f32_e32 v86, 1.0, v86
	v_add_f32_e32 v87, 1.0, v87
	v_rcp_f32_e32 v89, v80
	v_add_f32_e32 v80, 1.0, v82
	v_mul_f32_e32 v72, 0xbfb8aa3b, v72
	v_rcp_f32_e32 v86, v86
	v_rcp_f32_e32 v87, v87
	v_rcp_f32_e32 v90, v80
	v_exp_f32_e32 v72, v72
	v_mul_f32_e32 v73, 0xbfb8aa3b, v73
	v_cvt_pk_bf16_f32 v80, v84, v85
	v_lshl_add_u64 v[84:85], v[112:113], 0, v[96:97]
	v_exp_f32_e32 v73, v73
	v_lshlrev_b64 v[84:85], 9, v[84:85]
	v_lshl_add_u64 v[84:85], s[0:1], 0, v[84:85]
	v_mul_f32_e32 v76, 0xbfb8aa3b, v76
	v_mul_f32_e32 v77, 0xbfb8aa3b, v77
	v_cvt_pk_bf16_f32 v81, v86, v87
	v_cvt_pk_bf16_f32 v82, v88, v83
	v_cvt_pk_bf16_f32 v83, v89, v90
	v_lshl_add_u64 v[84:85], v[84:85], 0, v[114:115]
	v_exp_f32_e32 v76, v76
	v_exp_f32_e32 v77, v77
	v_add_f32_e32 v72, 1.0, v72
	v_lshl_add_u64 v[84:85], v[84:85], 0, v[228:229]
	global_store_dwordx4 v[84:85], v[80:83], off
	v_mul_f32_e32 v78, 0xbfb8aa3b, v78
	v_mul_f32_e32 v79, 0xbfb8aa3b, v79
	v_rcp_f32_e32 v82, v72
	v_add_f32_e32 v72, 1.0, v73
	v_mul_f32_e32 v73, 0xbfb8aa3b, v74
	v_exp_f32_e32 v73, v73
	v_mul_f32_e32 v74, 0xbfb8aa3b, v75
	v_exp_f32_e32 v78, v78
	v_exp_f32_e32 v79, v79
	v_exp_f32_e32 v74, v74
	v_add_f32_e32 v76, 1.0, v76
	v_add_f32_e32 v77, 1.0, v77
	v_rcp_f32_e32 v76, v76
	v_rcp_f32_e32 v77, v77
	v_rcp_f32_e32 v75, v72
	v_add_f32_e32 v72, 1.0, v73
	v_or_b32_e32 v80, 48, v146
	v_add_f32_e32 v78, 1.0, v78
	v_add_f32_e32 v79, 1.0, v79
	v_rcp_f32_e32 v83, v72
	v_add_f32_e32 v72, 1.0, v74
	v_mul_f32_e32 v64, 0xbfb8aa3b, v64
	v_ashrrev_i32_e32 v81, 31, v80
	v_rcp_f32_e32 v78, v78
	v_rcp_f32_e32 v79, v79
	v_rcp_f32_e32 v84, v72
	v_exp_f32_e32 v64, v64
	v_mul_f32_e32 v65, 0xbfb8aa3b, v65
	v_cvt_pk_bf16_f32 v72, v76, v77
	v_lshl_add_u64 v[76:77], v[120:121], 0, v[80:81]
	v_exp_f32_e32 v65, v65
	v_lshlrev_b64 v[76:77], 9, v[76:77]
	v_lshl_add_u64 v[76:77], s[0:1], 0, v[76:77]
	v_mul_f32_e32 v68, 0xbfb8aa3b, v68
	v_mul_f32_e32 v69, 0xbfb8aa3b, v69
	v_cvt_pk_bf16_f32 v73, v78, v79
	v_cvt_pk_bf16_f32 v74, v82, v75
	v_cvt_pk_bf16_f32 v75, v83, v84
	v_lshl_add_u64 v[76:77], v[76:77], 0, v[136:137]
	v_exp_f32_e32 v68, v68
	v_exp_f32_e32 v69, v69
	v_add_f32_e32 v64, 1.0, v64
	v_lshl_add_u64 v[76:77], v[76:77], 0, v[226:227]
	global_store_dwordx4 v[76:77], v[72:75], off
	v_mul_f32_e32 v70, 0xbfb8aa3b, v70
	v_mul_f32_e32 v71, 0xbfb8aa3b, v71
	v_rcp_f32_e32 v72, v64
	v_add_f32_e32 v64, 1.0, v65
	v_mul_f32_e32 v65, 0xbfb8aa3b, v66
	v_exp_f32_e32 v65, v65
	v_mul_f32_e32 v66, 0xbfb8aa3b, v67
	v_exp_f32_e32 v70, v70
	v_exp_f32_e32 v71, v71
	v_exp_f32_e32 v66, v66
	v_add_f32_e32 v68, 1.0, v68
	v_add_f32_e32 v69, 1.0, v69
	v_rcp_f32_e32 v68, v68
	v_rcp_f32_e32 v69, v69
	v_rcp_f32_e32 v67, v64
	v_add_f32_e32 v64, 1.0, v65
	v_add_f32_e32 v70, 1.0, v70
	v_add_f32_e32 v71, 1.0, v71
	v_rcp_f32_e32 v73, v64
	v_add_f32_e32 v64, 1.0, v66
	v_mul_f32_e32 v56, 0xbfb8aa3b, v56
	v_rcp_f32_e32 v70, v70
	v_rcp_f32_e32 v71, v71
	v_rcp_f32_e32 v74, v64
	v_exp_f32_e32 v56, v56
	v_mul_f32_e32 v57, 0xbfb8aa3b, v57
	v_cvt_pk_bf16_f32 v64, v68, v69
	v_lshl_add_u64 v[68:69], v[112:113], 0, v[80:81]
	v_exp_f32_e32 v57, v57
	v_lshlrev_b64 v[68:69], 9, v[68:69]
	v_lshl_add_u64 v[68:69], s[0:1], 0, v[68:69]
	v_mul_f32_e32 v60, 0xbfb8aa3b, v60
	v_mul_f32_e32 v61, 0xbfb8aa3b, v61
	v_cvt_pk_bf16_f32 v65, v70, v71
	v_cvt_pk_bf16_f32 v66, v72, v67
	v_cvt_pk_bf16_f32 v67, v73, v74
	v_lshl_add_u64 v[68:69], v[68:69], 0, v[114:115]
	v_exp_f32_e32 v60, v60
	v_exp_f32_e32 v61, v61
	v_add_f32_e32 v56, 1.0, v56
	v_lshl_add_u64 v[68:69], v[68:69], 0, v[228:229]
	global_store_dwordx4 v[68:69], v[64:67], off
	v_mul_f32_e32 v62, 0xbfb8aa3b, v62
	v_mul_f32_e32 v63, 0xbfb8aa3b, v63
	v_rcp_f32_e32 v66, v56
	v_add_f32_e32 v56, 1.0, v57
	v_mul_f32_e32 v57, 0xbfb8aa3b, v58
	v_exp_f32_e32 v57, v57
	v_mul_f32_e32 v58, 0xbfb8aa3b, v59
	v_exp_f32_e32 v62, v62
	v_exp_f32_e32 v63, v63
	v_exp_f32_e32 v58, v58
	v_add_f32_e32 v60, 1.0, v60
	v_add_f32_e32 v61, 1.0, v61
	v_rcp_f32_e32 v60, v60
	v_rcp_f32_e32 v61, v61
	v_rcp_f32_e32 v59, v56
	v_add_f32_e32 v56, 1.0, v57
	v_add_u32_e32 v64, 0x80, v146
	v_add_f32_e32 v62, 1.0, v62
	v_add_f32_e32 v63, 1.0, v63
	v_rcp_f32_e32 v67, v56
	v_add_f32_e32 v56, 1.0, v58
	v_mul_f32_e32 v48, 0xbfb8aa3b, v48
	v_ashrrev_i32_e32 v65, 31, v64
	v_rcp_f32_e32 v62, v62
	v_rcp_f32_e32 v63, v63
	v_rcp_f32_e32 v68, v56
	v_exp_f32_e32 v48, v48
	v_mul_f32_e32 v49, 0xbfb8aa3b, v49
	v_cvt_pk_bf16_f32 v56, v60, v61
	v_lshl_add_u64 v[60:61], v[120:121], 0, v[64:65]
	v_exp_f32_e32 v49, v49
	v_lshlrev_b64 v[60:61], 9, v[60:61]
	v_lshl_add_u64 v[60:61], s[0:1], 0, v[60:61]
	v_mul_f32_e32 v52, 0xbfb8aa3b, v52
	v_mul_f32_e32 v53, 0xbfb8aa3b, v53
	v_cvt_pk_bf16_f32 v57, v62, v63
	v_cvt_pk_bf16_f32 v58, v66, v59
	v_cvt_pk_bf16_f32 v59, v67, v68
	v_lshl_add_u64 v[60:61], v[60:61], 0, v[136:137]
	v_exp_f32_e32 v52, v52
	v_exp_f32_e32 v53, v53
	v_add_f32_e32 v48, 1.0, v48
	v_lshl_add_u64 v[60:61], v[60:61], 0, v[226:227]
	global_store_dwordx4 v[60:61], v[56:59], off
	v_mul_f32_e32 v54, 0xbfb8aa3b, v54
	v_mul_f32_e32 v55, 0xbfb8aa3b, v55
	v_rcp_f32_e32 v56, v48
	v_add_f32_e32 v48, 1.0, v49
	v_mul_f32_e32 v49, 0xbfb8aa3b, v50
	v_exp_f32_e32 v49, v49
	v_mul_f32_e32 v50, 0xbfb8aa3b, v51
	v_exp_f32_e32 v54, v54
	v_exp_f32_e32 v55, v55
	v_exp_f32_e32 v50, v50
	v_add_f32_e32 v52, 1.0, v52
	v_add_f32_e32 v53, 1.0, v53
	v_rcp_f32_e32 v52, v52
	v_rcp_f32_e32 v53, v53
	v_rcp_f32_e32 v51, v48
	v_add_f32_e32 v48, 1.0, v49
	v_add_f32_e32 v54, 1.0, v54
	v_add_f32_e32 v55, 1.0, v55
	v_rcp_f32_e32 v57, v48
	v_add_f32_e32 v48, 1.0, v50
	v_mul_f32_e32 v40, 0xbfb8aa3b, v40
	v_rcp_f32_e32 v54, v54
	v_rcp_f32_e32 v55, v55
	v_rcp_f32_e32 v58, v48
	v_exp_f32_e32 v40, v40
	v_mul_f32_e32 v41, 0xbfb8aa3b, v41
	v_cvt_pk_bf16_f32 v48, v52, v53
	v_lshl_add_u64 v[52:53], v[112:113], 0, v[64:65]
	v_exp_f32_e32 v41, v41
	v_lshlrev_b64 v[52:53], 9, v[52:53]
	v_lshl_add_u64 v[52:53], s[0:1], 0, v[52:53]
	v_mul_f32_e32 v44, 0xbfb8aa3b, v44
	v_mul_f32_e32 v45, 0xbfb8aa3b, v45
	v_cvt_pk_bf16_f32 v49, v54, v55
	v_cvt_pk_bf16_f32 v50, v56, v51
	v_cvt_pk_bf16_f32 v51, v57, v58
	v_lshl_add_u64 v[52:53], v[52:53], 0, v[114:115]
	v_exp_f32_e32 v44, v44
	v_exp_f32_e32 v45, v45
	v_add_f32_e32 v40, 1.0, v40
	v_lshl_add_u64 v[52:53], v[52:53], 0, v[228:229]
	global_store_dwordx4 v[52:53], v[48:51], off
	v_mul_f32_e32 v46, 0xbfb8aa3b, v46
	v_mul_f32_e32 v47, 0xbfb8aa3b, v47
	v_rcp_f32_e32 v50, v40
	v_add_f32_e32 v40, 1.0, v41
	v_mul_f32_e32 v41, 0xbfb8aa3b, v42
	v_exp_f32_e32 v41, v41
	v_mul_f32_e32 v42, 0xbfb8aa3b, v43
	v_exp_f32_e32 v46, v46
	v_exp_f32_e32 v47, v47
	v_exp_f32_e32 v42, v42
	v_add_f32_e32 v44, 1.0, v44
	v_add_f32_e32 v45, 1.0, v45
	v_rcp_f32_e32 v44, v44
	v_rcp_f32_e32 v45, v45
	v_rcp_f32_e32 v43, v40
	v_add_f32_e32 v40, 1.0, v41
	v_add_u32_e32 v48, 0x90, v146
	v_add_f32_e32 v46, 1.0, v46
	v_add_f32_e32 v47, 1.0, v47
	v_rcp_f32_e32 v51, v40
	v_add_f32_e32 v40, 1.0, v42
	v_mul_f32_e32 v32, 0xbfb8aa3b, v32
	v_ashrrev_i32_e32 v49, 31, v48
	v_rcp_f32_e32 v46, v46
	v_rcp_f32_e32 v47, v47
	v_rcp_f32_e32 v52, v40
	v_exp_f32_e32 v32, v32
	v_mul_f32_e32 v33, 0xbfb8aa3b, v33
	v_cvt_pk_bf16_f32 v40, v44, v45
	v_lshl_add_u64 v[44:45], v[120:121], 0, v[48:49]
	v_exp_f32_e32 v33, v33
	v_lshlrev_b64 v[44:45], 9, v[44:45]
	v_lshl_add_u64 v[44:45], s[0:1], 0, v[44:45]
	v_mul_f32_e32 v36, 0xbfb8aa3b, v36
	v_mul_f32_e32 v37, 0xbfb8aa3b, v37
	v_cvt_pk_bf16_f32 v41, v46, v47
	v_cvt_pk_bf16_f32 v42, v50, v43
	v_cvt_pk_bf16_f32 v43, v51, v52
	v_lshl_add_u64 v[44:45], v[44:45], 0, v[136:137]
	v_exp_f32_e32 v36, v36
	v_exp_f32_e32 v37, v37
	v_add_f32_e32 v32, 1.0, v32
	v_lshl_add_u64 v[44:45], v[44:45], 0, v[226:227]
	global_store_dwordx4 v[44:45], v[40:43], off
	v_mul_f32_e32 v38, 0xbfb8aa3b, v38
	v_mul_f32_e32 v39, 0xbfb8aa3b, v39
	v_rcp_f32_e32 v40, v32
	v_add_f32_e32 v32, 1.0, v33
	v_mul_f32_e32 v33, 0xbfb8aa3b, v34
	v_exp_f32_e32 v33, v33
	v_mul_f32_e32 v34, 0xbfb8aa3b, v35
	v_exp_f32_e32 v38, v38
	v_exp_f32_e32 v39, v39
	v_exp_f32_e32 v34, v34
	v_add_f32_e32 v36, 1.0, v36
	v_add_f32_e32 v37, 1.0, v37
	v_rcp_f32_e32 v36, v36
	v_rcp_f32_e32 v37, v37
	v_rcp_f32_e32 v35, v32
	v_add_f32_e32 v32, 1.0, v33
	v_add_f32_e32 v38, 1.0, v38
	v_add_f32_e32 v39, 1.0, v39
	v_rcp_f32_e32 v41, v32
	v_add_f32_e32 v32, 1.0, v34
	v_mul_f32_e32 v24, 0xbfb8aa3b, v24
	v_rcp_f32_e32 v38, v38
	v_rcp_f32_e32 v39, v39
	v_rcp_f32_e32 v42, v32
	v_exp_f32_e32 v24, v24
	v_mul_f32_e32 v25, 0xbfb8aa3b, v25
	v_cvt_pk_bf16_f32 v32, v36, v37
	v_lshl_add_u64 v[36:37], v[112:113], 0, v[48:49]
	v_exp_f32_e32 v25, v25
	v_lshlrev_b64 v[36:37], 9, v[36:37]
	v_lshl_add_u64 v[36:37], s[0:1], 0, v[36:37]
	v_mul_f32_e32 v28, 0xbfb8aa3b, v28
	v_mul_f32_e32 v29, 0xbfb8aa3b, v29
	v_cvt_pk_bf16_f32 v33, v38, v39
	v_cvt_pk_bf16_f32 v34, v40, v35
	v_cvt_pk_bf16_f32 v35, v41, v42
	v_lshl_add_u64 v[36:37], v[36:37], 0, v[114:115]
	v_exp_f32_e32 v28, v28
	v_exp_f32_e32 v29, v29
	v_add_f32_e32 v24, 1.0, v24
	v_lshl_add_u64 v[36:37], v[36:37], 0, v[228:229]
	global_store_dwordx4 v[36:37], v[32:35], off
	v_mul_f32_e32 v30, 0xbfb8aa3b, v30
	v_mul_f32_e32 v31, 0xbfb8aa3b, v31
	v_rcp_f32_e32 v34, v24
	v_add_f32_e32 v24, 1.0, v25
	v_mul_f32_e32 v25, 0xbfb8aa3b, v26
	v_exp_f32_e32 v25, v25
	v_mul_f32_e32 v26, 0xbfb8aa3b, v27
	v_exp_f32_e32 v30, v30
	v_exp_f32_e32 v31, v31
	v_exp_f32_e32 v26, v26
	v_add_f32_e32 v28, 1.0, v28
	v_add_f32_e32 v29, 1.0, v29
	v_rcp_f32_e32 v28, v28
	v_rcp_f32_e32 v29, v29
	v_rcp_f32_e32 v27, v24
	v_add_f32_e32 v24, 1.0, v25
	v_add_u32_e32 v32, 0xa0, v146
	v_add_f32_e32 v30, 1.0, v30
	v_add_f32_e32 v31, 1.0, v31
	v_rcp_f32_e32 v35, v24
	v_add_f32_e32 v24, 1.0, v26
	v_mul_f32_e32 v16, 0xbfb8aa3b, v16
	v_ashrrev_i32_e32 v33, 31, v32
	v_rcp_f32_e32 v30, v30
	v_rcp_f32_e32 v31, v31
	v_rcp_f32_e32 v36, v24
	v_exp_f32_e32 v16, v16
	v_mul_f32_e32 v17, 0xbfb8aa3b, v17
	v_cvt_pk_bf16_f32 v24, v28, v29
	v_lshl_add_u64 v[28:29], v[120:121], 0, v[32:33]
	v_exp_f32_e32 v17, v17
	v_lshlrev_b64 v[28:29], 9, v[28:29]
	v_lshl_add_u64 v[28:29], s[0:1], 0, v[28:29]
	v_mul_f32_e32 v20, 0xbfb8aa3b, v20
	v_mul_f32_e32 v21, 0xbfb8aa3b, v21
	v_cvt_pk_bf16_f32 v25, v30, v31
	v_cvt_pk_bf16_f32 v26, v34, v27
	v_cvt_pk_bf16_f32 v27, v35, v36
	v_lshl_add_u64 v[28:29], v[28:29], 0, v[136:137]
	v_exp_f32_e32 v20, v20
	v_exp_f32_e32 v21, v21
	v_add_f32_e32 v16, 1.0, v16
	v_lshl_add_u64 v[28:29], v[28:29], 0, v[226:227]
	global_store_dwordx4 v[28:29], v[24:27], off
	v_mul_f32_e32 v22, 0xbfb8aa3b, v22
	v_mul_f32_e32 v23, 0xbfb8aa3b, v23
	v_rcp_f32_e32 v24, v16
	v_add_f32_e32 v16, 1.0, v17
	v_mul_f32_e32 v17, 0xbfb8aa3b, v18
	v_exp_f32_e32 v17, v17
	v_mul_f32_e32 v18, 0xbfb8aa3b, v19
	v_exp_f32_e32 v22, v22
	v_exp_f32_e32 v23, v23
	v_exp_f32_e32 v18, v18
	v_add_f32_e32 v20, 1.0, v20
	v_add_f32_e32 v21, 1.0, v21
	v_rcp_f32_e32 v20, v20
	v_rcp_f32_e32 v21, v21
	v_rcp_f32_e32 v19, v16
	v_add_f32_e32 v16, 1.0, v17
	v_add_f32_e32 v22, 1.0, v22
	v_add_f32_e32 v23, 1.0, v23
	v_rcp_f32_e32 v25, v16
	v_add_f32_e32 v16, 1.0, v18
	v_mul_f32_e32 v8, 0xbfb8aa3b, v8
	v_rcp_f32_e32 v22, v22
	v_rcp_f32_e32 v23, v23
	v_rcp_f32_e32 v26, v16
	v_exp_f32_e32 v8, v8
	v_mul_f32_e32 v9, 0xbfb8aa3b, v9
	v_cvt_pk_bf16_f32 v16, v20, v21
	v_lshl_add_u64 v[20:21], v[112:113], 0, v[32:33]
	v_exp_f32_e32 v9, v9
	v_lshlrev_b64 v[20:21], 9, v[20:21]
	v_lshl_add_u64 v[20:21], s[0:1], 0, v[20:21]
	v_mul_f32_e32 v12, 0xbfb8aa3b, v12
	v_mul_f32_e32 v13, 0xbfb8aa3b, v13
	v_cvt_pk_bf16_f32 v17, v22, v23
	v_cvt_pk_bf16_f32 v18, v24, v19
	v_cvt_pk_bf16_f32 v19, v25, v26
	v_lshl_add_u64 v[20:21], v[20:21], 0, v[114:115]
	v_exp_f32_e32 v12, v12
	v_exp_f32_e32 v13, v13
	v_add_f32_e32 v8, 1.0, v8
	v_lshl_add_u64 v[20:21], v[20:21], 0, v[228:229]
	global_store_dwordx4 v[20:21], v[16:19], off
	v_mul_f32_e32 v14, 0xbfb8aa3b, v14
	v_mul_f32_e32 v15, 0xbfb8aa3b, v15
	v_rcp_f32_e32 v18, v8
	v_add_f32_e32 v8, 1.0, v9
	v_mul_f32_e32 v9, 0xbfb8aa3b, v10
	v_exp_f32_e32 v9, v9
	v_mul_f32_e32 v10, 0xbfb8aa3b, v11
	v_exp_f32_e32 v14, v14
	v_exp_f32_e32 v15, v15
	v_exp_f32_e32 v10, v10
	v_add_f32_e32 v12, 1.0, v12
	v_add_f32_e32 v13, 1.0, v13
	v_rcp_f32_e32 v12, v12
	v_rcp_f32_e32 v13, v13
	v_rcp_f32_e32 v11, v8
	v_add_f32_e32 v8, 1.0, v9
	v_add_u32_e32 v16, 0xb0, v146
	v_add_f32_e32 v14, 1.0, v14
	v_add_f32_e32 v15, 1.0, v15
	v_rcp_f32_e32 v19, v8
	v_add_f32_e32 v8, 1.0, v10
	v_mul_f32_e32 v0, 0xbfb8aa3b, v0
	v_ashrrev_i32_e32 v17, 31, v16
	v_rcp_f32_e32 v14, v14
	v_rcp_f32_e32 v15, v15
	v_rcp_f32_e32 v20, v8
	v_exp_f32_e32 v0, v0
	v_mul_f32_e32 v1, 0xbfb8aa3b, v1
	v_cvt_pk_bf16_f32 v8, v12, v13
	v_lshl_add_u64 v[12:13], v[120:121], 0, v[16:17]
	v_exp_f32_e32 v1, v1
	v_lshlrev_b64 v[12:13], 9, v[12:13]
	v_lshl_add_u64 v[12:13], s[0:1], 0, v[12:13]
	v_mul_f32_e32 v4, 0xbfb8aa3b, v4
	v_mul_f32_e32 v5, 0xbfb8aa3b, v5
	v_cvt_pk_bf16_f32 v9, v14, v15
	v_cvt_pk_bf16_f32 v10, v18, v11
	v_cvt_pk_bf16_f32 v11, v19, v20
	v_lshl_add_u64 v[12:13], v[12:13], 0, v[136:137]
	v_exp_f32_e32 v4, v4
	v_exp_f32_e32 v5, v5
	v_add_f32_e32 v0, 1.0, v0
	v_lshl_add_u64 v[12:13], v[12:13], 0, v[226:227]
	global_store_dwordx4 v[12:13], v[8:11], off
	v_mul_f32_e32 v6, 0xbfb8aa3b, v6
	v_mul_f32_e32 v7, 0xbfb8aa3b, v7
	v_rcp_f32_e32 v8, v0
	v_add_f32_e32 v0, 1.0, v1
	v_mul_f32_e32 v1, 0xbfb8aa3b, v2
	v_exp_f32_e32 v1, v1
	v_mul_f32_e32 v2, 0xbfb8aa3b, v3
	v_exp_f32_e32 v6, v6
	v_exp_f32_e32 v7, v7
	v_exp_f32_e32 v2, v2
	v_add_f32_e32 v4, 1.0, v4
	v_add_f32_e32 v5, 1.0, v5
	v_rcp_f32_e32 v4, v4
	v_rcp_f32_e32 v5, v5
	v_rcp_f32_e32 v3, v0
	v_add_f32_e32 v0, 1.0, v1
	v_add_f32_e32 v6, 1.0, v6
	v_add_f32_e32 v7, 1.0, v7
	v_rcp_f32_e32 v9, v0
	v_add_f32_e32 v0, 1.0, v2
	v_rcp_f32_e32 v6, v6
	v_rcp_f32_e32 v7, v7
	v_rcp_f32_e32 v10, v0
	v_cvt_pk_bf16_f32 v0, v4, v5
	v_lshl_add_u64 v[4:5], v[112:113], 0, v[16:17]
	v_lshlrev_b64 v[4:5], 9, v[4:5]
	v_lshl_add_u64 v[4:5], s[0:1], 0, v[4:5]
	v_cvt_pk_bf16_f32 v1, v6, v7
	v_cvt_pk_bf16_f32 v2, v8, v3
	v_cvt_pk_bf16_f32 v3, v9, v10
	v_lshl_add_u64 v[4:5], v[4:5], 0, v[114:115]
	s_and_b64 vcc, exec, s[2:3]
	s_mov_b32 s54, s14
	s_mov_b32 s22, s16
	s_mov_b64 s[26:27], s[20:21]
	s_mov_b64 s[24:25], s[18:19]
	v_lshl_add_u64 v[4:5], v[4:5], 0, v[228:229]
	global_store_dwordx4 v[4:5], v[0:3], off
	s_cbranch_vccz .LBB0_2265
	s_waitcnt vmcnt(0)
	s_cmpk_gt_u32 s30, 0xff
	s_cbranch_scc1 .LBB0_2276
	s_barrier

.LBB0_2286:
	s_ashr_i32 s25, s24, 31
	s_lshl_b64 s[26:27], s[24:25], 17
	v_mov_b64_e32 v[0:1], 0x100
	s_add_u32 s26, s12, s26
	v_cmp_lt_i64_e32 vcc, s[8:9], v[0:1]
	s_addc_u32 s27, s13, s27
	ds_read_b128 v[0:3], v188
	ds_read_b128 v[4:7], v188 offset:1024
	ds_read_b128 v[8:11], v188 offset:2048
	ds_read_b128 v[12:15], v188 offset:3072
	s_and_b64 s[28:29], vcc, exec
	s_cselect_b32 s41, s27, s35
	s_cselect_b32 s40, s26, s34
	s_ashr_i32 s23, s22, 31
	s_lshl_b64 s[28:29], s[22:23], 17
	s_add_u32 s28, s2, s28
	s_addc_u32 s29, s3, s29
	s_and_b64 s[38:39], vcc, exec
	s_cselect_b32 s39, s29, s37
	s_cselect_b32 s38, s28, s36
	s_add_u32 s62, s34, 0x10080
	s_addc_u32 s63, s35, 0
	s_add_i32 s25, s44, 0xc000
	v_lshl_add_u64 v[48:49], s[62:63], 0, v[160:161]
	s_mov_b32 m0, s25
	s_add_i32 s23, s44, 0xe000
	ds_read_b128 v[16:19], v189
	ds_read_b128 v[20:23], v189 offset:1024
	ds_read_b128 v[24:27], v189 offset:2048
	ds_read_b128 v[28:31], v189 offset:3072
	ds_read_b128 v[32:35], v189 offset:4096
	ds_read_b128 v[36:39], v189 offset:5120
	ds_read_b128 v[40:43], v189 offset:6144
	ds_read_b128 v[44:47], v189 offset:7168
	global_load_lds_dwordx4 v[48:49], off
	v_lshl_add_u64 v[48:49], s[62:63], 0, v[164:165]
	s_mov_b32 m0, s23
	s_nop 0
	global_load_lds_dwordx4 v[48:49], off
	s_waitcnt lgkmcnt(8)
	s_barrier
	s_waitcnt lgkmcnt(0)
	s_setprio 1
	s_waitcnt lgkmcnt(0)
	v_mfma_f32_16x16x32_bf16 v[48:51], v[0:3], v[16:19], 0
	v_mfma_f32_16x16x32_bf16 v[52:55], v[8:11], v[16:19], 0
	v_mfma_f32_16x16x32_bf16 v[56:59], v[0:3], v[24:27], 0
	v_mfma_f32_16x16x32_bf16 v[60:63], v[8:11], v[24:27], 0
	v_mfma_f32_16x16x32_bf16 v[64:67], v[0:3], v[32:35], 0
	v_mfma_f32_16x16x32_bf16 v[68:71], v[8:11], v[32:35], 0
	v_mfma_f32_16x16x32_bf16 v[72:75], v[0:3], v[40:43], 0
	v_mfma_f32_16x16x32_bf16 v[76:79], v[8:11], v[40:43], 0
	v_mfma_f32_16x16x32_bf16 v[48:51], v[4:7], v[20:23], v[48:51]
	v_mfma_f32_16x16x32_bf16 v[52:55], v[12:15], v[20:23], v[52:55]
	v_mfma_f32_16x16x32_bf16 v[56:59], v[4:7], v[28:31], v[56:59]
	v_mfma_f32_16x16x32_bf16 v[60:63], v[12:15], v[28:31], v[60:63]
	v_mfma_f32_16x16x32_bf16 v[64:67], v[4:7], v[36:39], v[64:67]
	v_mfma_f32_16x16x32_bf16 v[68:71], v[12:15], v[36:39], v[68:71]
	v_mfma_f32_16x16x32_bf16 v[72:75], v[4:7], v[44:47], v[72:75]
	v_mfma_f32_16x16x32_bf16 v[76:79], v[12:15], v[44:47], v[76:79]
	s_setprio 0
	s_barrier
	v_lshl_add_u64 v[186:187], s[36:37], 0, v[162:163]
	s_mov_b32 m0, s31
	v_lshl_add_u64 v[96:97], v[186:187], 0, s[18:19]
	v_lshl_add_u64 v[214:215], s[36:37], 0, v[166:167]
	ds_read_b128 v[80:83], v190
	ds_read_b128 v[84:87], v190 offset:1024
	ds_read_b128 v[88:91], v190 offset:2048
	ds_read_b128 v[92:95], v190 offset:3072
	global_load_lds_dwordx4 v[96:97], off
	v_lshl_add_u64 v[96:97], v[214:215], 0, s[18:19]
	s_mov_b32 m0, s43
	s_nop 0
	global_load_lds_dwordx4 v[96:97], off
	s_barrier
	s_waitcnt lgkmcnt(0)
	s_setprio 1
	s_waitcnt lgkmcnt(0)
	v_mfma_f32_16x16x32_bf16 v[96:99], v[80:83], v[16:19], 0
	v_mfma_f32_16x16x32_bf16 v[16:19], v[88:91], v[16:19], 0
	v_mfma_f32_16x16x32_bf16 v[96:99], v[84:87], v[20:23], v[96:99]
	v_mfma_f32_16x16x32_bf16 v[16:19], v[92:95], v[20:23], v[16:19]
	v_mfma_f32_16x16x32_bf16 v[20:23], v[80:83], v[24:27], 0
	v_mfma_f32_16x16x32_bf16 v[24:27], v[88:91], v[24:27], 0
	v_mfma_f32_16x16x32_bf16 v[20:23], v[84:87], v[28:31], v[20:23]
	v_mfma_f32_16x16x32_bf16 v[24:27], v[92:95], v[28:31], v[24:27]
	v_mfma_f32_16x16x32_bf16 v[28:31], v[80:83], v[32:35], 0
	v_mfma_f32_16x16x32_bf16 v[32:35], v[88:91], v[32:35], 0
	v_mfma_f32_16x16x32_bf16 v[28:31], v[84:87], v[36:39], v[28:31]
	v_mfma_f32_16x16x32_bf16 v[32:35], v[92:95], v[36:39], v[32:35]
	v_mfma_f32_16x16x32_bf16 v[36:39], v[80:83], v[40:43], 0
	v_mfma_f32_16x16x32_bf16 v[40:43], v[88:91], v[40:43], 0
	v_mfma_f32_16x16x32_bf16 v[36:39], v[84:87], v[44:47], v[36:39]
	v_mfma_f32_16x16x32_bf16 v[40:43], v[92:95], v[44:47], v[40:43]
	s_setprio 0
	v_lshl_add_u64 v[216:217], s[34:35], 0, v[160:161]
	s_mov_b32 m0, s44
	v_lshl_add_u64 v[128:129], v[216:217], 0, s[18:19]
	v_lshl_add_u64 v[218:219], s[34:35], 0, v[164:165]
	s_barrier
	ds_read_b128 v[44:47], v189 offset:16384
	ds_read_b128 v[100:103], v189 offset:17408
	ds_read_b128 v[104:107], v189 offset:18432
	ds_read_b128 v[108:111], v189 offset:19456
	ds_read_b128 v[112:115], v189 offset:20480
	ds_read_b128 v[116:119], v189 offset:21504
	ds_read_b128 v[120:123], v189 offset:22528
	ds_read_b128 v[124:127], v189 offset:23552
	global_load_lds_dwordx4 v[128:129], off
	v_lshl_add_u64 v[128:129], v[218:219], 0, s[18:19]
	s_mov_b32 m0, s45
	s_nop 0
	global_load_lds_dwordx4 v[128:129], off
	s_barrier
	s_waitcnt lgkmcnt(0)
	s_setprio 1
	s_waitcnt lgkmcnt(0)
	v_mfma_f32_16x16x32_bf16 v[128:131], v[0:3], v[44:47], 0
	v_mfma_f32_16x16x32_bf16 v[136:139], v[0:3], v[104:107], 0
	v_mfma_f32_16x16x32_bf16 v[144:147], v[0:3], v[112:115], 0
	v_mfma_f32_16x16x32_bf16 v[0:3], v[0:3], v[120:123], 0
	v_mfma_f32_16x16x32_bf16 v[128:131], v[4:7], v[100:103], v[128:131]
	v_mfma_f32_16x16x32_bf16 v[132:135], v[8:11], v[44:47], 0
	v_mfma_f32_16x16x32_bf16 v[136:139], v[4:7], v[108:111], v[136:139]
	v_mfma_f32_16x16x32_bf16 v[140:143], v[8:11], v[104:107], 0
	v_mfma_f32_16x16x32_bf16 v[144:147], v[4:7], v[116:119], v[144:147]
	v_mfma_f32_16x16x32_bf16 v[148:151], v[8:11], v[112:115], 0
	v_mfma_f32_16x16x32_bf16 v[0:3], v[4:7], v[124:127], v[0:3]
	v_mfma_f32_16x16x32_bf16 v[4:7], v[8:11], v[120:123], 0
	v_mfma_f32_16x16x32_bf16 v[132:135], v[12:15], v[100:103], v[132:135]
	v_mfma_f32_16x16x32_bf16 v[140:143], v[12:15], v[108:111], v[140:143]
	v_mfma_f32_16x16x32_bf16 v[148:151], v[12:15], v[116:119], v[148:151]
	v_mfma_f32_16x16x32_bf16 v[4:7], v[12:15], v[124:127], v[4:7]
	s_setprio 0
	s_barrier
	s_add_u32 s62, s36, 0x10100
	s_addc_u32 s63, s37, 0
	s_mov_b32 m0, s46
	v_lshl_add_u64 v[8:9], s[62:63], 0, v[162:163]
	global_load_lds_dwordx4 v[8:9], off
	v_lshl_add_u64 v[8:9], s[62:63], 0, v[166:167]
	s_mov_b32 m0, s47
	s_nop 0
	global_load_lds_dwordx4 v[8:9], off
	s_waitcnt vmcnt(6)
	s_barrier
	s_setprio 1
	v_mfma_f32_16x16x32_bf16 v[8:11], v[80:83], v[44:47], 0
	v_mfma_f32_16x16x32_bf16 v[12:15], v[88:91], v[44:47], 0
	v_mfma_f32_16x16x32_bf16 v[8:11], v[84:87], v[100:103], v[8:11]
	v_mfma_f32_16x16x32_bf16 v[12:15], v[92:95], v[100:103], v[12:15]
	v_mfma_f32_16x16x32_bf16 v[44:47], v[80:83], v[104:107], 0
	v_mfma_f32_16x16x32_bf16 v[100:103], v[88:91], v[104:107], 0
	v_mfma_f32_16x16x32_bf16 v[104:107], v[80:83], v[112:115], 0
	v_mfma_f32_16x16x32_bf16 v[80:83], v[80:83], v[120:123], 0
	v_mfma_f32_16x16x32_bf16 v[44:47], v[84:87], v[108:111], v[44:47]
	v_mfma_f32_16x16x32_bf16 v[100:103], v[92:95], v[108:111], v[100:103]
	v_mfma_f32_16x16x32_bf16 v[104:107], v[84:87], v[116:119], v[104:107]
	v_mfma_f32_16x16x32_bf16 v[108:111], v[88:91], v[112:115], 0
	v_mfma_f32_16x16x32_bf16 v[80:83], v[84:87], v[124:127], v[80:83]
	v_mfma_f32_16x16x32_bf16 v[84:87], v[88:91], v[120:123], 0
	v_mfma_f32_16x16x32_bf16 v[108:111], v[92:95], v[116:119], v[108:111]
	v_mfma_f32_16x16x32_bf16 v[84:87], v[92:95], v[124:127], v[84:87]
	s_setprio 0
	s_barrier
	ds_read_b128 v[88:91], v191
	ds_read_b128 v[92:95], v191 offset:1024
	ds_read_b128 v[112:115], v191 offset:2048
	ds_read_b128 v[116:119], v191 offset:3072
	s_add_u32 s62, s34, 0x10100
	s_addc_u32 s63, s35, 0
	s_mov_b32 m0, s48
	v_lshl_add_u64 v[198:199], s[62:63], 0, v[160:161]
	ds_read_b128 v[120:123], v189 offset:32768
	ds_read_b128 v[124:127], v189 offset:33792
	ds_read_b128 v[152:155], v189 offset:34816
	ds_read_b128 v[156:159], v189 offset:35840
	ds_read_b128 v[174:177], v189 offset:36864
	ds_read_b128 v[178:181], v189 offset:37888
	ds_read_b128 v[182:185], v189 offset:38912
	ds_read_b128 v[194:197], v189 offset:39936
	global_load_lds_dwordx4 v[198:199], off
	v_lshl_add_u64 v[198:199], s[62:63], 0, v[164:165]
	s_mov_b32 m0, s49
	s_nop 0
	global_load_lds_dwordx4 v[198:199], off
	s_waitcnt lgkmcnt(8)
	s_barrier
	s_waitcnt lgkmcnt(0)
	s_setprio 1
	s_waitcnt lgkmcnt(0)
	v_mfma_f32_16x16x32_bf16 v[48:51], v[88:91], v[120:123], v[48:51]
	v_mfma_f32_16x16x32_bf16 v[52:55], v[112:115], v[120:123], v[52:55]
	v_mfma_f32_16x16x32_bf16 v[56:59], v[88:91], v[152:155], v[56:59]
	v_mfma_f32_16x16x32_bf16 v[60:63], v[112:115], v[152:155], v[60:63]
	v_mfma_f32_16x16x32_bf16 v[64:67], v[88:91], v[174:177], v[64:67]
	v_mfma_f32_16x16x32_bf16 v[68:71], v[112:115], v[174:177], v[68:71]
	v_mfma_f32_16x16x32_bf16 v[72:75], v[88:91], v[182:185], v[72:75]
	v_mfma_f32_16x16x32_bf16 v[76:79], v[112:115], v[182:185], v[76:79]
	v_mfma_f32_16x16x32_bf16 v[48:51], v[92:95], v[124:127], v[48:51]
	v_mfma_f32_16x16x32_bf16 v[52:55], v[116:119], v[124:127], v[52:55]
	v_mfma_f32_16x16x32_bf16 v[56:59], v[92:95], v[156:159], v[56:59]
	v_mfma_f32_16x16x32_bf16 v[60:63], v[116:119], v[156:159], v[60:63]
	v_mfma_f32_16x16x32_bf16 v[64:67], v[92:95], v[178:181], v[64:67]
	v_mfma_f32_16x16x32_bf16 v[68:71], v[116:119], v[178:181], v[68:71]
	v_mfma_f32_16x16x32_bf16 v[72:75], v[92:95], v[194:197], v[72:75]
	v_mfma_f32_16x16x32_bf16 v[76:79], v[116:119], v[194:197], v[76:79]
	s_setprio 0
	s_barrier
	s_mov_b32 m0, s52
	v_lshl_add_u64 v[186:187], v[186:187], 0, s[20:21]
	ds_read_b128 v[198:201], v192
	ds_read_b128 v[202:205], v192 offset:1024
	ds_read_b128 v[206:209], v192 offset:2048
	ds_read_b128 v[210:213], v192 offset:3072
	global_load_lds_dwordx4 v[186:187], off
	v_lshl_add_u64 v[186:187], v[214:215], 0, s[20:21]
	s_mov_b32 m0, s53
	s_nop 0
	global_load_lds_dwordx4 v[186:187], off
	s_barrier
	s_waitcnt lgkmcnt(0)
	s_setprio 1
	s_waitcnt lgkmcnt(0)
	v_mfma_f32_16x16x32_bf16 v[96:99], v[198:201], v[120:123], v[96:99]
	v_mfma_f32_16x16x32_bf16 v[16:19], v[206:209], v[120:123], v[16:19]
	v_mfma_f32_16x16x32_bf16 v[20:23], v[198:201], v[152:155], v[20:23]
	v_mfma_f32_16x16x32_bf16 v[24:27], v[206:209], v[152:155], v[24:27]
	v_mfma_f32_16x16x32_bf16 v[28:31], v[198:201], v[174:177], v[28:31]
	v_mfma_f32_16x16x32_bf16 v[32:35], v[206:209], v[174:177], v[32:35]
	v_mfma_f32_16x16x32_bf16 v[36:39], v[198:201], v[182:185], v[36:39]
	v_mfma_f32_16x16x32_bf16 v[40:43], v[206:209], v[182:185], v[40:43]
	v_mfma_f32_16x16x32_bf16 v[96:99], v[202:205], v[124:127], v[96:99]
	v_mfma_f32_16x16x32_bf16 v[16:19], v[210:213], v[124:127], v[16:19]
	v_mfma_f32_16x16x32_bf16 v[20:23], v[202:205], v[156:159], v[20:23]
	v_mfma_f32_16x16x32_bf16 v[24:27], v[210:213], v[156:159], v[24:27]
	v_mfma_f32_16x16x32_bf16 v[28:31], v[202:205], v[178:181], v[28:31]
	v_mfma_f32_16x16x32_bf16 v[32:35], v[210:213], v[178:181], v[32:35]
	v_mfma_f32_16x16x32_bf16 v[36:39], v[202:205], v[194:197], v[36:39]
	v_mfma_f32_16x16x32_bf16 v[40:43], v[210:213], v[194:197], v[40:43]
	s_setprio 0
	s_mov_b32 m0, s54
	v_lshl_add_u64 v[186:187], v[216:217], 0, s[20:21]
	s_barrier
	ds_read_b128 v[120:123], v189 offset:49152
	ds_read_b128 v[124:127], v189 offset:50176
	ds_read_b128 v[152:155], v189 offset:51200
	ds_read_b128 v[156:159], v189 offset:52224
	ds_read_b128 v[174:177], v189 offset:53248
	ds_read_b128 v[178:181], v189 offset:54272
	ds_read_b128 v[182:185], v189 offset:55296
	ds_read_b128 v[194:197], v189 offset:56320
	global_load_lds_dwordx4 v[186:187], off
	v_lshl_add_u64 v[186:187], v[218:219], 0, s[20:21]
	s_mov_b32 m0, s55
	s_nop 0
	global_load_lds_dwordx4 v[186:187], off
	s_barrier
	s_waitcnt lgkmcnt(0)
	s_setprio 1
	s_waitcnt lgkmcnt(0)
	v_mfma_f32_16x16x32_bf16 v[128:131], v[88:91], v[120:123], v[128:131]
	v_mfma_f32_16x16x32_bf16 v[132:135], v[112:115], v[120:123], v[132:135]
	v_mfma_f32_16x16x32_bf16 v[136:139], v[88:91], v[152:155], v[136:139]
	v_mfma_f32_16x16x32_bf16 v[140:143], v[112:115], v[152:155], v[140:143]
	v_mfma_f32_16x16x32_bf16 v[144:147], v[88:91], v[174:177], v[144:147]
	v_mfma_f32_16x16x32_bf16 v[148:151], v[112:115], v[174:177], v[148:151]
	v_mfma_f32_16x16x32_bf16 v[0:3], v[88:91], v[182:185], v[0:3]
	v_mfma_f32_16x16x32_bf16 v[4:7], v[112:115], v[182:185], v[4:7]
	v_mfma_f32_16x16x32_bf16 v[128:131], v[92:95], v[124:127], v[128:131]
	v_mfma_f32_16x16x32_bf16 v[132:135], v[116:119], v[124:127], v[132:135]
	v_mfma_f32_16x16x32_bf16 v[136:139], v[92:95], v[156:159], v[136:139]
	v_mfma_f32_16x16x32_bf16 v[140:143], v[116:119], v[156:159], v[140:143]
	v_mfma_f32_16x16x32_bf16 v[144:147], v[92:95], v[178:181], v[144:147]
	v_mfma_f32_16x16x32_bf16 v[148:151], v[116:119], v[178:181], v[148:151]
	v_mfma_f32_16x16x32_bf16 v[0:3], v[92:95], v[194:197], v[0:3]
	v_mfma_f32_16x16x32_bf16 v[4:7], v[116:119], v[194:197], v[4:7]
	s_setprio 0
	s_barrier
	s_add_u32 s36, s36, 0x10180
	s_addc_u32 s37, s37, 0
	s_mov_b32 m0, s56
	v_lshl_add_u64 v[88:89], s[36:37], 0, v[162:163]
	global_load_lds_dwordx4 v[88:89], off
	v_lshl_add_u64 v[88:89], s[36:37], 0, v[166:167]
	s_mov_b32 m0, s57
	s_nop 0
	global_load_lds_dwordx4 v[88:89], off
	s_waitcnt vmcnt(6)
	s_barrier
	s_setprio 1
	v_mfma_f32_16x16x32_bf16 v[8:11], v[198:201], v[120:123], v[8:11]
	v_mfma_f32_16x16x32_bf16 v[12:15], v[206:209], v[120:123], v[12:15]
	v_mfma_f32_16x16x32_bf16 v[44:47], v[198:201], v[152:155], v[44:47]
	v_mfma_f32_16x16x32_bf16 v[88:91], v[206:209], v[152:155], v[100:103]
	v_mfma_f32_16x16x32_bf16 v[92:95], v[198:201], v[174:177], v[104:107]
	v_mfma_f32_16x16x32_bf16 v[100:103], v[206:209], v[174:177], v[108:111]
	v_mfma_f32_16x16x32_bf16 v[80:83], v[198:201], v[182:185], v[80:83]
	v_mfma_f32_16x16x32_bf16 v[84:87], v[206:209], v[182:185], v[84:87]
	v_mfma_f32_16x16x32_bf16 v[8:11], v[202:205], v[124:127], v[8:11]
	v_mfma_f32_16x16x32_bf16 v[12:15], v[210:213], v[124:127], v[12:15]
	v_mfma_f32_16x16x32_bf16 v[44:47], v[202:205], v[156:159], v[44:47]
	v_mfma_f32_16x16x32_bf16 v[88:91], v[210:213], v[156:159], v[88:91]
	v_mfma_f32_16x16x32_bf16 v[92:95], v[202:205], v[178:181], v[92:95]
	v_mfma_f32_16x16x32_bf16 v[100:103], v[210:213], v[178:181], v[100:103]
	v_mfma_f32_16x16x32_bf16 v[80:83], v[202:205], v[194:197], v[80:83]
	v_mfma_f32_16x16x32_bf16 v[84:87], v[210:213], v[194:197], v[84:87]
	s_setprio 0
	s_barrier
	ds_read_b128 v[104:107], v188
	ds_read_b128 v[108:111], v188 offset:1024
	ds_read_b128 v[112:115], v188 offset:2048
	ds_read_b128 v[116:119], v188 offset:3072
	s_add_u32 s34, s34, 0x10180
	s_addc_u32 s35, s35, 0
	s_mov_b32 m0, s25
	v_lshl_add_u64 v[186:187], s[34:35], 0, v[160:161]
	ds_read_b128 v[120:123], v189
	ds_read_b128 v[124:127], v189 offset:1024
	ds_read_b128 v[152:155], v189 offset:2048
	ds_read_b128 v[156:159], v189 offset:3072
	ds_read_b128 v[174:177], v189 offset:4096
	ds_read_b128 v[178:181], v189 offset:5120
	ds_read_b128 v[182:185], v189 offset:6144
	ds_read_b128 v[194:197], v189 offset:7168
	global_load_lds_dwordx4 v[186:187], off
	v_lshl_add_u64 v[186:187], s[34:35], 0, v[164:165]
	s_mov_b32 m0, s23
	s_nop 0
	global_load_lds_dwordx4 v[186:187], off
	s_waitcnt lgkmcnt(8)
	s_barrier
	s_waitcnt lgkmcnt(0)
	s_setprio 1
	s_waitcnt lgkmcnt(0)
	v_mfma_f32_16x16x32_bf16 v[48:51], v[104:107], v[120:123], v[48:51]
	v_mfma_f32_16x16x32_bf16 v[52:55], v[112:115], v[120:123], v[52:55]
	v_mfma_f32_16x16x32_bf16 v[56:59], v[104:107], v[152:155], v[56:59]
	v_mfma_f32_16x16x32_bf16 v[60:63], v[112:115], v[152:155], v[60:63]
	v_mfma_f32_16x16x32_bf16 v[64:67], v[104:107], v[174:177], v[64:67]
	v_mfma_f32_16x16x32_bf16 v[68:71], v[112:115], v[174:177], v[68:71]
	v_mfma_f32_16x16x32_bf16 v[72:75], v[104:107], v[182:185], v[72:75]
	v_mfma_f32_16x16x32_bf16 v[76:79], v[112:115], v[182:185], v[76:79]
	v_mfma_f32_16x16x32_bf16 v[48:51], v[108:111], v[124:127], v[48:51]
	v_mfma_f32_16x16x32_bf16 v[52:55], v[116:119], v[124:127], v[52:55]
	v_mfma_f32_16x16x32_bf16 v[56:59], v[108:111], v[156:159], v[56:59]
	v_mfma_f32_16x16x32_bf16 v[60:63], v[116:119], v[156:159], v[60:63]
	v_mfma_f32_16x16x32_bf16 v[64:67], v[108:111], v[178:181], v[64:67]
	v_mfma_f32_16x16x32_bf16 v[68:71], v[116:119], v[178:181], v[68:71]
	v_mfma_f32_16x16x32_bf16 v[72:75], v[108:111], v[194:197], v[72:75]
	v_mfma_f32_16x16x32_bf16 v[198:201], v[116:119], v[194:197], v[76:79]
	s_setprio 0
	s_barrier
	s_mov_b32 m0, s31
	v_lshl_add_u64 v[186:187], s[38:39], 0, v[162:163]
	ds_read_b128 v[76:79], v190
	ds_read_b128 v[202:205], v190 offset:1024
	ds_read_b128 v[206:209], v190 offset:2048
	ds_read_b128 v[210:213], v190 offset:3072
	global_load_lds_dwordx4 v[186:187], off
	v_lshl_add_u64 v[250:251], s[38:39], 0, v[166:167]
	s_mov_b32 m0, s43
	s_nop 0
	global_load_lds_dwordx4 v[250:251], off
	s_barrier
	s_waitcnt lgkmcnt(0)
	s_setprio 1
	s_waitcnt lgkmcnt(0)
	v_mfma_f32_16x16x32_bf16 v[96:99], v[76:79], v[120:123], v[96:99]
	v_mfma_f32_16x16x32_bf16 v[16:19], v[206:209], v[120:123], v[16:19]
	v_mfma_f32_16x16x32_bf16 v[20:23], v[76:79], v[152:155], v[20:23]
	v_mfma_f32_16x16x32_bf16 v[24:27], v[206:209], v[152:155], v[24:27]
	v_mfma_f32_16x16x32_bf16 v[28:31], v[76:79], v[174:177], v[28:31]
	v_mfma_f32_16x16x32_bf16 v[32:35], v[206:209], v[174:177], v[32:35]
	v_mfma_f32_16x16x32_bf16 v[36:39], v[76:79], v[182:185], v[36:39]
	v_mfma_f32_16x16x32_bf16 v[40:43], v[206:209], v[182:185], v[40:43]
	v_mfma_f32_16x16x32_bf16 v[96:99], v[202:205], v[124:127], v[96:99]
	v_mfma_f32_16x16x32_bf16 v[16:19], v[210:213], v[124:127], v[16:19]
	v_mfma_f32_16x16x32_bf16 v[20:23], v[202:205], v[156:159], v[20:23]
	v_mfma_f32_16x16x32_bf16 v[24:27], v[210:213], v[156:159], v[24:27]
	v_mfma_f32_16x16x32_bf16 v[28:31], v[202:205], v[178:181], v[28:31]
	v_mfma_f32_16x16x32_bf16 v[32:35], v[210:213], v[178:181], v[32:35]
	v_mfma_f32_16x16x32_bf16 v[36:39], v[202:205], v[194:197], v[36:39]
	v_mfma_f32_16x16x32_bf16 v[40:43], v[210:213], v[194:197], v[40:43]
	s_setprio 0
	s_mov_b32 m0, s44
	v_lshl_add_u64 v[252:253], s[40:41], 0, v[160:161]
	s_barrier
	ds_read_b128 v[120:123], v189 offset:16384
	ds_read_b128 v[124:127], v189 offset:17408
	ds_read_b128 v[152:155], v189 offset:18432
	ds_read_b128 v[156:159], v189 offset:19456
	ds_read_b128 v[174:177], v189 offset:20480
	ds_read_b128 v[178:181], v189 offset:21504
	ds_read_b128 v[182:185], v189 offset:22528
	ds_read_b128 v[194:197], v189 offset:23552
	global_load_lds_dwordx4 v[252:253], off
	v_lshl_add_u64 v[170:171], s[40:41], 0, v[164:165]
	s_mov_b32 m0, s45
	s_nop 0
	global_load_lds_dwordx4 v[170:171], off
	s_barrier
	s_waitcnt lgkmcnt(0)
	s_setprio 1
	s_waitcnt lgkmcnt(0)
	v_mfma_f32_16x16x32_bf16 v[136:139], v[104:107], v[152:155], v[136:139]
	v_mfma_f32_16x16x32_bf16 v[214:217], v[108:111], v[156:159], v[136:139]
	v_mfma_f32_16x16x32_bf16 v[136:139], v[112:115], v[152:155], v[140:143]
	v_mfma_f32_16x16x32_bf16 v[218:221], v[116:119], v[156:159], v[136:139]
	v_mfma_f32_16x16x32_bf16 v[136:139], v[104:107], v[174:177], v[144:147]
	v_mfma_f32_16x16x32_bf16 v[128:131], v[104:107], v[120:123], v[128:131]
	v_mfma_f32_16x16x32_bf16 v[132:135], v[112:115], v[120:123], v[132:135]
	v_mfma_f32_16x16x32_bf16 v[222:225], v[108:111], v[178:181], v[136:139]
	v_mfma_f32_16x16x32_bf16 v[136:139], v[112:115], v[174:177], v[148:151]
	v_mfma_f32_16x16x32_bf16 v[0:3], v[104:107], v[182:185], v[0:3]
	v_mfma_f32_16x16x32_bf16 v[4:7], v[112:115], v[182:185], v[4:7]
	v_mfma_f32_16x16x32_bf16 v[128:131], v[108:111], v[124:127], v[128:131]
	v_mfma_f32_16x16x32_bf16 v[132:135], v[116:119], v[124:127], v[132:135]
	v_mfma_f32_16x16x32_bf16 v[148:151], v[116:119], v[178:181], v[136:139]
	v_mfma_f32_16x16x32_bf16 v[0:3], v[108:111], v[194:197], v[0:3]
	v_mfma_f32_16x16x32_bf16 v[4:7], v[116:119], v[194:197], v[4:7]
	s_setprio 0
	s_barrier
	s_add_u32 s34, s38, 0x10000
	s_addc_u32 s35, s39, 0
	s_mov_b32 m0, s46
	v_lshl_add_u64 v[104:105], s[34:35], 0, v[162:163]
	global_load_lds_dwordx4 v[104:105], off
	v_lshl_add_u64 v[104:105], s[34:35], 0, v[166:167]
	s_mov_b32 m0, s47
	s_nop 0
	global_load_lds_dwordx4 v[104:105], off
	s_waitcnt vmcnt(6)
	s_barrier
	s_setprio 1
	v_mfma_f32_16x16x32_bf16 v[12:15], v[206:209], v[120:123], v[12:15]
	v_mfma_f32_16x16x32_bf16 v[8:11], v[76:79], v[120:123], v[8:11]
	v_mfma_f32_16x16x32_bf16 v[120:123], v[210:213], v[124:127], v[12:15]
	v_mfma_f32_16x16x32_bf16 v[12:15], v[76:79], v[152:155], v[44:47]
	v_mfma_f32_16x16x32_bf16 v[8:11], v[202:205], v[124:127], v[8:11]
	v_mfma_f32_16x16x32_bf16 v[124:127], v[202:205], v[156:159], v[12:15]
	v_mfma_f32_16x16x32_bf16 v[12:15], v[206:209], v[152:155], v[88:91]
	v_mfma_f32_16x16x32_bf16 v[152:155], v[210:213], v[156:159], v[12:15]
	v_mfma_f32_16x16x32_bf16 v[12:15], v[76:79], v[174:177], v[92:95]
	v_mfma_f32_16x16x32_bf16 v[226:229], v[202:205], v[178:181], v[12:15]
	v_mfma_f32_16x16x32_bf16 v[12:15], v[206:209], v[174:177], v[100:103]
	v_mfma_f32_16x16x32_bf16 v[100:103], v[210:213], v[178:181], v[12:15]
	v_mfma_f32_16x16x32_bf16 v[12:15], v[76:79], v[182:185], v[80:83]
	v_mfma_f32_16x16x32_bf16 v[174:177], v[202:205], v[194:197], v[12:15]
	v_mfma_f32_16x16x32_bf16 v[12:15], v[206:209], v[182:185], v[84:87]
	v_mfma_f32_16x16x32_bf16 v[178:181], v[210:213], v[194:197], v[12:15]
	s_setprio 0
	s_barrier
	s_nop 4
	ds_read_b128 v[12:15], v191
	ds_read_b128 v[182:185], v191 offset:1024
	ds_read_b128 v[194:197], v191 offset:2048
	ds_read_b128 v[202:205], v191 offset:3072
	s_add_u32 s34, s40, 0x10000
	s_addc_u32 s35, s41, 0
	s_mov_b32 m0, s48
	v_lshl_add_u64 v[76:77], s[34:35], 0, v[160:161]
	ds_read_b128 v[44:47], v189 offset:32768
	ds_read_b128 v[80:83], v189 offset:33792
	ds_read_b128 v[88:91], v189 offset:34816
	ds_read_b128 v[104:107], v189 offset:35840
	ds_read_b128 v[206:209], v189 offset:36864
	ds_read_b128 v[210:213], v189 offset:37888
	ds_read_b128 v[230:233], v189 offset:38912
	ds_read_b128 v[234:237], v189 offset:39936
	global_load_lds_dwordx4 v[76:77], off
	v_lshl_add_u64 v[76:77], s[34:35], 0, v[164:165]
	s_mov_b32 m0, s49
	s_nop 0
	global_load_lds_dwordx4 v[76:77], off
	s_waitcnt lgkmcnt(8)
	s_barrier
	s_waitcnt lgkmcnt(0)
	s_setprio 1
	s_waitcnt lgkmcnt(0)
	v_mfma_f32_16x16x32_bf16 v[48:51], v[12:15], v[44:47], v[48:51]
	v_mfma_f32_16x16x32_bf16 v[156:159], v[182:185], v[80:83], v[48:51]
	v_mfma_f32_16x16x32_bf16 v[48:51], v[194:197], v[44:47], v[52:55]
	v_mfma_f32_16x16x32_bf16 v[140:143], v[202:205], v[80:83], v[48:51]
	v_mfma_f32_16x16x32_bf16 v[48:51], v[12:15], v[88:91], v[56:59]
	v_mfma_f32_16x16x32_bf16 v[116:119], v[182:185], v[104:107], v[48:51]
	v_mfma_f32_16x16x32_bf16 v[48:51], v[194:197], v[88:91], v[60:63]
	v_mfma_f32_16x16x32_bf16 v[108:111], v[202:205], v[104:107], v[48:51]
	v_mfma_f32_16x16x32_bf16 v[48:51], v[12:15], v[206:209], v[64:67]
	v_mfma_f32_16x16x32_bf16 v[92:95], v[182:185], v[210:213], v[48:51]
	v_mfma_f32_16x16x32_bf16 v[48:51], v[194:197], v[206:209], v[68:71]
	v_mfma_f32_16x16x32_bf16 v[84:87], v[202:205], v[210:213], v[48:51]
	v_mfma_f32_16x16x32_bf16 v[48:51], v[12:15], v[230:233], v[72:75]
	v_mfma_f32_16x16x32_bf16 v[76:79], v[182:185], v[234:237], v[48:51]
	v_mfma_f32_16x16x32_bf16 v[48:51], v[194:197], v[230:233], v[198:201]
	v_mfma_f32_16x16x32_bf16 v[68:71], v[202:205], v[234:237], v[48:51]
	s_setprio 0
	s_barrier
	s_mov_b32 m0, s52
	s_nop 3
	v_lshl_add_u64 v[48:49], v[186:187], 0, s[16:17]
	ds_read_b128 v[198:201], v192
	ds_read_b128 v[238:241], v192 offset:1024
	ds_read_b128 v[242:245], v192 offset:2048
	ds_read_b128 v[246:249], v192 offset:3072
	global_load_lds_dwordx4 v[48:49], off
	v_lshl_add_u64 v[48:49], v[250:251], 0, s[16:17]
	s_mov_b32 m0, s53
	s_nop 0
	global_load_lds_dwordx4 v[48:49], off
	s_barrier
	s_waitcnt lgkmcnt(0)
	s_setprio 1
	s_waitcnt lgkmcnt(0)
	v_mfma_f32_16x16x32_bf16 v[16:19], v[242:245], v[44:47], v[16:19]
	v_mfma_f32_16x16x32_bf16 v[136:139], v[246:249], v[80:83], v[16:19]
	v_mfma_f32_16x16x32_bf16 v[16:19], v[198:201], v[88:91], v[20:23]
	v_mfma_f32_16x16x32_bf16 v[112:115], v[238:241], v[104:107], v[16:19]
	v_mfma_f32_16x16x32_bf16 v[16:19], v[242:245], v[88:91], v[24:27]
	v_mfma_f32_16x16x32_bf16 v[104:107], v[246:249], v[104:107], v[16:19]
	v_mfma_f32_16x16x32_bf16 v[16:19], v[198:201], v[206:209], v[28:31]
	v_mfma_f32_16x16x32_bf16 v[48:51], v[198:201], v[44:47], v[96:99]
	v_mfma_f32_16x16x32_bf16 v[88:91], v[238:241], v[210:213], v[16:19]
	v_mfma_f32_16x16x32_bf16 v[16:19], v[242:245], v[206:209], v[32:35]
	v_mfma_f32_16x16x32_bf16 v[144:147], v[238:241], v[80:83], v[48:51]
	v_mfma_f32_16x16x32_bf16 v[80:83], v[246:249], v[210:213], v[16:19]
	v_mfma_f32_16x16x32_bf16 v[16:19], v[198:201], v[230:233], v[36:39]
	v_mfma_f32_16x16x32_bf16 v[72:75], v[238:241], v[234:237], v[16:19]
	v_mfma_f32_16x16x32_bf16 v[16:19], v[242:245], v[230:233], v[40:43]
	v_mfma_f32_16x16x32_bf16 v[64:67], v[246:249], v[234:237], v[16:19]
	s_setprio 0
	s_mov_b32 m0, s54
	v_lshl_add_u64 v[20:21], v[252:253], 0, s[16:17]
	s_barrier
	s_nop 2
	ds_read_b128 v[16:19], v189 offset:49152
	ds_read_b128 v[24:27], v189 offset:50176
	ds_read_b128 v[32:35], v189 offset:51200
	ds_read_b128 v[96:99], v189 offset:52224
	ds_read_b128 v[206:209], v189 offset:53248
	ds_read_b128 v[210:213], v189 offset:54272
	ds_read_b128 v[230:233], v189 offset:55296
	ds_read_b128 v[234:237], v189 offset:56320
	global_load_lds_dwordx4 v[20:21], off
	v_lshl_add_u64 v[20:21], v[170:171], 0, s[16:17]
	s_mov_b32 m0, s55
	s_nop 0
	global_load_lds_dwordx4 v[20:21], off
	s_barrier
	s_waitcnt lgkmcnt(0)
	s_setprio 1
	s_waitcnt lgkmcnt(0)
	v_mfma_f32_16x16x32_bf16 v[20:23], v[12:15], v[16:19], v[128:131]
	v_mfma_f32_16x16x32_bf16 v[60:63], v[182:185], v[24:27], v[20:23]
	v_mfma_f32_16x16x32_bf16 v[20:23], v[194:197], v[16:19], v[132:135]
	v_mfma_f32_16x16x32_bf16 v[52:55], v[202:205], v[24:27], v[20:23]
	v_mfma_f32_16x16x32_bf16 v[20:23], v[12:15], v[32:35], v[214:217]
	v_mfma_f32_16x16x32_bf16 v[44:47], v[182:185], v[96:99], v[20:23]
	v_mfma_f32_16x16x32_bf16 v[20:23], v[194:197], v[32:35], v[218:221]
	v_mfma_f32_16x16x32_bf16 v[36:39], v[202:205], v[96:99], v[20:23]
	v_mfma_f32_16x16x32_bf16 v[20:23], v[12:15], v[206:209], v[222:225]
	v_mfma_f32_16x16x32_bf16 v[0:3], v[12:15], v[230:233], v[0:3]
	v_mfma_f32_16x16x32_bf16 v[28:31], v[182:185], v[210:213], v[20:23]
	v_mfma_f32_16x16x32_bf16 v[20:23], v[194:197], v[206:209], v[148:151]
	v_mfma_f32_16x16x32_bf16 v[12:15], v[182:185], v[234:237], v[0:3]
	v_mfma_f32_16x16x32_bf16 v[0:3], v[194:197], v[230:233], v[4:7]
	v_mfma_f32_16x16x32_bf16 v[20:23], v[202:205], v[210:213], v[20:23]
	v_mfma_f32_16x16x32_bf16 v[4:7], v[202:205], v[234:237], v[0:3]
	s_setprio 0
	s_barrier
	s_add_u32 s34, s38, 0x10080
	s_addc_u32 s35, s39, 0
	s_mov_b32 m0, s56
	s_nop 0
	v_lshl_add_u64 v[0:1], s[34:35], 0, v[162:163]
	global_load_lds_dwordx4 v[0:1], off
	v_lshl_add_u64 v[0:1], s[34:35], 0, v[166:167]
	s_mov_b32 m0, s57
	s_nop 0
	global_load_lds_dwordx4 v[0:1], off
	s_waitcnt vmcnt(6)
	s_barrier
	s_setprio 1
	v_mfma_f32_16x16x32_bf16 v[0:3], v[198:201], v[16:19], v[8:11]
	v_mfma_f32_16x16x32_bf16 v[56:59], v[238:241], v[24:27], v[0:3]
	v_mfma_f32_16x16x32_bf16 v[0:3], v[242:245], v[16:19], v[120:123]
	v_mfma_f32_16x16x32_bf16 v[48:51], v[246:249], v[24:27], v[0:3]
	v_mfma_f32_16x16x32_bf16 v[0:3], v[198:201], v[32:35], v[124:127]
	v_mfma_f32_16x16x32_bf16 v[40:43], v[238:241], v[96:99], v[0:3]
	v_mfma_f32_16x16x32_bf16 v[0:3], v[242:245], v[32:35], v[152:155]
	v_mfma_f32_16x16x32_bf16 v[32:35], v[246:249], v[96:99], v[0:3]
	v_mfma_f32_16x16x32_bf16 v[0:3], v[198:201], v[206:209], v[226:229]
	v_mfma_f32_16x16x32_bf16 v[24:27], v[238:241], v[210:213], v[0:3]
	v_mfma_f32_16x16x32_bf16 v[0:3], v[242:245], v[206:209], v[100:103]
	v_mfma_f32_16x16x32_bf16 v[16:19], v[246:249], v[210:213], v[0:3]
	v_mfma_f32_16x16x32_bf16 v[0:3], v[198:201], v[230:233], v[174:177]
	v_mfma_f32_16x16x32_bf16 v[8:11], v[238:241], v[234:237], v[0:3]
	v_mfma_f32_16x16x32_bf16 v[0:3], v[242:245], v[230:233], v[178:181]
	v_mfma_f32_16x16x32_bf16 v[0:3], v[246:249], v[234:237], v[0:3]
	s_setprio 0
	v_mov_b32_e32 v96, 0
	s_barrier
	s_lshl_b32 s23, s30, 8
	v_mbcnt_lo_u32_b32 v96, -1, v96
	v_mbcnt_hi_u32_b32 v96, -1, v96
	s_add_i32 s23, s23, s50
	v_and_or_b32 v176, v96, 15, s23
	s_lshl_b32 s23, s60, 8
	v_ashrrev_i32_e32 v96, 1, v96
	v_and_b32_e32 v96, -8, v96
	s_or_b32 s23, s23, s51
	v_add_u32_e32 v170, s23, v96
	v_ashrrev_i32_e32 v177, 31, v176
	v_ashrrev_i32_e32 v171, 31, v170
	v_lshlrev_b64 v[96:97], 11, v[176:177]
	v_lshl_add_u64 v[96:97], s[6:7], 0, v[96:97]
	v_lshlrev_b64 v[178:179], 1, v[170:171]
	v_lshl_add_u64 v[96:97], v[96:97], 0, v[178:179]
	v_add_u32_e32 v226, 0x80, v170
	v_lshrrev_b32_e32 v98, 8, v170
	global_load_dwordx4 v[194:197], v[96:97], off
	global_load_dwordx4 v[198:201], v[96:97], off offset:256
	v_lshrrev_b32_e32 v96, 8, v226
	v_mul_hi_i32_i24_e32 v181, 0x4080, v98
	v_mul_i32_i24_e32 v180, 0x4080, v98
	v_mul_hi_i32_i24_e32 v183, 0x4080, v96
	v_mul_i32_i24_e32 v182, 0x4080, v96
	v_lshl_add_u64 v[98:99], v[180:181], 0, v[176:177]
	v_and_b32_e32 v100, 0xf8, v170
	v_lshl_add_u64 v[96:97], v[182:183], 0, v[176:177]
	v_lshlrev_b64 v[98:99], 9, v[98:99]
	v_lshlrev_b32_e32 v168, 1, v100
	v_and_b32_e32 v100, 0xf8, v226
	v_lshlrev_b64 v[96:97], 9, v[96:97]
	v_lshl_add_u64 v[98:99], s[10:11], 0, v[98:99]
	v_lshl_add_u64 v[96:97], s[10:11], 0, v[96:97]
	v_lshlrev_b32_e32 v184, 1, v100
	v_mov_b32_e32 v185, v169
	v_mbcnt_lo_u32_b32 v100, -1, 0
	v_mbcnt_hi_u32_b32 v100, -1, v100
	v_bfe_u32 v168, v170, 4, 4
	v_and_b32_e32 v184, 15, v100
	v_sub_u32_e32 v168, v168, v184
	v_lshlrev_b32_e32 v168, 9, v168
	v_lshl_add_u32 v168, v184, 4, v168
	v_bfe_u32 v184, v100, 4, 1
	v_lshl_add_u32 v168, v184, 8, v168
	v_ashrrev_i32_e32 v169, 31, v168
	v_add_u32_e32 v184, 0x1000, v168
	v_ashrrev_i32_e32 v185, 31, v184
	v_or_b32_e32 v228, 16, v176
	v_lshl_add_u64 v[98:99], v[98:99], 0, v[168:169]
	v_lshl_add_u64 v[96:97], v[96:97], 0, v[184:185]
	v_ashrrev_i32_e32 v229, 31, v228
	global_load_dwordx4 v[202:205], v[98:99], off
	global_load_dwordx4 v[206:209], v[96:97], off
	v_lshlrev_b64 v[96:97], 11, v[228:229]
	v_lshl_add_u64 v[96:97], s[6:7], 0, v[96:97]
	v_lshl_add_u64 v[96:97], v[96:97], 0, v[178:179]
	v_lshl_add_u64 v[98:99], v[180:181], 0, v[228:229]
	global_load_dwordx4 v[210:213], v[96:97], off
	global_load_dwordx4 v[214:217], v[96:97], off offset:256
	v_lshl_add_u64 v[96:97], v[182:183], 0, v[228:229]
	v_lshlrev_b64 v[98:99], 9, v[98:99]
	v_lshlrev_b64 v[96:97], 9, v[96:97]
	v_lshl_add_u64 v[98:99], s[10:11], 0, v[98:99]
	v_lshl_add_u64 v[96:97], s[10:11], 0, v[96:97]
	v_or_b32_e32 v230, 32, v176
	v_lshl_add_u64 v[98:99], v[98:99], 0, v[168:169]
	v_lshl_add_u64 v[96:97], v[96:97], 0, v[184:185]
	v_ashrrev_i32_e32 v231, 31, v230
	global_load_dwordx4 v[218:221], v[98:99], off
	global_load_dwordx4 v[222:225], v[96:97], off
	v_lshlrev_b64 v[96:97], 11, v[230:231]
	v_lshl_add_u64 v[96:97], s[6:7], 0, v[96:97]
	v_lshl_add_u64 v[96:97], v[96:97], 0, v[178:179]
	v_lshl_add_u64 v[98:99], v[180:181], 0, v[230:231]
	v_lshlrev_b64 v[98:99], 9, v[98:99]
	global_load_dwordx4 v[148:151], v[96:97], off
	global_load_dwordx4 v[128:131], v[96:97], off offset:256
	v_lshl_add_u64 v[96:97], v[182:183], 0, v[230:231]
	v_lshl_add_u64 v[98:99], s[10:11], 0, v[98:99]
	v_lshlrev_b64 v[96:97], 9, v[96:97]
	v_or_b32_e32 v186, 48, v176
	v_lshl_add_u64 v[98:99], v[98:99], 0, v[168:169]
	v_lshl_add_u64 v[96:97], s[10:11], 0, v[96:97]
	v_ashrrev_i32_e32 v187, 31, v186
	v_lshl_add_u64 v[96:97], v[96:97], 0, v[184:185]
	global_load_dwordx4 v[152:155], v[98:99], off
	global_load_dwordx4 v[132:135], v[96:97], off
	v_lshl_add_u64 v[98:99], v[180:181], 0, v[186:187]
	v_lshl_add_u64 v[102:103], v[182:183], 0, v[186:187]
	v_lshlrev_b64 v[96:97], 11, v[186:187]
	v_lshlrev_b64 v[98:99], 9, v[98:99]
	v_lshlrev_b64 v[102:103], 9, v[102:103]
	v_lshl_add_u64 v[96:97], s[6:7], 0, v[96:97]
	v_lshl_add_u64 v[98:99], s[10:11], 0, v[98:99]
	v_lshl_add_u64 v[102:103], s[10:11], 0, v[102:103]
	v_lshl_add_u64 v[96:97], v[96:97], 0, v[178:179]
	v_lshl_add_u64 v[100:101], v[98:99], 0, v[168:169]
	v_lshl_add_u64 v[102:103], v[102:103], 0, v[184:185]
	global_load_dwordx4 v[120:123], v[96:97], off
	s_nop 0
	global_load_dwordx4 v[96:99], v[96:97], off offset:256
	s_nop 0
	global_load_dwordx4 v[124:127], v[100:101], off
	s_nop 0
	global_load_dwordx4 v[100:103], v[102:103], off
	v_ashrrev_i32_e32 v227, 31, v226
	v_lshlrev_b64 v[174:175], 12, v[176:177]
	v_lshl_add_u64 v[232:233], s[14:15], 0, v[174:175]
	v_lshlrev_b64 v[174:175], 2, v[170:171]
	s_waitcnt vmcnt(0)
	v_lshlrev_b32_e32 v234, 16, v194
	v_and_b32_e32 v235, 0xffff0000, v194
	v_lshlrev_b32_e32 v236, 16, v202
	v_and_b32_e32 v237, 0xffff0000, v202
	v_lshlrev_b32_e32 v194, 16, v195
	v_and_b32_e32 v195, 0xffff0000, v195
	v_lshlrev_b32_e32 v202, 16, v203
	v_and_b32_e32 v203, 0xffff0000, v203
	v_lshl_add_u64 v[170:171], v[232:233], 0, v[174:175]
	v_pk_fma_f32 v[156:157], v[156:157], v[236:237], v[234:235]
	v_pk_fma_f32 v[158:159], v[158:159], v[202:203], v[194:195]
	global_store_dwordx4 v[170:171], v[156:159], off
	s_nop 1
	v_lshlrev_b32_e32 v156, 16, v196
	v_and_b32_e32 v157, 0xffff0000, v196
	v_lshlrev_b32_e32 v158, 16, v204
	v_and_b32_e32 v159, 0xffff0000, v204
	v_pk_fma_f32 v[140:141], v[140:141], v[158:159], v[156:157]
	v_lshlrev_b32_e32 v156, 16, v197
	v_and_b32_e32 v157, 0xffff0000, v197
	v_lshlrev_b32_e32 v158, 16, v205
	v_and_b32_e32 v159, 0xffff0000, v205
	v_pk_fma_f32 v[142:143], v[142:143], v[158:159], v[156:157]
	global_store_dwordx4 v[170:171], v[140:143], off offset:16
	v_lshlrev_b32_e32 v158, 16, v206
	v_and_b32_e32 v159, 0xffff0000, v206
	v_lshlrev_b32_e32 v142, 16, v198
	v_and_b32_e32 v143, 0xffff0000, v198
	v_lshlrev_b64 v[140:141], 2, v[226:227]
	v_pk_fma_f32 v[142:143], v[144:145], v[158:159], v[142:143]
	v_lshlrev_b32_e32 v144, 16, v199
	v_and_b32_e32 v145, 0xffff0000, v199
	v_lshlrev_b32_e32 v158, 16, v207
	v_and_b32_e32 v159, 0xffff0000, v207
	v_lshl_add_u64 v[156:157], v[232:233], 0, v[140:141]
	v_pk_fma_f32 v[144:145], v[146:147], v[158:159], v[144:145]
	global_store_dwordx4 v[156:157], v[142:145], off
	s_nop 1
	v_lshlrev_b32_e32 v142, 16, v200
	v_and_b32_e32 v143, 0xffff0000, v200
	v_lshlrev_b32_e32 v144, 16, v208
	v_and_b32_e32 v145, 0xffff0000, v208
	v_pk_fma_f32 v[136:137], v[136:137], v[144:145], v[142:143]
	v_lshlrev_b32_e32 v142, 16, v201
	v_and_b32_e32 v143, 0xffff0000, v201
	v_lshlrev_b32_e32 v144, 16, v209
	v_and_b32_e32 v145, 0xffff0000, v209
	v_pk_fma_f32 v[138:139], v[138:139], v[144:145], v[142:143]
	global_store_dwordx4 v[156:157], v[136:139], off offset:16
	v_lshlrev_b32_e32 v142, 16, v210
	v_and_b32_e32 v143, 0xffff0000, v210
	v_lshlrev_b64 v[136:137], 12, v[228:229]
	v_lshlrev_b32_e32 v144, 16, v218
	v_and_b32_e32 v145, 0xffff0000, v218
	v_lshl_add_u64 v[136:137], s[14:15], 0, v[136:137]
	v_pk_fma_f32 v[116:117], v[116:117], v[144:145], v[142:143]
	v_lshlrev_b32_e32 v142, 16, v211
	v_and_b32_e32 v143, 0xffff0000, v211
	v_lshlrev_b32_e32 v144, 16, v219
	v_and_b32_e32 v145, 0xffff0000, v219
	v_lshl_add_u64 v[138:139], v[136:137], 0, v[174:175]
	v_pk_fma_f32 v[118:119], v[118:119], v[144:145], v[142:143]
	global_store_dwordx4 v[138:139], v[116:119], off
	s_nop 1
	v_lshlrev_b32_e32 v116, 16, v212
	v_and_b32_e32 v117, 0xffff0000, v212
	v_lshlrev_b32_e32 v118, 16, v220
	v_and_b32_e32 v119, 0xffff0000, v220
	v_pk_fma_f32 v[108:109], v[108:109], v[118:119], v[116:117]
	v_lshlrev_b32_e32 v116, 16, v213
	v_and_b32_e32 v117, 0xffff0000, v213
	v_lshlrev_b32_e32 v118, 16, v221
	v_and_b32_e32 v119, 0xffff0000, v221
	v_pk_fma_f32 v[110:111], v[110:111], v[118:119], v[116:117]
	global_store_dwordx4 v[138:139], v[108:111], off offset:16
	v_lshl_add_u64 v[116:117], v[136:137], 0, v[140:141]
	s_nop 0
	v_lshlrev_b32_e32 v108, 16, v214
	v_and_b32_e32 v109, 0xffff0000, v214
	v_lshlrev_b32_e32 v110, 16, v222
	v_and_b32_e32 v111, 0xffff0000, v222
	v_pk_fma_f32 v[108:109], v[112:113], v[110:111], v[108:109]
	v_lshlrev_b32_e32 v110, 16, v215
	v_and_b32_e32 v111, 0xffff0000, v215
	v_lshlrev_b32_e32 v112, 16, v223
	v_and_b32_e32 v113, 0xffff0000, v223
	v_pk_fma_f32 v[110:111], v[114:115], v[112:113], v[110:111]
	global_store_dwordx4 v[116:117], v[108:111], off
	s_nop 1
	v_lshlrev_b32_e32 v108, 16, v216
	v_and_b32_e32 v109, 0xffff0000, v216
	v_lshlrev_b32_e32 v110, 16, v224
	v_and_b32_e32 v111, 0xffff0000, v224
	v_pk_fma_f32 v[104:105], v[104:105], v[110:111], v[108:109]
	v_lshlrev_b32_e32 v108, 16, v217
	v_and_b32_e32 v109, 0xffff0000, v217
	v_lshlrev_b32_e32 v110, 16, v225
	v_and_b32_e32 v111, 0xffff0000, v225
	v_pk_fma_f32 v[106:107], v[106:107], v[110:111], v[108:109]
	global_store_dwordx4 v[116:117], v[104:107], off offset:16
	v_lshlrev_b32_e32 v108, 16, v148
	v_and_b32_e32 v109, 0xffff0000, v148
	v_lshlrev_b64 v[104:105], 12, v[230:231]
	v_lshlrev_b32_e32 v110, 16, v152
	v_and_b32_e32 v111, 0xffff0000, v152
	v_lshl_add_u64 v[104:105], s[14:15], 0, v[104:105]
	v_pk_fma_f32 v[92:93], v[92:93], v[110:111], v[108:109]
	v_lshlrev_b32_e32 v108, 16, v149
	v_and_b32_e32 v109, 0xffff0000, v149
	v_lshlrev_b32_e32 v110, 16, v153
	v_and_b32_e32 v111, 0xffff0000, v153
	v_lshl_add_u64 v[106:107], v[104:105], 0, v[174:175]
	v_pk_fma_f32 v[94:95], v[94:95], v[110:111], v[108:109]
	global_store_dwordx4 v[106:107], v[92:95], off
	s_nop 1
	v_lshlrev_b32_e32 v92, 16, v150
	v_and_b32_e32 v93, 0xffff0000, v150
	v_lshlrev_b32_e32 v94, 16, v154
	v_and_b32_e32 v95, 0xffff0000, v154
	v_pk_fma_f32 v[84:85], v[84:85], v[94:95], v[92:93]
	v_lshlrev_b32_e32 v92, 16, v151
	v_and_b32_e32 v93, 0xffff0000, v151
	v_lshlrev_b32_e32 v94, 16, v155
	v_and_b32_e32 v95, 0xffff0000, v155
	v_pk_fma_f32 v[86:87], v[86:87], v[94:95], v[92:93]
	global_store_dwordx4 v[106:107], v[84:87], off offset:16
	v_lshl_add_u64 v[92:93], v[104:105], 0, v[140:141]
	s_nop 0
	v_lshlrev_b32_e32 v84, 16, v128
	v_and_b32_e32 v85, 0xffff0000, v128
	v_lshlrev_b32_e32 v86, 16, v132
	v_and_b32_e32 v87, 0xffff0000, v132
	v_pk_fma_f32 v[84:85], v[88:89], v[86:87], v[84:85]
	v_lshlrev_b32_e32 v86, 16, v129
	v_and_b32_e32 v87, 0xffff0000, v129
	v_lshlrev_b32_e32 v88, 16, v133
	v_and_b32_e32 v89, 0xffff0000, v133
	v_pk_fma_f32 v[86:87], v[90:91], v[88:89], v[86:87]
	global_store_dwordx4 v[92:93], v[84:87], off
	s_nop 1
	v_lshlrev_b32_e32 v84, 16, v130
	v_and_b32_e32 v85, 0xffff0000, v130
	v_lshlrev_b32_e32 v86, 16, v134
	v_and_b32_e32 v87, 0xffff0000, v134
	v_pk_fma_f32 v[80:81], v[80:81], v[86:87], v[84:85]
	v_lshlrev_b32_e32 v84, 16, v131
	v_and_b32_e32 v85, 0xffff0000, v131
	v_lshlrev_b32_e32 v86, 16, v135
	v_and_b32_e32 v87, 0xffff0000, v135
	v_pk_fma_f32 v[82:83], v[82:83], v[86:87], v[84:85]
	global_store_dwordx4 v[92:93], v[80:83], off offset:16
	v_lshlrev_b32_e32 v84, 16, v120
	v_and_b32_e32 v85, 0xffff0000, v120
	v_lshlrev_b64 v[80:81], 12, v[186:187]
	v_lshlrev_b32_e32 v86, 16, v124
	v_and_b32_e32 v87, 0xffff0000, v124
	v_lshl_add_u64 v[80:81], s[14:15], 0, v[80:81]
	v_pk_fma_f32 v[76:77], v[76:77], v[86:87], v[84:85]
	v_lshlrev_b32_e32 v84, 16, v121
	v_and_b32_e32 v85, 0xffff0000, v121
	v_lshlrev_b32_e32 v86, 16, v125
	v_and_b32_e32 v87, 0xffff0000, v125
	v_lshl_add_u64 v[82:83], v[80:81], 0, v[174:175]
	v_pk_fma_f32 v[78:79], v[78:79], v[86:87], v[84:85]
	global_store_dwordx4 v[82:83], v[76:79], off
	s_nop 1
	v_lshlrev_b32_e32 v76, 16, v122
	v_and_b32_e32 v77, 0xffff0000, v122
	v_lshlrev_b32_e32 v78, 16, v126
	v_and_b32_e32 v79, 0xffff0000, v126
	v_pk_fma_f32 v[68:69], v[68:69], v[78:79], v[76:77]
	v_lshlrev_b32_e32 v76, 16, v123
	v_and_b32_e32 v77, 0xffff0000, v123
	v_lshlrev_b32_e32 v78, 16, v127
	v_and_b32_e32 v79, 0xffff0000, v127
	v_pk_fma_f32 v[70:71], v[70:71], v[78:79], v[76:77]
	global_store_dwordx4 v[82:83], v[68:71], off offset:16
	v_lshl_add_u64 v[76:77], v[80:81], 0, v[140:141]
	s_nop 0
	v_lshlrev_b32_e32 v68, 16, v96
	v_and_b32_e32 v69, 0xffff0000, v96
	v_lshlrev_b32_e32 v70, 16, v100
	v_and_b32_e32 v71, 0xffff0000, v100
	v_pk_fma_f32 v[68:69], v[72:73], v[70:71], v[68:69]
	v_lshlrev_b32_e32 v70, 16, v97
	v_and_b32_e32 v71, 0xffff0000, v97
	v_lshlrev_b32_e32 v72, 16, v101
	v_and_b32_e32 v73, 0xffff0000, v101
	v_pk_fma_f32 v[70:71], v[74:75], v[72:73], v[70:71]
	global_store_dwordx4 v[76:77], v[68:71], off
	s_nop 1
	v_lshlrev_b32_e32 v68, 16, v98
	v_and_b32_e32 v69, 0xffff0000, v98
	v_lshlrev_b32_e32 v70, 16, v102
	v_and_b32_e32 v71, 0xffff0000, v102
	v_pk_fma_f32 v[64:65], v[64:65], v[70:71], v[68:69]
	v_lshlrev_b32_e32 v68, 16, v99
	v_and_b32_e32 v69, 0xffff0000, v99
	v_lshlrev_b32_e32 v70, 16, v103
	v_and_b32_e32 v71, 0xffff0000, v103
	v_pk_fma_f32 v[66:67], v[66:67], v[70:71], v[68:69]
	global_store_dwordx4 v[76:77], v[64:67], off offset:16
	v_add_u32_e32 v130, 0x80, v176
	v_ashrrev_i32_e32 v131, 31, v130
	v_lshlrev_b64 v[64:65], 11, v[130:131]
	v_lshl_add_u64 v[64:65], s[6:7], 0, v[64:65]
	v_lshl_add_u64 v[64:65], v[64:65], 0, v[178:179]
	v_lshl_add_u64 v[66:67], v[180:181], 0, v[130:131]
	global_load_dwordx4 v[98:101], v[64:65], off
	global_load_dwordx4 v[102:105], v[64:65], off offset:256
	v_lshl_add_u64 v[64:65], v[182:183], 0, v[130:131]
	v_lshlrev_b64 v[66:67], 9, v[66:67]
	v_lshlrev_b64 v[64:65], 9, v[64:65]
	v_lshl_add_u64 v[66:67], s[10:11], 0, v[66:67]
	v_lshl_add_u64 v[64:65], s[10:11], 0, v[64:65]
	v_add_u32_e32 v132, 0x90, v176
	v_lshl_add_u64 v[66:67], v[66:67], 0, v[168:169]
	v_lshl_add_u64 v[64:65], v[64:65], 0, v[184:185]
	v_ashrrev_i32_e32 v133, 31, v132
	global_load_dwordx4 v[106:109], v[66:67], off
	global_load_dwordx4 v[110:113], v[64:65], off
	v_lshlrev_b64 v[64:65], 11, v[132:133]
	v_lshl_add_u64 v[64:65], s[6:7], 0, v[64:65]
	v_lshl_add_u64 v[64:65], v[64:65], 0, v[178:179]
	v_lshl_add_u64 v[66:67], v[180:181], 0, v[132:133]
	global_load_dwordx4 v[114:117], v[64:65], off
	global_load_dwordx4 v[118:121], v[64:65], off offset:256
	v_lshl_add_u64 v[64:65], v[182:183], 0, v[132:133]
	v_lshlrev_b64 v[66:67], 9, v[66:67]
	v_lshlrev_b64 v[64:65], 9, v[64:65]
	v_lshl_add_u64 v[66:67], s[10:11], 0, v[66:67]
	v_lshl_add_u64 v[64:65], s[10:11], 0, v[64:65]
	v_add_u32_e32 v134, 0xa0, v176
	v_lshl_add_u64 v[66:67], v[66:67], 0, v[168:169]
	v_lshl_add_u64 v[64:65], v[64:65], 0, v[184:185]
	v_ashrrev_i32_e32 v135, 31, v134
	global_load_dwordx4 v[122:125], v[66:67], off
	global_load_dwordx4 v[126:129], v[64:65], off
	v_lshlrev_b64 v[64:65], 11, v[134:135]
	v_lshl_add_u64 v[64:65], s[6:7], 0, v[64:65]
	v_lshl_add_u64 v[64:65], v[64:65], 0, v[178:179]
	v_lshl_add_u64 v[66:67], v[180:181], 0, v[134:135]
	v_lshlrev_b64 v[66:67], 9, v[66:67]
	global_load_dwordx4 v[88:91], v[64:65], off
	global_load_dwordx4 v[80:83], v[64:65], off offset:256
	v_lshl_add_u64 v[64:65], v[182:183], 0, v[134:135]
	v_lshl_add_u64 v[66:67], s[10:11], 0, v[66:67]
	v_lshlrev_b64 v[64:65], 9, v[64:65]
	v_add_u32_e32 v96, 0xb0, v176
	v_lshl_add_u64 v[66:67], v[66:67], 0, v[168:169]
	v_lshl_add_u64 v[64:65], s[10:11], 0, v[64:65]
	v_ashrrev_i32_e32 v97, 31, v96
	v_lshl_add_u64 v[64:65], v[64:65], 0, v[184:185]
	global_load_dwordx4 v[92:95], v[66:67], off
	global_load_dwordx4 v[84:87], v[64:65], off
	v_lshl_add_u64 v[66:67], v[180:181], 0, v[96:97]
	v_lshl_add_u64 v[70:71], v[182:183], 0, v[96:97]
	v_lshlrev_b64 v[64:65], 11, v[96:97]
	v_lshlrev_b64 v[66:67], 9, v[66:67]
	v_lshlrev_b64 v[70:71], 9, v[70:71]
	v_lshl_add_u64 v[64:65], s[6:7], 0, v[64:65]
	v_lshl_add_u64 v[66:67], s[10:11], 0, v[66:67]
	v_lshl_add_u64 v[70:71], s[10:11], 0, v[70:71]
	v_lshl_add_u64 v[64:65], v[64:65], 0, v[178:179]
	v_lshl_add_u64 v[68:69], v[66:67], 0, v[168:169]
	v_lshl_add_u64 v[70:71], v[70:71], 0, v[184:185]
	global_load_dwordx4 v[72:75], v[64:65], off
	s_nop 0
	global_load_dwordx4 v[64:67], v[64:65], off offset:256
	s_nop 0
	global_load_dwordx4 v[76:79], v[68:69], off
	s_nop 0
	global_load_dwordx4 v[68:71], v[70:71], off
	v_lshlrev_b64 v[130:131], 12, v[130:131]
	v_lshl_add_u64 v[130:131], s[14:15], 0, v[130:131]
	s_waitcnt vmcnt(0)
	v_lshlrev_b32_e32 v138, 16, v98
	v_and_b32_e32 v139, 0xffff0000, v98
	v_lshlrev_b32_e32 v142, 16, v106
	v_and_b32_e32 v143, 0xffff0000, v106
	v_lshlrev_b32_e32 v98, 16, v99
	v_and_b32_e32 v99, 0xffff0000, v99
	v_lshlrev_b32_e32 v106, 16, v107
	v_and_b32_e32 v107, 0xffff0000, v107
	v_lshl_add_u64 v[136:137], v[130:131], 0, v[174:175]
	v_pk_fma_f32 v[60:61], v[60:61], v[142:143], v[138:139]
	v_pk_fma_f32 v[62:63], v[62:63], v[106:107], v[98:99]
	global_store_dwordx4 v[136:137], v[60:63], off
	s_nop 1
	v_lshlrev_b32_e32 v60, 16, v100
	v_and_b32_e32 v61, 0xffff0000, v100
	v_lshlrev_b32_e32 v62, 16, v108
	v_and_b32_e32 v63, 0xffff0000, v108
	v_pk_fma_f32 v[52:53], v[52:53], v[62:63], v[60:61]
	v_lshlrev_b32_e32 v60, 16, v101
	v_and_b32_e32 v61, 0xffff0000, v101
	v_lshlrev_b32_e32 v62, 16, v109
	v_and_b32_e32 v63, 0xffff0000, v109
	v_pk_fma_f32 v[54:55], v[54:55], v[62:63], v[60:61]
	global_store_dwordx4 v[136:137], v[52:55], off offset:16
	v_lshl_add_u64 v[60:61], v[130:131], 0, v[140:141]
	s_nop 0
	v_lshlrev_b32_e32 v52, 16, v102
	v_and_b32_e32 v53, 0xffff0000, v102
	v_lshlrev_b32_e32 v54, 16, v110
	v_and_b32_e32 v55, 0xffff0000, v110
	v_pk_fma_f32 v[52:53], v[56:57], v[54:55], v[52:53]
	v_lshlrev_b32_e32 v54, 16, v103
	v_and_b32_e32 v55, 0xffff0000, v103
	v_lshlrev_b32_e32 v56, 16, v111
	v_and_b32_e32 v57, 0xffff0000, v111
	v_pk_fma_f32 v[54:55], v[58:59], v[56:57], v[54:55]
	global_store_dwordx4 v[60:61], v[52:55], off
	s_nop 1
	v_lshlrev_b32_e32 v52, 16, v104
	v_and_b32_e32 v53, 0xffff0000, v104
	v_lshlrev_b32_e32 v54, 16, v112
	v_and_b32_e32 v55, 0xffff0000, v112
	v_pk_fma_f32 v[48:49], v[48:49], v[54:55], v[52:53]
	v_lshlrev_b32_e32 v52, 16, v105
	v_and_b32_e32 v53, 0xffff0000, v105
	v_lshlrev_b32_e32 v54, 16, v113
	v_and_b32_e32 v55, 0xffff0000, v113
	v_pk_fma_f32 v[50:51], v[50:51], v[54:55], v[52:53]
	global_store_dwordx4 v[60:61], v[48:51], off offset:16
	v_lshlrev_b32_e32 v52, 16, v114
	v_and_b32_e32 v53, 0xffff0000, v114
	v_lshlrev_b64 v[48:49], 12, v[132:133]
	v_lshlrev_b32_e32 v54, 16, v122
	v_and_b32_e32 v55, 0xffff0000, v122
	v_lshl_add_u64 v[48:49], s[14:15], 0, v[48:49]
	v_pk_fma_f32 v[44:45], v[44:45], v[54:55], v[52:53]
	v_lshlrev_b32_e32 v52, 16, v115
	v_and_b32_e32 v53, 0xffff0000, v115
	v_lshlrev_b32_e32 v54, 16, v123
	v_and_b32_e32 v55, 0xffff0000, v123
	v_lshl_add_u64 v[50:51], v[48:49], 0, v[174:175]
	v_pk_fma_f32 v[46:47], v[46:47], v[54:55], v[52:53]
	global_store_dwordx4 v[50:51], v[44:47], off
	s_nop 1
	v_lshlrev_b32_e32 v44, 16, v116
	v_and_b32_e32 v45, 0xffff0000, v116
	v_lshlrev_b32_e32 v46, 16, v124
	v_and_b32_e32 v47, 0xffff0000, v124
	v_pk_fma_f32 v[36:37], v[36:37], v[46:47], v[44:45]
	v_lshlrev_b32_e32 v44, 16, v117
	v_and_b32_e32 v45, 0xffff0000, v117
	v_lshlrev_b32_e32 v46, 16, v125
	v_and_b32_e32 v47, 0xffff0000, v125
	v_pk_fma_f32 v[38:39], v[38:39], v[46:47], v[44:45]
	global_store_dwordx4 v[50:51], v[36:39], off offset:16
	v_lshl_add_u64 v[44:45], v[48:49], 0, v[140:141]
	s_nop 0
	v_lshlrev_b32_e32 v36, 16, v118
	v_and_b32_e32 v37, 0xffff0000, v118
	v_lshlrev_b32_e32 v38, 16, v126
	v_and_b32_e32 v39, 0xffff0000, v126
	v_pk_fma_f32 v[36:37], v[40:41], v[38:39], v[36:37]
	v_lshlrev_b32_e32 v38, 16, v119
	v_and_b32_e32 v39, 0xffff0000, v119
	v_lshlrev_b32_e32 v40, 16, v127
	v_and_b32_e32 v41, 0xffff0000, v127
	v_pk_fma_f32 v[38:39], v[42:43], v[40:41], v[38:39]
	global_store_dwordx4 v[44:45], v[36:39], off
	s_nop 1
	v_lshlrev_b32_e32 v36, 16, v120
	v_and_b32_e32 v37, 0xffff0000, v120
	v_lshlrev_b32_e32 v38, 16, v128
	v_and_b32_e32 v39, 0xffff0000, v128
	v_pk_fma_f32 v[32:33], v[32:33], v[38:39], v[36:37]
	v_lshlrev_b32_e32 v36, 16, v121
	v_and_b32_e32 v37, 0xffff0000, v121
	v_lshlrev_b32_e32 v38, 16, v129
	v_and_b32_e32 v39, 0xffff0000, v129
	v_pk_fma_f32 v[34:35], v[34:35], v[38:39], v[36:37]
	global_store_dwordx4 v[44:45], v[32:35], off offset:16
	v_lshlrev_b32_e32 v36, 16, v88
	v_and_b32_e32 v37, 0xffff0000, v88
	v_lshlrev_b64 v[32:33], 12, v[134:135]
	v_lshlrev_b32_e32 v38, 16, v92
	v_and_b32_e32 v39, 0xffff0000, v92
	v_lshl_add_u64 v[32:33], s[14:15], 0, v[32:33]
	v_pk_fma_f32 v[28:29], v[28:29], v[38:39], v[36:37]
	v_lshlrev_b32_e32 v36, 16, v89
	v_and_b32_e32 v37, 0xffff0000, v89
	v_lshlrev_b32_e32 v38, 16, v93
	v_and_b32_e32 v39, 0xffff0000, v93
	v_lshl_add_u64 v[34:35], v[32:33], 0, v[174:175]
	v_pk_fma_f32 v[30:31], v[30:31], v[38:39], v[36:37]
	global_store_dwordx4 v[34:35], v[28:31], off
	s_nop 1
	v_lshlrev_b32_e32 v28, 16, v90
	v_and_b32_e32 v29, 0xffff0000, v90
	v_lshlrev_b32_e32 v30, 16, v94
	v_and_b32_e32 v31, 0xffff0000, v94
	v_pk_fma_f32 v[20:21], v[20:21], v[30:31], v[28:29]
	v_lshlrev_b32_e32 v28, 16, v91
	v_and_b32_e32 v29, 0xffff0000, v91
	v_lshlrev_b32_e32 v30, 16, v95
	v_and_b32_e32 v31, 0xffff0000, v95
	v_pk_fma_f32 v[22:23], v[22:23], v[30:31], v[28:29]
	global_store_dwordx4 v[34:35], v[20:23], off offset:16
	v_lshl_add_u64 v[28:29], v[32:33], 0, v[140:141]
	s_nop 0
	v_lshlrev_b32_e32 v20, 16, v80
	v_and_b32_e32 v21, 0xffff0000, v80
	v_lshlrev_b32_e32 v22, 16, v84
	v_and_b32_e32 v23, 0xffff0000, v84
	v_pk_fma_f32 v[20:21], v[24:25], v[22:23], v[20:21]
	v_lshlrev_b32_e32 v22, 16, v81
	v_and_b32_e32 v23, 0xffff0000, v81
	v_lshlrev_b32_e32 v24, 16, v85
	v_and_b32_e32 v25, 0xffff0000, v85
	v_pk_fma_f32 v[22:23], v[26:27], v[24:25], v[22:23]
	global_store_dwordx4 v[28:29], v[20:23], off
	s_nop 1
	v_lshlrev_b32_e32 v20, 16, v82
	v_and_b32_e32 v21, 0xffff0000, v82
	v_lshlrev_b32_e32 v22, 16, v86
	v_and_b32_e32 v23, 0xffff0000, v86
	v_pk_fma_f32 v[16:17], v[16:17], v[22:23], v[20:21]
	v_lshlrev_b32_e32 v20, 16, v83
	v_and_b32_e32 v21, 0xffff0000, v83
	v_lshlrev_b32_e32 v22, 16, v87
	v_and_b32_e32 v23, 0xffff0000, v87
	v_pk_fma_f32 v[18:19], v[18:19], v[22:23], v[20:21]
	global_store_dwordx4 v[28:29], v[16:19], off offset:16
	v_lshlrev_b32_e32 v20, 16, v72
	v_and_b32_e32 v21, 0xffff0000, v72
	v_lshlrev_b64 v[16:17], 12, v[96:97]
	v_lshlrev_b32_e32 v22, 16, v76
	v_and_b32_e32 v23, 0xffff0000, v76
	v_lshl_add_u64 v[16:17], s[14:15], 0, v[16:17]
	v_pk_fma_f32 v[12:13], v[12:13], v[22:23], v[20:21]
	v_lshlrev_b32_e32 v20, 16, v73
	v_and_b32_e32 v21, 0xffff0000, v73
	v_lshlrev_b32_e32 v22, 16, v77
	v_and_b32_e32 v23, 0xffff0000, v77
	v_lshl_add_u64 v[18:19], v[16:17], 0, v[174:175]
	v_pk_fma_f32 v[14:15], v[14:15], v[22:23], v[20:21]
	global_store_dwordx4 v[18:19], v[12:15], off
	s_nop 1
	v_lshlrev_b32_e32 v12, 16, v74
	v_and_b32_e32 v13, 0xffff0000, v74
	v_lshlrev_b32_e32 v14, 16, v78
	v_and_b32_e32 v15, 0xffff0000, v78
	v_pk_fma_f32 v[4:5], v[4:5], v[14:15], v[12:13]
	v_lshlrev_b32_e32 v12, 16, v75
	v_and_b32_e32 v13, 0xffff0000, v75
	v_lshlrev_b32_e32 v14, 16, v79
	v_and_b32_e32 v15, 0xffff0000, v79
	v_pk_fma_f32 v[6:7], v[6:7], v[14:15], v[12:13]
	global_store_dwordx4 v[18:19], v[4:7], off offset:16
	v_lshl_add_u64 v[12:13], v[16:17], 0, v[140:141]
	s_nop 0
	v_lshlrev_b32_e32 v4, 16, v68
	v_and_b32_e32 v5, 0xffff0000, v68
	v_lshlrev_b32_e32 v6, 16, v64
	v_and_b32_e32 v7, 0xffff0000, v64
	v_pk_fma_f32 v[4:5], v[8:9], v[4:5], v[6:7]
	v_lshlrev_b32_e32 v6, 16, v69
	v_and_b32_e32 v7, 0xffff0000, v69
	v_lshlrev_b32_e32 v8, 16, v65
	v_and_b32_e32 v9, 0xffff0000, v65
	v_pk_fma_f32 v[6:7], v[10:11], v[6:7], v[8:9]
	global_store_dwordx4 v[12:13], v[4:7], off
	s_nop 1
	v_lshlrev_b32_e32 v4, 16, v70
	v_and_b32_e32 v5, 0xffff0000, v70
	v_lshlrev_b32_e32 v6, 16, v66
	v_and_b32_e32 v7, 0xffff0000, v66
	v_pk_fma_f32 v[0:1], v[0:1], v[4:5], v[6:7]
	v_lshlrev_b32_e32 v4, 16, v71
	v_and_b32_e32 v5, 0xffff0000, v71
	v_lshlrev_b32_e32 v6, 16, v67
	v_and_b32_e32 v7, 0xffff0000, v67
	v_pk_fma_f32 v[2:3], v[2:3], v[4:5], v[6:7]
	global_store_dwordx4 v[12:13], v[0:3], off offset:16
	s_add_i32 s59, s59, s33
	s_andn2_b64 vcc, exec, s[0:1]
	s_mov_b32 s60, s22
	s_mov_b32 s30, s24
	s_mov_b64 s[36:37], s[28:29]
	s_mov_b64 s[34:35], s[26:27]
	s_cbranch_vccz .LBB0_2292
